# K-loop: merged vmcnt(8)+lgkmcnt(0) into one wait and raised priority before the pre-MFMA barrier (on top of v14)
# speedup vs baseline: 1.0057x; 1.0019x over previous
.LBB0_92:
	ds_read_b128 v[146:149], v143
	ds_read_b128 v[150:153], v143 offset:1024
	ds_read_b128 v[154:157], v143 offset:2048
	ds_read_b128 v[158:161], v143 offset:3072
	ds_read_b128 v[162:165], v144
	ds_read_b128 v[166:169], v144 offset:1024
	ds_read_b128 v[170:173], v144 offset:2048
	ds_read_b128 v[178:181], v144 offset:3072
	ds_read_b128 v[182:185], v145
	ds_read_b128 v[186:189], v145 offset:1024
	ds_read_b128 v[190:193], v145 offset:2048
	ds_read_b128 v[194:197], v145 offset:3072
	ds_read_b128 v[198:201], v145 offset:4096
	ds_read_b128 v[206:209], v145 offset:5120
	ds_read_b128 v[210:213], v145 offset:6144
	ds_read_b128 v[214:217], v145 offset:7168
	s_add_u32 s0, s28, 0xfff80080
	s_addc_u32 s1, s29, -1
	s_cmp_eq_u32 s68, 28
	s_cselect_b32 s35, s13, s1
	s_cselect_b32 s34, s63, s0
	s_cselect_b32 s31, s64, s67
	s_cselect_b32 s30, s65, s66
	s_add_i32 m0, s27, 0xc000
	v_lshl_add_u64 v[174:175], s[28:29], 0, v[136:137]
	global_load_lds_dwordx4 v[174:175], off
	s_add_i32 m0, s27, 0xe000
	v_lshl_add_u64 v[174:175], s[28:29], 0, v[138:139]
	global_load_lds_dwordx4 v[174:175], off
	s_waitcnt vmcnt(8) lgkmcnt(0)
	s_setprio 1
	s_barrier
	v_mfma_f32_16x16x32_bf16 v[124:127], v[146:149], v[182:185], v[124:127]
	v_mfma_f32_16x16x32_bf16 v[120:123], v[154:157], v[182:185], v[120:123]
	v_mfma_f32_16x16x32_bf16 v[116:119], v[146:149], v[190:193], v[116:119]
	v_mfma_f32_16x16x32_bf16 v[108:111], v[154:157], v[190:193], v[108:111]
	v_mfma_f32_16x16x32_bf16 v[100:103], v[146:149], v[198:201], v[100:103]
	v_mfma_f32_16x16x32_bf16 v[92:95], v[154:157], v[198:201], v[92:95]
	v_mfma_f32_16x16x32_bf16 v[84:87], v[146:149], v[210:213], v[84:87]
	v_mfma_f32_16x16x32_bf16 v[76:79], v[154:157], v[210:213], v[76:79]
	v_mfma_f32_16x16x32_bf16 v[124:127], v[150:153], v[186:189], v[124:127]
	v_mfma_f32_16x16x32_bf16 v[120:123], v[158:161], v[186:189], v[120:123]
	v_mfma_f32_16x16x32_bf16 v[116:119], v[150:153], v[194:197], v[116:119]
	v_mfma_f32_16x16x32_bf16 v[108:111], v[158:161], v[194:197], v[108:111]
	v_mfma_f32_16x16x32_bf16 v[100:103], v[150:153], v[206:209], v[100:103]
	v_mfma_f32_16x16x32_bf16 v[92:95], v[158:161], v[206:209], v[92:95]
	v_mfma_f32_16x16x32_bf16 v[84:87], v[150:153], v[214:217], v[84:87]
	v_mfma_f32_16x16x32_bf16 v[76:79], v[158:161], v[214:217], v[76:79]
	v_mfma_f32_16x16x32_bf16 v[112:115], v[162:165], v[182:185], v[112:115]
	v_mfma_f32_16x16x32_bf16 v[104:107], v[170:173], v[182:185], v[104:107]
	v_mfma_f32_16x16x32_bf16 v[96:99], v[162:165], v[190:193], v[96:99]
	v_mfma_f32_16x16x32_bf16 v[88:91], v[170:173], v[190:193], v[88:91]
	v_mfma_f32_16x16x32_bf16 v[80:83], v[162:165], v[198:201], v[80:83]
	v_mfma_f32_16x16x32_bf16 v[72:75], v[170:173], v[198:201], v[72:75]
	v_mfma_f32_16x16x32_bf16 v[68:71], v[162:165], v[210:213], v[68:71]
	v_mfma_f32_16x16x32_bf16 v[64:67], v[170:173], v[210:213], v[64:67]
	v_mfma_f32_16x16x32_bf16 v[112:115], v[166:169], v[186:189], v[112:115]
	v_mfma_f32_16x16x32_bf16 v[104:107], v[178:181], v[186:189], v[104:107]
	v_mfma_f32_16x16x32_bf16 v[96:99], v[166:169], v[194:197], v[96:99]
	v_mfma_f32_16x16x32_bf16 v[88:91], v[178:181], v[194:197], v[88:91]
	v_mfma_f32_16x16x32_bf16 v[80:83], v[166:169], v[206:209], v[80:83]
	v_mfma_f32_16x16x32_bf16 v[72:75], v[178:181], v[206:209], v[72:75]
	v_mfma_f32_16x16x32_bf16 v[68:71], v[166:169], v[214:217], v[68:71]
	v_mfma_f32_16x16x32_bf16 v[64:67], v[178:181], v[214:217], v[64:67]
	s_setprio 0
	s_barrier
	ds_read_b128 v[182:185], v145 offset:16384
	ds_read_b128 v[186:189], v145 offset:17408
	ds_read_b128 v[190:193], v145 offset:18432
	ds_read_b128 v[194:197], v145 offset:19456
	ds_read_b128 v[198:201], v145 offset:20480
	ds_read_b128 v[206:209], v145 offset:21504
	ds_read_b128 v[210:213], v145 offset:22528
	ds_read_b128 v[214:217], v145 offset:23552
	s_add_i32 s0, s58, s48
	s_mov_b32 m0, s0
	v_lshl_add_u64 v[174:175], s[30:31], 0, v[132:133]
	global_load_lds_dwordx4 v[174:175], off
	s_add_i32 m0, s0, 0x2000
	s_add_u32 s0, s30, 0x80000
	v_lshl_add_u64 v[202:203], s[30:31], 0, v[128:129]
	s_addc_u32 s1, s31, 0
	s_add_i32 s2, s59, s48
	global_load_lds_dwordx4 v[202:203], off
	v_lshl_add_u64 v[218:219], s[0:1], 0, v[132:133]
	s_mov_b32 m0, s2
	v_lshl_add_u64 v[220:221], s[34:35], 0, v[130:131]
	global_load_lds_dwordx4 v[218:219], off
	s_add_i32 m0, s2, 0x2000
	v_lshl_add_u64 v[218:219], s[0:1], 0, v[128:129]
	global_load_lds_dwordx4 v[218:219], off
	s_mov_b32 m0, s27
	v_lshl_add_u64 v[218:219], s[34:35], 0, v[134:135]
	global_load_lds_dwordx4 v[218:219], off
	s_mov_b32 m0, s50
	s_nop 0
	global_load_lds_dwordx4 v[220:221], off
	s_waitcnt vmcnt(8) lgkmcnt(0)
	s_setprio 1
	s_barrier
	v_mfma_f32_16x16x32_bf16 v[60:63], v[146:149], v[182:185], v[60:63]
	v_mfma_f32_16x16x32_bf16 v[56:59], v[154:157], v[182:185], v[56:59]
	v_mfma_f32_16x16x32_bf16 v[52:55], v[146:149], v[190:193], v[52:55]
	v_mfma_f32_16x16x32_bf16 v[44:47], v[154:157], v[190:193], v[44:47]
	v_mfma_f32_16x16x32_bf16 v[36:39], v[146:149], v[198:201], v[36:39]
	v_mfma_f32_16x16x32_bf16 v[28:31], v[154:157], v[198:201], v[28:31]
	v_mfma_f32_16x16x32_bf16 v[20:23], v[146:149], v[210:213], v[20:23]
	v_mfma_f32_16x16x32_bf16 v[12:15], v[154:157], v[210:213], v[12:15]
	v_mfma_f32_16x16x32_bf16 v[60:63], v[150:153], v[186:189], v[60:63]
	v_mfma_f32_16x16x32_bf16 v[56:59], v[158:161], v[186:189], v[56:59]
	v_mfma_f32_16x16x32_bf16 v[52:55], v[150:153], v[194:197], v[52:55]
	v_mfma_f32_16x16x32_bf16 v[44:47], v[158:161], v[194:197], v[44:47]
	v_mfma_f32_16x16x32_bf16 v[36:39], v[150:153], v[206:209], v[36:39]
	v_mfma_f32_16x16x32_bf16 v[28:31], v[158:161], v[206:209], v[28:31]
	v_mfma_f32_16x16x32_bf16 v[20:23], v[150:153], v[214:217], v[20:23]
	v_mfma_f32_16x16x32_bf16 v[12:15], v[158:161], v[214:217], v[12:15]
	v_mfma_f32_16x16x32_bf16 v[48:51], v[162:165], v[182:185], v[48:51]
	v_mfma_f32_16x16x32_bf16 v[40:43], v[170:173], v[182:185], v[40:43]
	v_mfma_f32_16x16x32_bf16 v[32:35], v[162:165], v[190:193], v[32:35]
	v_mfma_f32_16x16x32_bf16 v[24:27], v[170:173], v[190:193], v[24:27]
	v_mfma_f32_16x16x32_bf16 v[16:19], v[162:165], v[198:201], v[16:19]
	v_mfma_f32_16x16x32_bf16 v[8:11], v[170:173], v[198:201], v[8:11]
	v_mfma_f32_16x16x32_bf16 v[4:7], v[162:165], v[210:213], v[4:7]
	v_mfma_f32_16x16x32_bf16 v[0:3], v[170:173], v[210:213], v[0:3]
	v_mfma_f32_16x16x32_bf16 v[48:51], v[166:169], v[186:189], v[48:51]
	v_mfma_f32_16x16x32_bf16 v[40:43], v[178:181], v[186:189], v[40:43]
	v_mfma_f32_16x16x32_bf16 v[32:35], v[166:169], v[194:197], v[32:35]
	v_mfma_f32_16x16x32_bf16 v[24:27], v[178:181], v[194:197], v[24:27]
	v_mfma_f32_16x16x32_bf16 v[16:19], v[166:169], v[206:209], v[16:19]
	v_mfma_f32_16x16x32_bf16 v[8:11], v[178:181], v[206:209], v[8:11]
	v_mfma_f32_16x16x32_bf16 v[4:7], v[166:169], v[214:217], v[4:7]
	v_mfma_f32_16x16x32_bf16 v[0:3], v[178:181], v[214:217], v[0:3]
	s_setprio 0
	s_barrier
	ds_read_b128 v[182:185], v145 offset:32768
	ds_read_b128 v[186:189], v145 offset:33792
	ds_read_b128 v[190:193], v145 offset:34816
	ds_read_b128 v[194:197], v145 offset:35840
	ds_read_b128 v[198:201], v145 offset:36864
	ds_read_b128 v[206:209], v145 offset:37888
	ds_read_b128 v[210:213], v145 offset:38912
	ds_read_b128 v[214:217], v145 offset:39936
	s_add_i32 s2, 0, 0x18000
	s_add_i32 s38, 0, 0x1c000
	v_add_u32_e32 v158, s2, v142
	v_add_u32_e32 v177, s38, v142
	ds_read_b128 v[146:149], v158
	ds_read_b128 v[150:153], v158 offset:1024
	ds_read_b128 v[154:157], v158 offset:2048
	ds_read_b128 v[158:161], v158 offset:3072
	ds_read_b128 v[162:165], v177
	ds_read_b128 v[166:169], v177 offset:1024
	ds_read_b128 v[170:173], v177 offset:2048
	ds_read_b128 v[178:181], v177 offset:3072
	s_add_u32 s0, s34, 0x80000
	s_addc_u32 s1, s35, 0
	s_mov_b32 m0, s51
	v_lshl_add_u64 v[222:223], s[0:1], 0, v[134:135]
	global_load_lds_dwordx4 v[222:223], off
	s_mov_b32 m0, s52
	v_lshl_add_u64 v[222:223], s[0:1], 0, v[130:131]
	global_load_lds_dwordx4 v[222:223], off
	s_waitcnt vmcnt(8) lgkmcnt(0)
	s_setprio 1
	s_barrier
	v_mfma_f32_16x16x32_bf16 v[124:127], v[146:149], v[182:185], v[124:127]
	v_mfma_f32_16x16x32_bf16 v[120:123], v[154:157], v[182:185], v[120:123]
	v_mfma_f32_16x16x32_bf16 v[116:119], v[146:149], v[190:193], v[116:119]
	v_mfma_f32_16x16x32_bf16 v[108:111], v[154:157], v[190:193], v[108:111]
	v_mfma_f32_16x16x32_bf16 v[100:103], v[146:149], v[198:201], v[100:103]
	v_mfma_f32_16x16x32_bf16 v[92:95], v[154:157], v[198:201], v[92:95]
	v_mfma_f32_16x16x32_bf16 v[84:87], v[146:149], v[210:213], v[84:87]
	v_mfma_f32_16x16x32_bf16 v[76:79], v[154:157], v[210:213], v[76:79]
	v_mfma_f32_16x16x32_bf16 v[124:127], v[150:153], v[186:189], v[124:127]
	v_mfma_f32_16x16x32_bf16 v[120:123], v[158:161], v[186:189], v[120:123]
	v_mfma_f32_16x16x32_bf16 v[116:119], v[150:153], v[194:197], v[116:119]
	v_mfma_f32_16x16x32_bf16 v[108:111], v[158:161], v[194:197], v[108:111]
	v_mfma_f32_16x16x32_bf16 v[100:103], v[150:153], v[206:209], v[100:103]
	v_mfma_f32_16x16x32_bf16 v[92:95], v[158:161], v[206:209], v[92:95]
	v_mfma_f32_16x16x32_bf16 v[84:87], v[150:153], v[214:217], v[84:87]
	v_mfma_f32_16x16x32_bf16 v[76:79], v[158:161], v[214:217], v[76:79]
	v_mfma_f32_16x16x32_bf16 v[112:115], v[162:165], v[182:185], v[112:115]
	v_mfma_f32_16x16x32_bf16 v[104:107], v[170:173], v[182:185], v[104:107]
	v_mfma_f32_16x16x32_bf16 v[96:99], v[162:165], v[190:193], v[96:99]
	v_mfma_f32_16x16x32_bf16 v[88:91], v[170:173], v[190:193], v[88:91]
	v_mfma_f32_16x16x32_bf16 v[80:83], v[162:165], v[198:201], v[80:83]
	v_mfma_f32_16x16x32_bf16 v[72:75], v[170:173], v[198:201], v[72:75]
	v_mfma_f32_16x16x32_bf16 v[68:71], v[162:165], v[210:213], v[68:71]
	v_mfma_f32_16x16x32_bf16 v[64:67], v[170:173], v[210:213], v[64:67]
	v_mfma_f32_16x16x32_bf16 v[112:115], v[166:169], v[186:189], v[112:115]
	v_mfma_f32_16x16x32_bf16 v[104:107], v[178:181], v[186:189], v[104:107]
	v_mfma_f32_16x16x32_bf16 v[96:99], v[166:169], v[194:197], v[96:99]
	v_mfma_f32_16x16x32_bf16 v[88:91], v[178:181], v[194:197], v[88:91]
	v_mfma_f32_16x16x32_bf16 v[80:83], v[166:169], v[206:209], v[80:83]
	v_mfma_f32_16x16x32_bf16 v[72:75], v[178:181], v[206:209], v[72:75]
	v_mfma_f32_16x16x32_bf16 v[68:71], v[166:169], v[214:217], v[68:71]
	v_mfma_f32_16x16x32_bf16 v[64:67], v[178:181], v[214:217], v[64:67]
	s_setprio 0
	s_barrier
	ds_read_b128 v[182:185], v145 offset:49152
	ds_read_b128 v[186:189], v145 offset:50176
	ds_read_b128 v[190:193], v145 offset:51200
	ds_read_b128 v[194:197], v145 offset:52224
	ds_read_b128 v[198:201], v145 offset:53248
	ds_read_b128 v[206:209], v145 offset:54272
	ds_read_b128 v[210:213], v145 offset:55296
	ds_read_b128 v[214:217], v145 offset:56320
	s_add_i32 s0, s2, s48
	s_mov_b32 m0, s0
	v_lshl_add_u64 v[174:175], v[174:175], 0, s[8:9]
	global_load_lds_dwordx4 v[174:175], off
	s_add_i32 m0, s0, 0x2000
	s_add_u32 s0, s30, 0x80080
	v_lshl_add_u64 v[174:175], v[202:203], 0, s[8:9]
	s_addc_u32 s1, s31, 0
	s_add_i32 s2, s38, s48
	global_load_lds_dwordx4 v[174:175], off
	s_mov_b32 m0, s2
	v_lshl_add_u64 v[174:175], s[0:1], 0, v[132:133]
	global_load_lds_dwordx4 v[174:175], off
	s_add_i32 m0, s2, 0x2000
	v_lshl_add_u64 v[174:175], s[0:1], 0, v[128:129]
	global_load_lds_dwordx4 v[174:175], off
	s_mov_b32 m0, s55
	v_lshl_add_u64 v[174:175], v[218:219], 0, s[8:9]
	global_load_lds_dwordx4 v[174:175], off
	s_mov_b32 m0, s56
	v_lshl_add_u64 v[174:175], v[220:221], 0, s[8:9]
	global_load_lds_dwordx4 v[174:175], off
	s_waitcnt vmcnt(8) lgkmcnt(0)
	s_setprio 1
	s_barrier
	v_mfma_f32_16x16x32_bf16 v[60:63], v[146:149], v[182:185], v[60:63]
	v_mfma_f32_16x16x32_bf16 v[56:59], v[154:157], v[182:185], v[56:59]
	v_mfma_f32_16x16x32_bf16 v[52:55], v[146:149], v[190:193], v[52:55]
	v_mfma_f32_16x16x32_bf16 v[44:47], v[154:157], v[190:193], v[44:47]
	v_mfma_f32_16x16x32_bf16 v[36:39], v[146:149], v[198:201], v[36:39]
	v_mfma_f32_16x16x32_bf16 v[28:31], v[154:157], v[198:201], v[28:31]
	v_mfma_f32_16x16x32_bf16 v[20:23], v[146:149], v[210:213], v[20:23]
	v_mfma_f32_16x16x32_bf16 v[12:15], v[154:157], v[210:213], v[12:15]
	v_mfma_f32_16x16x32_bf16 v[60:63], v[150:153], v[186:189], v[60:63]
	v_mfma_f32_16x16x32_bf16 v[56:59], v[158:161], v[186:189], v[56:59]
	v_mfma_f32_16x16x32_bf16 v[52:55], v[150:153], v[194:197], v[52:55]
	v_mfma_f32_16x16x32_bf16 v[44:47], v[158:161], v[194:197], v[44:47]
	v_mfma_f32_16x16x32_bf16 v[36:39], v[150:153], v[206:209], v[36:39]
	v_mfma_f32_16x16x32_bf16 v[28:31], v[158:161], v[206:209], v[28:31]
	v_mfma_f32_16x16x32_bf16 v[20:23], v[150:153], v[214:217], v[20:23]
	v_mfma_f32_16x16x32_bf16 v[12:15], v[158:161], v[214:217], v[12:15]
	v_mfma_f32_16x16x32_bf16 v[48:51], v[162:165], v[182:185], v[48:51]
	v_mfma_f32_16x16x32_bf16 v[40:43], v[170:173], v[182:185], v[40:43]
	v_mfma_f32_16x16x32_bf16 v[32:35], v[162:165], v[190:193], v[32:35]
	v_mfma_f32_16x16x32_bf16 v[24:27], v[170:173], v[190:193], v[24:27]
	v_mfma_f32_16x16x32_bf16 v[16:19], v[162:165], v[198:201], v[16:19]
	v_mfma_f32_16x16x32_bf16 v[8:11], v[170:173], v[198:201], v[8:11]
	v_mfma_f32_16x16x32_bf16 v[4:7], v[162:165], v[210:213], v[4:7]
	v_mfma_f32_16x16x32_bf16 v[0:3], v[170:173], v[210:213], v[0:3]
	v_mfma_f32_16x16x32_bf16 v[48:51], v[166:169], v[186:189], v[48:51]
	v_mfma_f32_16x16x32_bf16 v[40:43], v[178:181], v[186:189], v[40:43]
	v_mfma_f32_16x16x32_bf16 v[32:35], v[166:169], v[194:197], v[32:35]
	v_mfma_f32_16x16x32_bf16 v[24:27], v[178:181], v[194:197], v[24:27]
	v_mfma_f32_16x16x32_bf16 v[16:19], v[166:169], v[206:209], v[16:19]
	v_mfma_f32_16x16x32_bf16 v[8:11], v[178:181], v[206:209], v[8:11]
	v_mfma_f32_16x16x32_bf16 v[4:7], v[166:169], v[214:217], v[4:7]
	v_mfma_f32_16x16x32_bf16 v[0:3], v[178:181], v[214:217], v[0:3]
	s_setprio 0
	s_barrier
	s_add_i32 s68, s68, 2
	s_add_u32 s28, s28, 0x100
	s_addc_u32 s29, s29, 0
	s_add_u32 s66, s66, 0x100
	s_addc_u32 s67, s67, 0
	s_cmp_gt_u32 s68, 29
	s_cbranch_scc0 .LBB0_92
	s_and_b64 vcc, exec, s[10:11]
	s_cbranch_vccz .LBB0_95
	s_barrier

.LBB0_300:
	ds_read_b128 v[128:131], v157
	ds_read_b128 v[132:135], v157 offset:1024
	ds_read_b128 v[136:139], v157 offset:2048
	ds_read_b128 v[140:143], v157 offset:3072
	ds_read_b128 v[160:163], v158
	ds_read_b128 v[164:167], v158 offset:1024
	ds_read_b128 v[168:171], v158 offset:2048
	ds_read_b128 v[172:175], v158 offset:3072
	ds_read_b128 v[178:181], v159
	ds_read_b128 v[182:185], v159 offset:1024
	ds_read_b128 v[186:189], v159 offset:2048
	ds_read_b128 v[190:193], v159 offset:3072
	ds_read_b128 v[194:197], v159 offset:4096
	ds_read_b128 v[198:201], v159 offset:5120
	ds_read_b128 v[206:209], v159 offset:6144
	ds_read_b128 v[210:213], v159 offset:7168
	s_add_u32 s0, s62, 0xfff80080
	s_addc_u32 s1, s63, -1
	s_cmp_eq_u32 s89, 28
	s_cselect_b32 s67, s14, s1
	s_cselect_b32 s66, s49, s0
	s_cselect_b32 s65, s61, s88
	s_cselect_b32 s64, s68, s69
	s_add_i32 m0, s72, 0xc000
	v_lshl_add_u64 v[152:153], s[62:63], 0, v[148:149]
	global_load_lds_dwordx4 v[152:153], off
	s_add_i32 m0, s72, 0xe000
	v_lshl_add_u64 v[152:153], s[62:63], 0, v[150:151]
	global_load_lds_dwordx4 v[152:153], off
	s_waitcnt vmcnt(8) lgkmcnt(0)
	s_setprio 1
	s_barrier
	v_mfma_f32_16x16x32_bf16 v[124:127], v[128:131], v[178:181], v[124:127]
	v_mfma_f32_16x16x32_bf16 v[120:123], v[136:139], v[178:181], v[120:123]
	v_mfma_f32_16x16x32_bf16 v[112:115], v[128:131], v[186:189], v[112:115]
	v_mfma_f32_16x16x32_bf16 v[108:111], v[136:139], v[186:189], v[108:111]
	v_mfma_f32_16x16x32_bf16 v[96:99], v[128:131], v[194:197], v[96:99]
	v_mfma_f32_16x16x32_bf16 v[92:95], v[136:139], v[194:197], v[92:95]
	v_mfma_f32_16x16x32_bf16 v[80:83], v[128:131], v[206:209], v[80:83]
	v_mfma_f32_16x16x32_bf16 v[76:79], v[136:139], v[206:209], v[76:79]
	v_mfma_f32_16x16x32_bf16 v[124:127], v[132:135], v[182:185], v[124:127]
	v_mfma_f32_16x16x32_bf16 v[120:123], v[140:143], v[182:185], v[120:123]
	v_mfma_f32_16x16x32_bf16 v[112:115], v[132:135], v[190:193], v[112:115]
	v_mfma_f32_16x16x32_bf16 v[108:111], v[140:143], v[190:193], v[108:111]
	v_mfma_f32_16x16x32_bf16 v[96:99], v[132:135], v[198:201], v[96:99]
	v_mfma_f32_16x16x32_bf16 v[92:95], v[140:143], v[198:201], v[92:95]
	v_mfma_f32_16x16x32_bf16 v[80:83], v[132:135], v[210:213], v[80:83]
	v_mfma_f32_16x16x32_bf16 v[76:79], v[140:143], v[210:213], v[76:79]
	v_mfma_f32_16x16x32_bf16 v[116:119], v[160:163], v[178:181], v[116:119]
	v_mfma_f32_16x16x32_bf16 v[104:107], v[168:171], v[178:181], v[104:107]
	v_mfma_f32_16x16x32_bf16 v[100:103], v[160:163], v[186:189], v[100:103]
	v_mfma_f32_16x16x32_bf16 v[88:91], v[168:171], v[186:189], v[88:91]
	v_mfma_f32_16x16x32_bf16 v[84:87], v[160:163], v[194:197], v[84:87]
	v_mfma_f32_16x16x32_bf16 v[72:75], v[168:171], v[194:197], v[72:75]
	v_mfma_f32_16x16x32_bf16 v[68:71], v[160:163], v[206:209], v[68:71]
	v_mfma_f32_16x16x32_bf16 v[64:67], v[168:171], v[206:209], v[64:67]
	v_mfma_f32_16x16x32_bf16 v[116:119], v[164:167], v[182:185], v[116:119]
	v_mfma_f32_16x16x32_bf16 v[104:107], v[172:175], v[182:185], v[104:107]
	v_mfma_f32_16x16x32_bf16 v[100:103], v[164:167], v[190:193], v[100:103]
	v_mfma_f32_16x16x32_bf16 v[88:91], v[172:175], v[190:193], v[88:91]
	v_mfma_f32_16x16x32_bf16 v[84:87], v[164:167], v[198:201], v[84:87]
	v_mfma_f32_16x16x32_bf16 v[72:75], v[172:175], v[198:201], v[72:75]
	v_mfma_f32_16x16x32_bf16 v[68:71], v[164:167], v[210:213], v[68:71]
	v_mfma_f32_16x16x32_bf16 v[64:67], v[172:175], v[210:213], v[64:67]
	s_setprio 0
	s_barrier
	ds_read_b128 v[178:181], v159 offset:16384
	ds_read_b128 v[182:185], v159 offset:17408
	ds_read_b128 v[186:189], v159 offset:18432
	ds_read_b128 v[190:193], v159 offset:19456
	ds_read_b128 v[194:197], v159 offset:20480
	ds_read_b128 v[198:201], v159 offset:21504
	ds_read_b128 v[206:209], v159 offset:22528
	ds_read_b128 v[210:213], v159 offset:23552
	s_add_i32 s0, s83, s71
	s_mov_b32 m0, s0
	v_lshl_add_u64 v[152:153], s[64:65], 0, v[146:147]
	global_load_lds_dwordx4 v[152:153], off
	s_add_i32 m0, s0, 0x2000
	s_add_u32 s0, s64, 0x80000
	v_lshl_add_u64 v[202:203], s[64:65], 0, v[144:145]
	s_addc_u32 s1, s65, 0
	s_add_i32 s2, s84, s71
	global_load_lds_dwordx4 v[202:203], off
	v_lshl_add_u64 v[214:215], s[0:1], 0, v[146:147]
	s_mov_b32 m0, s2
	v_lshl_add_u64 v[216:217], s[66:67], 0, v[144:145]
	global_load_lds_dwordx4 v[214:215], off
	s_add_i32 m0, s2, 0x2000
	v_lshl_add_u64 v[214:215], s[0:1], 0, v[144:145]
	global_load_lds_dwordx4 v[214:215], off
	s_mov_b32 m0, s72
	v_lshl_add_u64 v[214:215], s[66:67], 0, v[146:147]
	global_load_lds_dwordx4 v[214:215], off
	s_mov_b32 m0, s73
	s_nop 0
	global_load_lds_dwordx4 v[216:217], off
	s_waitcnt vmcnt(8) lgkmcnt(0)
	s_setprio 1
	s_barrier
	v_mfma_f32_16x16x32_bf16 v[60:63], v[128:131], v[178:181], v[60:63]
	v_mfma_f32_16x16x32_bf16 v[56:59], v[136:139], v[178:181], v[56:59]
	v_mfma_f32_16x16x32_bf16 v[48:51], v[128:131], v[186:189], v[48:51]
	v_mfma_f32_16x16x32_bf16 v[44:47], v[136:139], v[186:189], v[44:47]
	v_mfma_f32_16x16x32_bf16 v[32:35], v[128:131], v[194:197], v[32:35]
	v_mfma_f32_16x16x32_bf16 v[28:31], v[136:139], v[194:197], v[28:31]
	v_mfma_f32_16x16x32_bf16 v[16:19], v[128:131], v[206:209], v[16:19]
	v_mfma_f32_16x16x32_bf16 v[12:15], v[136:139], v[206:209], v[12:15]
	v_mfma_f32_16x16x32_bf16 v[60:63], v[132:135], v[182:185], v[60:63]
	v_mfma_f32_16x16x32_bf16 v[56:59], v[140:143], v[182:185], v[56:59]
	v_mfma_f32_16x16x32_bf16 v[48:51], v[132:135], v[190:193], v[48:51]
	v_mfma_f32_16x16x32_bf16 v[44:47], v[140:143], v[190:193], v[44:47]
	v_mfma_f32_16x16x32_bf16 v[32:35], v[132:135], v[198:201], v[32:35]
	v_mfma_f32_16x16x32_bf16 v[28:31], v[140:143], v[198:201], v[28:31]
	v_mfma_f32_16x16x32_bf16 v[16:19], v[132:135], v[210:213], v[16:19]
	v_mfma_f32_16x16x32_bf16 v[12:15], v[140:143], v[210:213], v[12:15]
	v_mfma_f32_16x16x32_bf16 v[52:55], v[160:163], v[178:181], v[52:55]
	v_mfma_f32_16x16x32_bf16 v[40:43], v[168:171], v[178:181], v[40:43]
	v_mfma_f32_16x16x32_bf16 v[36:39], v[160:163], v[186:189], v[36:39]
	v_mfma_f32_16x16x32_bf16 v[24:27], v[168:171], v[186:189], v[24:27]
	v_mfma_f32_16x16x32_bf16 v[20:23], v[160:163], v[194:197], v[20:23]
	v_mfma_f32_16x16x32_bf16 v[8:11], v[168:171], v[194:197], v[8:11]
	v_mfma_f32_16x16x32_bf16 v[4:7], v[160:163], v[206:209], v[4:7]
	v_mfma_f32_16x16x32_bf16 v[0:3], v[168:171], v[206:209], v[0:3]
	v_mfma_f32_16x16x32_bf16 v[52:55], v[164:167], v[182:185], v[52:55]
	v_mfma_f32_16x16x32_bf16 v[40:43], v[172:175], v[182:185], v[40:43]
	v_mfma_f32_16x16x32_bf16 v[36:39], v[164:167], v[190:193], v[36:39]
	v_mfma_f32_16x16x32_bf16 v[24:27], v[172:175], v[190:193], v[24:27]
	v_mfma_f32_16x16x32_bf16 v[20:23], v[164:167], v[198:201], v[20:23]
	v_mfma_f32_16x16x32_bf16 v[8:11], v[172:175], v[198:201], v[8:11]
	v_mfma_f32_16x16x32_bf16 v[4:7], v[164:167], v[210:213], v[4:7]
	v_mfma_f32_16x16x32_bf16 v[0:3], v[172:175], v[210:213], v[0:3]
	s_setprio 0
	s_barrier
	ds_read_b128 v[178:181], v159 offset:32768
	ds_read_b128 v[182:185], v159 offset:33792
	ds_read_b128 v[186:189], v159 offset:34816
	ds_read_b128 v[190:193], v159 offset:35840
	ds_read_b128 v[194:197], v159 offset:36864
	ds_read_b128 v[198:201], v159 offset:37888
	ds_read_b128 v[206:209], v159 offset:38912
	ds_read_b128 v[210:213], v159 offset:39936
	s_add_i32 s2, 0, 0x18000
	s_add_i32 s3, 0, 0x1c000
	v_add_u32_e32 v140, s2, v156
	v_add_u32_e32 v172, s3, v156
	ds_read_b128 v[128:131], v140
	ds_read_b128 v[132:135], v140 offset:1024
	ds_read_b128 v[136:139], v140 offset:2048
	ds_read_b128 v[140:143], v140 offset:3072
	ds_read_b128 v[160:163], v172
	ds_read_b128 v[164:167], v172 offset:1024
	ds_read_b128 v[168:171], v172 offset:2048
	ds_read_b128 v[172:175], v172 offset:3072
	s_add_u32 s0, s66, 0x80000
	s_addc_u32 s1, s67, 0
	s_mov_b32 m0, s74
	v_lshl_add_u64 v[218:219], s[0:1], 0, v[146:147]
	global_load_lds_dwordx4 v[218:219], off
	s_mov_b32 m0, s75
	v_lshl_add_u64 v[218:219], s[0:1], 0, v[144:145]
	global_load_lds_dwordx4 v[218:219], off
	s_waitcnt vmcnt(8) lgkmcnt(0)
	s_setprio 1
	s_barrier
	v_mfma_f32_16x16x32_bf16 v[124:127], v[128:131], v[178:181], v[124:127]
	v_mfma_f32_16x16x32_bf16 v[120:123], v[136:139], v[178:181], v[120:123]
	v_mfma_f32_16x16x32_bf16 v[112:115], v[128:131], v[186:189], v[112:115]
	v_mfma_f32_16x16x32_bf16 v[108:111], v[136:139], v[186:189], v[108:111]
	v_mfma_f32_16x16x32_bf16 v[96:99], v[128:131], v[194:197], v[96:99]
	v_mfma_f32_16x16x32_bf16 v[92:95], v[136:139], v[194:197], v[92:95]
	v_mfma_f32_16x16x32_bf16 v[80:83], v[128:131], v[206:209], v[80:83]
	v_mfma_f32_16x16x32_bf16 v[76:79], v[136:139], v[206:209], v[76:79]
	v_mfma_f32_16x16x32_bf16 v[124:127], v[132:135], v[182:185], v[124:127]
	v_mfma_f32_16x16x32_bf16 v[120:123], v[140:143], v[182:185], v[120:123]
	v_mfma_f32_16x16x32_bf16 v[112:115], v[132:135], v[190:193], v[112:115]
	v_mfma_f32_16x16x32_bf16 v[108:111], v[140:143], v[190:193], v[108:111]
	v_mfma_f32_16x16x32_bf16 v[96:99], v[132:135], v[198:201], v[96:99]
	v_mfma_f32_16x16x32_bf16 v[92:95], v[140:143], v[198:201], v[92:95]
	v_mfma_f32_16x16x32_bf16 v[80:83], v[132:135], v[210:213], v[80:83]
	v_mfma_f32_16x16x32_bf16 v[76:79], v[140:143], v[210:213], v[76:79]
	v_mfma_f32_16x16x32_bf16 v[116:119], v[160:163], v[178:181], v[116:119]
	v_mfma_f32_16x16x32_bf16 v[104:107], v[168:171], v[178:181], v[104:107]
	v_mfma_f32_16x16x32_bf16 v[100:103], v[160:163], v[186:189], v[100:103]
	v_mfma_f32_16x16x32_bf16 v[88:91], v[168:171], v[186:189], v[88:91]
	v_mfma_f32_16x16x32_bf16 v[84:87], v[160:163], v[194:197], v[84:87]
	v_mfma_f32_16x16x32_bf16 v[72:75], v[168:171], v[194:197], v[72:75]
	v_mfma_f32_16x16x32_bf16 v[68:71], v[160:163], v[206:209], v[68:71]
	v_mfma_f32_16x16x32_bf16 v[64:67], v[168:171], v[206:209], v[64:67]
	v_mfma_f32_16x16x32_bf16 v[116:119], v[164:167], v[182:185], v[116:119]
	v_mfma_f32_16x16x32_bf16 v[104:107], v[172:175], v[182:185], v[104:107]
	v_mfma_f32_16x16x32_bf16 v[100:103], v[164:167], v[190:193], v[100:103]
	v_mfma_f32_16x16x32_bf16 v[88:91], v[172:175], v[190:193], v[88:91]
	v_mfma_f32_16x16x32_bf16 v[84:87], v[164:167], v[198:201], v[84:87]
	v_mfma_f32_16x16x32_bf16 v[72:75], v[172:175], v[198:201], v[72:75]
	v_mfma_f32_16x16x32_bf16 v[68:71], v[164:167], v[210:213], v[68:71]
	v_mfma_f32_16x16x32_bf16 v[64:67], v[172:175], v[210:213], v[64:67]
	s_setprio 0
	s_barrier
	ds_read_b128 v[178:181], v159 offset:49152
	ds_read_b128 v[182:185], v159 offset:50176
	ds_read_b128 v[186:189], v159 offset:51200
	ds_read_b128 v[190:193], v159 offset:52224
	ds_read_b128 v[194:197], v159 offset:53248
	ds_read_b128 v[198:201], v159 offset:54272
	ds_read_b128 v[206:209], v159 offset:55296
	ds_read_b128 v[210:213], v159 offset:56320
	s_add_i32 s0, s2, s71
	s_mov_b32 m0, s0
	v_lshl_add_u64 v[152:153], v[152:153], 0, s[12:13]
	global_load_lds_dwordx4 v[152:153], off
	s_add_i32 m0, s0, 0x2000
	s_add_u32 s0, s64, 0x80080
	v_lshl_add_u64 v[152:153], v[202:203], 0, s[12:13]
	s_addc_u32 s1, s65, 0
	s_add_i32 s2, s3, s71
	global_load_lds_dwordx4 v[152:153], off
	s_mov_b32 m0, s2
	v_lshl_add_u64 v[152:153], s[0:1], 0, v[146:147]
	global_load_lds_dwordx4 v[152:153], off
	s_add_i32 m0, s2, 0x2000
	v_lshl_add_u64 v[152:153], s[0:1], 0, v[144:145]
	global_load_lds_dwordx4 v[152:153], off
	s_mov_b32 m0, s81
	v_lshl_add_u64 v[152:153], v[214:215], 0, s[12:13]
	global_load_lds_dwordx4 v[152:153], off
	s_mov_b32 m0, s82
	v_lshl_add_u64 v[152:153], v[216:217], 0, s[12:13]
	global_load_lds_dwordx4 v[152:153], off
	s_waitcnt vmcnt(8) lgkmcnt(0)
	s_setprio 1
	s_barrier
	v_mfma_f32_16x16x32_bf16 v[60:63], v[128:131], v[178:181], v[60:63]
	v_mfma_f32_16x16x32_bf16 v[56:59], v[136:139], v[178:181], v[56:59]
	v_mfma_f32_16x16x32_bf16 v[48:51], v[128:131], v[186:189], v[48:51]
	v_mfma_f32_16x16x32_bf16 v[44:47], v[136:139], v[186:189], v[44:47]
	v_mfma_f32_16x16x32_bf16 v[32:35], v[128:131], v[194:197], v[32:35]
	v_mfma_f32_16x16x32_bf16 v[28:31], v[136:139], v[194:197], v[28:31]
	v_mfma_f32_16x16x32_bf16 v[16:19], v[128:131], v[206:209], v[16:19]
	v_mfma_f32_16x16x32_bf16 v[12:15], v[136:139], v[206:209], v[12:15]
	v_mfma_f32_16x16x32_bf16 v[60:63], v[132:135], v[182:185], v[60:63]
	v_mfma_f32_16x16x32_bf16 v[56:59], v[140:143], v[182:185], v[56:59]
	v_mfma_f32_16x16x32_bf16 v[48:51], v[132:135], v[190:193], v[48:51]
	v_mfma_f32_16x16x32_bf16 v[44:47], v[140:143], v[190:193], v[44:47]
	v_mfma_f32_16x16x32_bf16 v[32:35], v[132:135], v[198:201], v[32:35]
	v_mfma_f32_16x16x32_bf16 v[28:31], v[140:143], v[198:201], v[28:31]
	v_mfma_f32_16x16x32_bf16 v[16:19], v[132:135], v[210:213], v[16:19]
	v_mfma_f32_16x16x32_bf16 v[12:15], v[140:143], v[210:213], v[12:15]
	v_mfma_f32_16x16x32_bf16 v[52:55], v[160:163], v[178:181], v[52:55]
	v_mfma_f32_16x16x32_bf16 v[40:43], v[168:171], v[178:181], v[40:43]
	v_mfma_f32_16x16x32_bf16 v[36:39], v[160:163], v[186:189], v[36:39]
	v_mfma_f32_16x16x32_bf16 v[24:27], v[168:171], v[186:189], v[24:27]
	v_mfma_f32_16x16x32_bf16 v[20:23], v[160:163], v[194:197], v[20:23]
	v_mfma_f32_16x16x32_bf16 v[8:11], v[168:171], v[194:197], v[8:11]
	v_mfma_f32_16x16x32_bf16 v[4:7], v[160:163], v[206:209], v[4:7]
	v_mfma_f32_16x16x32_bf16 v[0:3], v[168:171], v[206:209], v[0:3]
	v_mfma_f32_16x16x32_bf16 v[52:55], v[164:167], v[182:185], v[52:55]
	v_mfma_f32_16x16x32_bf16 v[40:43], v[172:175], v[182:185], v[40:43]
	v_mfma_f32_16x16x32_bf16 v[36:39], v[164:167], v[190:193], v[36:39]
	v_mfma_f32_16x16x32_bf16 v[24:27], v[172:175], v[190:193], v[24:27]
	v_mfma_f32_16x16x32_bf16 v[20:23], v[164:167], v[198:201], v[20:23]
	v_mfma_f32_16x16x32_bf16 v[8:11], v[172:175], v[198:201], v[8:11]
	v_mfma_f32_16x16x32_bf16 v[4:7], v[164:167], v[210:213], v[4:7]
	v_mfma_f32_16x16x32_bf16 v[0:3], v[172:175], v[210:213], v[0:3]
	s_setprio 0
	s_barrier
	s_add_i32 s89, s89, 2
	s_add_u32 s62, s62, 0x100
	s_addc_u32 s63, s63, 0
	s_add_u32 s69, s69, 0x100
	s_addc_u32 s88, s88, 0
	s_cmp_gt_u32 s89, 29
	s_cbranch_scc0 .LBB0_300
	s_and_b64 vcc, exec, s[16:17]
	s_cbranch_vccz .LBB0_303
	s_barrier

.LBB0_399:
	ds_read_b128 v[128:131], v207
	ds_read_b128 v[132:135], v207 offset:1024
	ds_read_b128 v[136:139], v207 offset:2048
	ds_read_b128 v[140:143], v207 offset:3072
	ds_read_b128 v[144:147], v208
	ds_read_b128 v[148:151], v208 offset:1024
	ds_read_b128 v[152:155], v208 offset:2048
	ds_read_b128 v[156:159], v208 offset:3072
	ds_read_b128 v[160:163], v209
	ds_read_b128 v[164:167], v209 offset:1024
	ds_read_b128 v[168:171], v209 offset:2048
	ds_read_b128 v[172:175], v209 offset:3072
	ds_read_b128 v[190:193], v209 offset:4096
	ds_read_b128 v[194:197], v209 offset:5120
	ds_read_b128 v[198:201], v209 offset:6144
	ds_read_b128 v[210:213], v209 offset:7168
	s_add_u32 s0, s4, 0xfff80080
	s_addc_u32 s1, s5, -1
	s_cmp_eq_u32 vcc_hi, 28
	s_cselect_b32 s11, s7, s1
	s_cselect_b32 s10, s12, s0
	s_cselect_b32 s9, s13, vcc_lo
	s_cselect_b32 s8, s15, s65
	s_add_i32 m0, s81, 0xc000
	v_lshl_add_u64 v[202:203], s[4:5], 0, v[186:187]
	global_load_lds_dwordx4 v[202:203], off
	s_add_i32 m0, s81, 0xe000
	v_lshl_add_u64 v[202:203], s[4:5], 0, v[188:189]
	global_load_lds_dwordx4 v[202:203], off
	s_waitcnt vmcnt(8) lgkmcnt(0)
	s_setprio 1
	s_barrier
	v_mfma_f32_16x16x32_bf16 v[124:127], v[128:131], v[160:163], v[124:127]
	v_mfma_f32_16x16x32_bf16 v[56:59], v[136:139], v[160:163], v[56:59]
	v_mfma_f32_16x16x32_bf16 v[116:119], v[128:131], v[168:171], v[116:119]
	v_mfma_f32_16x16x32_bf16 v[52:55], v[136:139], v[168:171], v[52:55]
	v_mfma_f32_16x16x32_bf16 v[108:111], v[128:131], v[190:193], v[108:111]
	v_mfma_f32_16x16x32_bf16 v[44:47], v[136:139], v[190:193], v[44:47]
	v_mfma_f32_16x16x32_bf16 v[104:107], v[128:131], v[198:201], v[104:107]
	v_mfma_f32_16x16x32_bf16 v[32:35], v[136:139], v[198:201], v[32:35]
	v_mfma_f32_16x16x32_bf16 v[124:127], v[132:135], v[164:167], v[124:127]
	v_mfma_f32_16x16x32_bf16 v[56:59], v[140:143], v[164:167], v[56:59]
	v_mfma_f32_16x16x32_bf16 v[116:119], v[132:135], v[172:175], v[116:119]
	v_mfma_f32_16x16x32_bf16 v[52:55], v[140:143], v[172:175], v[52:55]
	v_mfma_f32_16x16x32_bf16 v[108:111], v[132:135], v[194:197], v[108:111]
	v_mfma_f32_16x16x32_bf16 v[44:47], v[140:143], v[194:197], v[44:47]
	v_mfma_f32_16x16x32_bf16 v[104:107], v[132:135], v[210:213], v[104:107]
	v_mfma_f32_16x16x32_bf16 v[32:35], v[140:143], v[210:213], v[32:35]
	v_mfma_f32_16x16x32_bf16 v[120:123], v[144:147], v[160:163], v[120:123]
	v_mfma_f32_16x16x32_bf16 v[60:63], v[152:155], v[160:163], v[60:63]
	v_mfma_f32_16x16x32_bf16 v[112:115], v[144:147], v[168:171], v[112:115]
	v_mfma_f32_16x16x32_bf16 v[48:51], v[152:155], v[168:171], v[48:51]
	v_mfma_f32_16x16x32_bf16 v[100:103], v[144:147], v[190:193], v[100:103]
	v_mfma_f32_16x16x32_bf16 v[40:43], v[152:155], v[190:193], v[40:43]
	v_mfma_f32_16x16x32_bf16 v[96:99], v[144:147], v[198:201], v[96:99]
	v_mfma_f32_16x16x32_bf16 v[36:39], v[152:155], v[198:201], v[36:39]
	v_mfma_f32_16x16x32_bf16 v[120:123], v[148:151], v[164:167], v[120:123]
	v_mfma_f32_16x16x32_bf16 v[60:63], v[156:159], v[164:167], v[60:63]
	v_mfma_f32_16x16x32_bf16 v[112:115], v[148:151], v[172:175], v[112:115]
	v_mfma_f32_16x16x32_bf16 v[48:51], v[156:159], v[172:175], v[48:51]
	v_mfma_f32_16x16x32_bf16 v[100:103], v[148:151], v[194:197], v[100:103]
	v_mfma_f32_16x16x32_bf16 v[40:43], v[156:159], v[194:197], v[40:43]
	v_mfma_f32_16x16x32_bf16 v[96:99], v[148:151], v[210:213], v[96:99]
	v_mfma_f32_16x16x32_bf16 v[36:39], v[156:159], v[210:213], v[36:39]
	s_setprio 0
	s_barrier
	ds_read_b128 v[160:163], v209 offset:16384
	ds_read_b128 v[164:167], v209 offset:17408
	ds_read_b128 v[168:171], v209 offset:18432
	ds_read_b128 v[172:175], v209 offset:19456
	ds_read_b128 v[190:193], v209 offset:20480
	ds_read_b128 v[194:197], v209 offset:21504
	ds_read_b128 v[198:201], v209 offset:22528
	ds_read_b128 v[210:213], v209 offset:23552
	s_add_i32 s0, s95, s80
	s_mov_b32 m0, s0
	v_lshl_add_u64 v[202:203], s[8:9], 0, v[180:181]
	global_load_lds_dwordx4 v[202:203], off
	s_add_i32 m0, s0, 0x2000
	s_add_u32 s0, s8, 0x80000
	v_lshl_add_u64 v[214:215], s[8:9], 0, v[184:185]
	s_addc_u32 s1, s9, 0
	s_add_i32 s2, s96, s80
	global_load_lds_dwordx4 v[214:215], off
	v_lshl_add_u64 v[216:217], s[0:1], 0, v[180:181]
	s_mov_b32 m0, s2
	v_lshl_add_u64 v[218:219], s[10:11], 0, v[182:183]
	global_load_lds_dwordx4 v[216:217], off
	s_add_i32 m0, s2, 0x2000
	v_lshl_add_u64 v[216:217], s[0:1], 0, v[184:185]
	global_load_lds_dwordx4 v[216:217], off
	s_mov_b32 m0, s81
	v_lshl_add_u64 v[216:217], s[10:11], 0, v[178:179]
	global_load_lds_dwordx4 v[216:217], off
	s_mov_b32 m0, s82
	s_nop 0
	global_load_lds_dwordx4 v[218:219], off
	s_waitcnt vmcnt(8) lgkmcnt(0)
	s_setprio 1
	s_barrier
	v_mfma_f32_16x16x32_bf16 v[92:95], v[128:131], v[160:163], v[92:95]
	v_mfma_f32_16x16x32_bf16 v[24:27], v[136:139], v[160:163], v[24:27]
	v_mfma_f32_16x16x32_bf16 v[84:87], v[128:131], v[168:171], v[84:87]
	v_mfma_f32_16x16x32_bf16 v[20:23], v[136:139], v[168:171], v[20:23]
	v_mfma_f32_16x16x32_bf16 v[76:79], v[128:131], v[190:193], v[76:79]
	v_mfma_f32_16x16x32_bf16 v[12:15], v[136:139], v[190:193], v[12:15]
	v_mfma_f32_16x16x32_bf16 v[72:75], v[128:131], v[198:201], v[72:75]
	v_mfma_f32_16x16x32_bf16 v[0:3], v[136:139], v[198:201], v[0:3]
	v_mfma_f32_16x16x32_bf16 v[92:95], v[132:135], v[164:167], v[92:95]
	v_mfma_f32_16x16x32_bf16 v[24:27], v[140:143], v[164:167], v[24:27]
	v_mfma_f32_16x16x32_bf16 v[84:87], v[132:135], v[172:175], v[84:87]
	v_mfma_f32_16x16x32_bf16 v[20:23], v[140:143], v[172:175], v[20:23]
	v_mfma_f32_16x16x32_bf16 v[76:79], v[132:135], v[194:197], v[76:79]
	v_mfma_f32_16x16x32_bf16 v[12:15], v[140:143], v[194:197], v[12:15]
	v_mfma_f32_16x16x32_bf16 v[72:75], v[132:135], v[210:213], v[72:75]
	v_mfma_f32_16x16x32_bf16 v[0:3], v[140:143], v[210:213], v[0:3]
	v_mfma_f32_16x16x32_bf16 v[88:91], v[144:147], v[160:163], v[88:91]
	v_mfma_f32_16x16x32_bf16 v[28:31], v[152:155], v[160:163], v[28:31]
	v_mfma_f32_16x16x32_bf16 v[80:83], v[144:147], v[168:171], v[80:83]
	v_mfma_f32_16x16x32_bf16 v[16:19], v[152:155], v[168:171], v[16:19]
	v_mfma_f32_16x16x32_bf16 v[68:71], v[144:147], v[190:193], v[68:71]
	v_mfma_f32_16x16x32_bf16 v[8:11], v[152:155], v[190:193], v[8:11]
	v_mfma_f32_16x16x32_bf16 v[64:67], v[144:147], v[198:201], v[64:67]
	v_mfma_f32_16x16x32_bf16 v[4:7], v[152:155], v[198:201], v[4:7]
	v_mfma_f32_16x16x32_bf16 v[88:91], v[148:151], v[164:167], v[88:91]
	v_mfma_f32_16x16x32_bf16 v[28:31], v[156:159], v[164:167], v[28:31]
	v_mfma_f32_16x16x32_bf16 v[80:83], v[148:151], v[172:175], v[80:83]
	v_mfma_f32_16x16x32_bf16 v[16:19], v[156:159], v[172:175], v[16:19]
	v_mfma_f32_16x16x32_bf16 v[68:71], v[148:151], v[194:197], v[68:71]
	v_mfma_f32_16x16x32_bf16 v[8:11], v[156:159], v[194:197], v[8:11]
	v_mfma_f32_16x16x32_bf16 v[64:67], v[148:151], v[210:213], v[64:67]
	v_mfma_f32_16x16x32_bf16 v[4:7], v[156:159], v[210:213], v[4:7]
	s_setprio 0
	s_barrier
	ds_read_b128 v[160:163], v209 offset:32768
	ds_read_b128 v[164:167], v209 offset:33792
	ds_read_b128 v[168:171], v209 offset:34816
	ds_read_b128 v[172:175], v209 offset:35840
	ds_read_b128 v[190:193], v209 offset:36864
	ds_read_b128 v[194:197], v209 offset:37888
	ds_read_b128 v[198:201], v209 offset:38912
	ds_read_b128 v[210:213], v209 offset:39936
	s_add_i32 s2, 0, 0x18000
	s_add_i32 s3, 0, 0x1c000
	v_add_u32_e32 v140, s2, v206
	v_add_u32_e32 v156, s3, v206
	ds_read_b128 v[128:131], v140
	ds_read_b128 v[132:135], v140 offset:1024
	ds_read_b128 v[136:139], v140 offset:2048
	ds_read_b128 v[140:143], v140 offset:3072
	ds_read_b128 v[144:147], v156
	ds_read_b128 v[148:151], v156 offset:1024
	ds_read_b128 v[152:155], v156 offset:2048
	ds_read_b128 v[156:159], v156 offset:3072
	s_add_u32 s0, s10, 0x80000
	s_addc_u32 s1, s11, 0
	s_mov_b32 m0, s83
	v_lshl_add_u64 v[220:221], s[0:1], 0, v[178:179]
	global_load_lds_dwordx4 v[220:221], off
	s_mov_b32 m0, s84
	v_lshl_add_u64 v[220:221], s[0:1], 0, v[182:183]
	global_load_lds_dwordx4 v[220:221], off
	s_waitcnt vmcnt(8) lgkmcnt(0)
	s_setprio 1
	s_barrier
	v_mfma_f32_16x16x32_bf16 v[124:127], v[128:131], v[160:163], v[124:127]
	v_mfma_f32_16x16x32_bf16 v[56:59], v[136:139], v[160:163], v[56:59]
	v_mfma_f32_16x16x32_bf16 v[116:119], v[128:131], v[168:171], v[116:119]
	v_mfma_f32_16x16x32_bf16 v[52:55], v[136:139], v[168:171], v[52:55]
	v_mfma_f32_16x16x32_bf16 v[108:111], v[128:131], v[190:193], v[108:111]
	v_mfma_f32_16x16x32_bf16 v[44:47], v[136:139], v[190:193], v[44:47]
	v_mfma_f32_16x16x32_bf16 v[104:107], v[128:131], v[198:201], v[104:107]
	v_mfma_f32_16x16x32_bf16 v[32:35], v[136:139], v[198:201], v[32:35]
	v_mfma_f32_16x16x32_bf16 v[124:127], v[132:135], v[164:167], v[124:127]
	v_mfma_f32_16x16x32_bf16 v[56:59], v[140:143], v[164:167], v[56:59]
	v_mfma_f32_16x16x32_bf16 v[116:119], v[132:135], v[172:175], v[116:119]
	v_mfma_f32_16x16x32_bf16 v[52:55], v[140:143], v[172:175], v[52:55]
	v_mfma_f32_16x16x32_bf16 v[108:111], v[132:135], v[194:197], v[108:111]
	v_mfma_f32_16x16x32_bf16 v[44:47], v[140:143], v[194:197], v[44:47]
	v_mfma_f32_16x16x32_bf16 v[104:107], v[132:135], v[210:213], v[104:107]
	v_mfma_f32_16x16x32_bf16 v[32:35], v[140:143], v[210:213], v[32:35]
	v_mfma_f32_16x16x32_bf16 v[120:123], v[144:147], v[160:163], v[120:123]
	v_mfma_f32_16x16x32_bf16 v[60:63], v[152:155], v[160:163], v[60:63]
	v_mfma_f32_16x16x32_bf16 v[112:115], v[144:147], v[168:171], v[112:115]
	v_mfma_f32_16x16x32_bf16 v[48:51], v[152:155], v[168:171], v[48:51]
	v_mfma_f32_16x16x32_bf16 v[100:103], v[144:147], v[190:193], v[100:103]
	v_mfma_f32_16x16x32_bf16 v[40:43], v[152:155], v[190:193], v[40:43]
	v_mfma_f32_16x16x32_bf16 v[96:99], v[144:147], v[198:201], v[96:99]
	v_mfma_f32_16x16x32_bf16 v[36:39], v[152:155], v[198:201], v[36:39]
	v_mfma_f32_16x16x32_bf16 v[120:123], v[148:151], v[164:167], v[120:123]
	v_mfma_f32_16x16x32_bf16 v[60:63], v[156:159], v[164:167], v[60:63]
	v_mfma_f32_16x16x32_bf16 v[112:115], v[148:151], v[172:175], v[112:115]
	v_mfma_f32_16x16x32_bf16 v[48:51], v[156:159], v[172:175], v[48:51]
	v_mfma_f32_16x16x32_bf16 v[100:103], v[148:151], v[194:197], v[100:103]
	v_mfma_f32_16x16x32_bf16 v[40:43], v[156:159], v[194:197], v[40:43]
	v_mfma_f32_16x16x32_bf16 v[96:99], v[148:151], v[210:213], v[96:99]
	v_mfma_f32_16x16x32_bf16 v[36:39], v[156:159], v[210:213], v[36:39]
	s_setprio 0
	s_barrier
	ds_read_b128 v[160:163], v209 offset:49152
	ds_read_b128 v[164:167], v209 offset:50176
	ds_read_b128 v[168:171], v209 offset:51200
	ds_read_b128 v[172:175], v209 offset:52224
	ds_read_b128 v[190:193], v209 offset:53248
	ds_read_b128 v[194:197], v209 offset:54272
	ds_read_b128 v[198:201], v209 offset:55296
	ds_read_b128 v[210:213], v209 offset:56320
	s_add_i32 s0, s2, s80
	s_mov_b32 m0, s0
	v_lshl_add_u64 v[202:203], v[202:203], 0, s[24:25]
	global_load_lds_dwordx4 v[202:203], off
	s_add_i32 m0, s0, 0x2000
	s_add_u32 s0, s8, 0x80080
	v_lshl_add_u64 v[202:203], v[214:215], 0, s[24:25]
	s_addc_u32 s1, s9, 0
	s_add_i32 s2, s3, s80
	global_load_lds_dwordx4 v[202:203], off
	s_mov_b32 m0, s2
	v_lshl_add_u64 v[202:203], s[0:1], 0, v[180:181]
	global_load_lds_dwordx4 v[202:203], off
	s_add_i32 m0, s2, 0x2000
	v_lshl_add_u64 v[202:203], s[0:1], 0, v[184:185]
	global_load_lds_dwordx4 v[202:203], off
	s_mov_b32 m0, s90
	v_lshl_add_u64 v[202:203], v[216:217], 0, s[24:25]
	global_load_lds_dwordx4 v[202:203], off
	s_mov_b32 m0, s91
	v_lshl_add_u64 v[202:203], v[218:219], 0, s[24:25]
	global_load_lds_dwordx4 v[202:203], off
	s_waitcnt vmcnt(8) lgkmcnt(0)
	s_setprio 1
	s_barrier
	v_mfma_f32_16x16x32_bf16 v[92:95], v[128:131], v[160:163], v[92:95]
	v_mfma_f32_16x16x32_bf16 v[24:27], v[136:139], v[160:163], v[24:27]
	v_mfma_f32_16x16x32_bf16 v[84:87], v[128:131], v[168:171], v[84:87]
	v_mfma_f32_16x16x32_bf16 v[20:23], v[136:139], v[168:171], v[20:23]
	v_mfma_f32_16x16x32_bf16 v[76:79], v[128:131], v[190:193], v[76:79]
	v_mfma_f32_16x16x32_bf16 v[12:15], v[136:139], v[190:193], v[12:15]
	v_mfma_f32_16x16x32_bf16 v[72:75], v[128:131], v[198:201], v[72:75]
	v_mfma_f32_16x16x32_bf16 v[0:3], v[136:139], v[198:201], v[0:3]
	v_mfma_f32_16x16x32_bf16 v[92:95], v[132:135], v[164:167], v[92:95]
	v_mfma_f32_16x16x32_bf16 v[24:27], v[140:143], v[164:167], v[24:27]
	v_mfma_f32_16x16x32_bf16 v[84:87], v[132:135], v[172:175], v[84:87]
	v_mfma_f32_16x16x32_bf16 v[20:23], v[140:143], v[172:175], v[20:23]
	v_mfma_f32_16x16x32_bf16 v[76:79], v[132:135], v[194:197], v[76:79]
	v_mfma_f32_16x16x32_bf16 v[12:15], v[140:143], v[194:197], v[12:15]
	v_mfma_f32_16x16x32_bf16 v[72:75], v[132:135], v[210:213], v[72:75]
	v_mfma_f32_16x16x32_bf16 v[0:3], v[140:143], v[210:213], v[0:3]
	v_mfma_f32_16x16x32_bf16 v[88:91], v[144:147], v[160:163], v[88:91]
	v_mfma_f32_16x16x32_bf16 v[28:31], v[152:155], v[160:163], v[28:31]
	v_mfma_f32_16x16x32_bf16 v[80:83], v[144:147], v[168:171], v[80:83]
	v_mfma_f32_16x16x32_bf16 v[16:19], v[152:155], v[168:171], v[16:19]
	v_mfma_f32_16x16x32_bf16 v[68:71], v[144:147], v[190:193], v[68:71]
	v_mfma_f32_16x16x32_bf16 v[8:11], v[152:155], v[190:193], v[8:11]
	v_mfma_f32_16x16x32_bf16 v[64:67], v[144:147], v[198:201], v[64:67]
	v_mfma_f32_16x16x32_bf16 v[4:7], v[152:155], v[198:201], v[4:7]
	v_mfma_f32_16x16x32_bf16 v[88:91], v[148:151], v[164:167], v[88:91]
	v_mfma_f32_16x16x32_bf16 v[28:31], v[156:159], v[164:167], v[28:31]
	v_mfma_f32_16x16x32_bf16 v[80:83], v[148:151], v[172:175], v[80:83]
	v_mfma_f32_16x16x32_bf16 v[16:19], v[156:159], v[172:175], v[16:19]
	v_mfma_f32_16x16x32_bf16 v[68:71], v[148:151], v[194:197], v[68:71]
	v_mfma_f32_16x16x32_bf16 v[8:11], v[156:159], v[194:197], v[8:11]
	v_mfma_f32_16x16x32_bf16 v[64:67], v[148:151], v[210:213], v[64:67]
	v_mfma_f32_16x16x32_bf16 v[4:7], v[156:159], v[210:213], v[4:7]
	s_setprio 0
	s_barrier
	s_add_i32 vcc_hi, vcc_hi, 2
	s_add_u32 s4, s4, 0x100
	s_addc_u32 s5, s5, 0
	s_add_u32 s65, s65, 0x100
	s_addc_u32 vcc_lo, vcc_lo, 0
	s_cmp_gt_u32 vcc_hi, 29
	s_cbranch_scc0 .LBB0_399
	s_and_b64 vcc, exec, s[26:27]
	s_cbranch_vccz .LBB0_402
	s_barrier

.LBB0_541:
	ds_read_b128 v[128:131], v157
	ds_read_b128 v[132:135], v157 offset:1024
	ds_read_b128 v[136:139], v157 offset:2048
	ds_read_b128 v[140:143], v157 offset:3072
	ds_read_b128 v[160:163], v158
	ds_read_b128 v[164:167], v158 offset:1024
	ds_read_b128 v[168:171], v158 offset:2048
	ds_read_b128 v[172:175], v158 offset:3072
	ds_read_b128 v[178:181], v159
	ds_read_b128 v[182:185], v159 offset:1024
	ds_read_b128 v[186:189], v159 offset:2048
	ds_read_b128 v[190:193], v159 offset:3072
	ds_read_b128 v[194:197], v159 offset:4096
	ds_read_b128 v[206:209], v159 offset:5120
	ds_read_b128 v[210:213], v159 offset:6144
	ds_read_b128 v[214:217], v159 offset:7168
	s_add_u32 s58, s56, 0x100
	s_addc_u32 s59, s57, 0
	s_cmpk_eq_i32 s89, 0x54
	s_cselect_b32 s63, s12, s59
	s_cselect_b32 s62, s55, s58
	s_cselect_b32 s61, s85, s88
	s_cselect_b32 s60, s86, s87
	s_add_i32 m0, s66, 0xc000
	v_lshl_add_u64 v[152:153], s[56:57], 0, v[148:149]
	global_load_lds_dwordx4 v[152:153], off
	s_add_i32 m0, s66, 0xe000
	v_lshl_add_u64 v[152:153], s[56:57], 0, v[150:151]
	global_load_lds_dwordx4 v[152:153], off
	s_waitcnt vmcnt(8) lgkmcnt(0)
	s_setprio 1
	s_barrier
	v_mfma_f32_16x16x32_bf16 v[124:127], v[128:131], v[178:181], v[124:127]
	v_mfma_f32_16x16x32_bf16 v[120:123], v[136:139], v[178:181], v[120:123]
	v_mfma_f32_16x16x32_bf16 v[112:115], v[128:131], v[186:189], v[112:115]
	v_mfma_f32_16x16x32_bf16 v[108:111], v[136:139], v[186:189], v[108:111]
	v_mfma_f32_16x16x32_bf16 v[96:99], v[128:131], v[194:197], v[96:99]
	v_mfma_f32_16x16x32_bf16 v[92:95], v[136:139], v[194:197], v[92:95]
	v_mfma_f32_16x16x32_bf16 v[80:83], v[128:131], v[210:213], v[80:83]
	v_mfma_f32_16x16x32_bf16 v[76:79], v[136:139], v[210:213], v[76:79]
	v_mfma_f32_16x16x32_bf16 v[124:127], v[132:135], v[182:185], v[124:127]
	v_mfma_f32_16x16x32_bf16 v[120:123], v[140:143], v[182:185], v[120:123]
	v_mfma_f32_16x16x32_bf16 v[112:115], v[132:135], v[190:193], v[112:115]
	v_mfma_f32_16x16x32_bf16 v[108:111], v[140:143], v[190:193], v[108:111]
	v_mfma_f32_16x16x32_bf16 v[96:99], v[132:135], v[206:209], v[96:99]
	v_mfma_f32_16x16x32_bf16 v[92:95], v[140:143], v[206:209], v[92:95]
	v_mfma_f32_16x16x32_bf16 v[80:83], v[132:135], v[214:217], v[80:83]
	v_mfma_f32_16x16x32_bf16 v[76:79], v[140:143], v[214:217], v[76:79]
	v_mfma_f32_16x16x32_bf16 v[116:119], v[160:163], v[178:181], v[116:119]
	v_mfma_f32_16x16x32_bf16 v[104:107], v[168:171], v[178:181], v[104:107]
	v_mfma_f32_16x16x32_bf16 v[100:103], v[160:163], v[186:189], v[100:103]
	v_mfma_f32_16x16x32_bf16 v[88:91], v[168:171], v[186:189], v[88:91]
	v_mfma_f32_16x16x32_bf16 v[84:87], v[160:163], v[194:197], v[84:87]
	v_mfma_f32_16x16x32_bf16 v[72:75], v[168:171], v[194:197], v[72:75]
	v_mfma_f32_16x16x32_bf16 v[68:71], v[160:163], v[210:213], v[68:71]
	v_mfma_f32_16x16x32_bf16 v[64:67], v[168:171], v[210:213], v[64:67]
	v_mfma_f32_16x16x32_bf16 v[116:119], v[164:167], v[182:185], v[116:119]
	v_mfma_f32_16x16x32_bf16 v[104:107], v[172:175], v[182:185], v[104:107]
	v_mfma_f32_16x16x32_bf16 v[100:103], v[164:167], v[190:193], v[100:103]
	v_mfma_f32_16x16x32_bf16 v[88:91], v[172:175], v[190:193], v[88:91]
	v_mfma_f32_16x16x32_bf16 v[84:87], v[164:167], v[206:209], v[84:87]
	v_mfma_f32_16x16x32_bf16 v[72:75], v[172:175], v[206:209], v[72:75]
	v_mfma_f32_16x16x32_bf16 v[68:71], v[164:167], v[214:217], v[68:71]
	v_mfma_f32_16x16x32_bf16 v[64:67], v[172:175], v[214:217], v[64:67]
	s_setprio 0
	s_barrier
	ds_read_b128 v[178:181], v159 offset:16384
	ds_read_b128 v[182:185], v159 offset:17408
	ds_read_b128 v[186:189], v159 offset:18432
	ds_read_b128 v[190:193], v159 offset:19456
	ds_read_b128 v[194:197], v159 offset:20480
	ds_read_b128 v[206:209], v159 offset:21504
	ds_read_b128 v[210:213], v159 offset:22528
	ds_read_b128 v[214:217], v159 offset:23552
	s_add_i32 s0, s79, s65
	s_mov_b32 m0, s0
	v_lshl_add_u64 v[152:153], s[60:61], 0, v[146:147]
	global_load_lds_dwordx4 v[152:153], off
	s_add_i32 m0, s0, 0x2000
	s_add_u32 s0, s60, 0x160000
	v_lshl_add_u64 v[198:199], s[60:61], 0, v[144:145]
	s_addc_u32 s1, s61, 0
	s_add_i32 s2, s80, s65
	global_load_lds_dwordx4 v[198:199], off
	v_lshl_add_u64 v[202:203], s[0:1], 0, v[146:147]
	s_mov_b32 m0, s2
	v_lshl_add_u64 v[218:219], s[62:63], 0, v[144:145]
	global_load_lds_dwordx4 v[202:203], off
	s_add_i32 m0, s2, 0x2000
	v_lshl_add_u64 v[202:203], s[0:1], 0, v[144:145]
	global_load_lds_dwordx4 v[202:203], off
	s_mov_b32 m0, s66
	v_lshl_add_u64 v[202:203], s[62:63], 0, v[146:147]
	global_load_lds_dwordx4 v[202:203], off
	s_mov_b32 m0, s67
	s_nop 0
	global_load_lds_dwordx4 v[218:219], off
	s_waitcnt vmcnt(8) lgkmcnt(0)
	s_setprio 1
	s_barrier
	v_mfma_f32_16x16x32_bf16 v[60:63], v[128:131], v[178:181], v[60:63]
	v_mfma_f32_16x16x32_bf16 v[56:59], v[136:139], v[178:181], v[56:59]
	v_mfma_f32_16x16x32_bf16 v[48:51], v[128:131], v[186:189], v[48:51]
	v_mfma_f32_16x16x32_bf16 v[44:47], v[136:139], v[186:189], v[44:47]
	v_mfma_f32_16x16x32_bf16 v[32:35], v[128:131], v[194:197], v[32:35]
	v_mfma_f32_16x16x32_bf16 v[28:31], v[136:139], v[194:197], v[28:31]
	v_mfma_f32_16x16x32_bf16 v[16:19], v[128:131], v[210:213], v[16:19]
	v_mfma_f32_16x16x32_bf16 v[12:15], v[136:139], v[210:213], v[12:15]
	v_mfma_f32_16x16x32_bf16 v[60:63], v[132:135], v[182:185], v[60:63]
	v_mfma_f32_16x16x32_bf16 v[56:59], v[140:143], v[182:185], v[56:59]
	v_mfma_f32_16x16x32_bf16 v[48:51], v[132:135], v[190:193], v[48:51]
	v_mfma_f32_16x16x32_bf16 v[44:47], v[140:143], v[190:193], v[44:47]
	v_mfma_f32_16x16x32_bf16 v[32:35], v[132:135], v[206:209], v[32:35]
	v_mfma_f32_16x16x32_bf16 v[28:31], v[140:143], v[206:209], v[28:31]
	v_mfma_f32_16x16x32_bf16 v[16:19], v[132:135], v[214:217], v[16:19]
	v_mfma_f32_16x16x32_bf16 v[12:15], v[140:143], v[214:217], v[12:15]
	v_mfma_f32_16x16x32_bf16 v[52:55], v[160:163], v[178:181], v[52:55]
	v_mfma_f32_16x16x32_bf16 v[40:43], v[168:171], v[178:181], v[40:43]
	v_mfma_f32_16x16x32_bf16 v[36:39], v[160:163], v[186:189], v[36:39]
	v_mfma_f32_16x16x32_bf16 v[24:27], v[168:171], v[186:189], v[24:27]
	v_mfma_f32_16x16x32_bf16 v[20:23], v[160:163], v[194:197], v[20:23]
	v_mfma_f32_16x16x32_bf16 v[8:11], v[168:171], v[194:197], v[8:11]
	v_mfma_f32_16x16x32_bf16 v[4:7], v[160:163], v[210:213], v[4:7]
	v_mfma_f32_16x16x32_bf16 v[0:3], v[168:171], v[210:213], v[0:3]
	v_mfma_f32_16x16x32_bf16 v[52:55], v[164:167], v[182:185], v[52:55]
	v_mfma_f32_16x16x32_bf16 v[40:43], v[172:175], v[182:185], v[40:43]
	v_mfma_f32_16x16x32_bf16 v[36:39], v[164:167], v[190:193], v[36:39]
	v_mfma_f32_16x16x32_bf16 v[24:27], v[172:175], v[190:193], v[24:27]
	v_mfma_f32_16x16x32_bf16 v[20:23], v[164:167], v[206:209], v[20:23]
	v_mfma_f32_16x16x32_bf16 v[8:11], v[172:175], v[206:209], v[8:11]
	v_mfma_f32_16x16x32_bf16 v[4:7], v[164:167], v[214:217], v[4:7]
	v_mfma_f32_16x16x32_bf16 v[0:3], v[172:175], v[214:217], v[0:3]
	s_setprio 0
	s_barrier
	ds_read_b128 v[178:181], v159 offset:32768
	ds_read_b128 v[182:185], v159 offset:33792
	ds_read_b128 v[186:189], v159 offset:34816
	ds_read_b128 v[190:193], v159 offset:35840
	ds_read_b128 v[194:197], v159 offset:36864
	ds_read_b128 v[206:209], v159 offset:37888
	ds_read_b128 v[210:213], v159 offset:38912
	ds_read_b128 v[214:217], v159 offset:39936
	s_add_i32 s2, 0, 0x18000
	s_add_i32 s3, 0, 0x1c000
	v_add_u32_e32 v140, s2, v156
	v_add_u32_e32 v172, s3, v156
	ds_read_b128 v[128:131], v140
	ds_read_b128 v[132:135], v140 offset:1024
	ds_read_b128 v[136:139], v140 offset:2048
	ds_read_b128 v[140:143], v140 offset:3072
	ds_read_b128 v[160:163], v172
	ds_read_b128 v[164:167], v172 offset:1024
	ds_read_b128 v[168:171], v172 offset:2048
	ds_read_b128 v[172:175], v172 offset:3072
	s_add_u32 s0, s62, 0x160000
	s_addc_u32 s1, s63, 0
	s_mov_b32 m0, s68
	v_lshl_add_u64 v[220:221], s[0:1], 0, v[146:147]
	global_load_lds_dwordx4 v[220:221], off
	s_mov_b32 m0, s69
	v_lshl_add_u64 v[220:221], s[0:1], 0, v[144:145]
	global_load_lds_dwordx4 v[220:221], off
	s_waitcnt vmcnt(8) lgkmcnt(0)
	s_setprio 1
	s_barrier
	v_mfma_f32_16x16x32_bf16 v[124:127], v[128:131], v[178:181], v[124:127]
	v_mfma_f32_16x16x32_bf16 v[120:123], v[136:139], v[178:181], v[120:123]
	v_mfma_f32_16x16x32_bf16 v[112:115], v[128:131], v[186:189], v[112:115]
	v_mfma_f32_16x16x32_bf16 v[108:111], v[136:139], v[186:189], v[108:111]
	v_mfma_f32_16x16x32_bf16 v[96:99], v[128:131], v[194:197], v[96:99]
	v_mfma_f32_16x16x32_bf16 v[92:95], v[136:139], v[194:197], v[92:95]
	v_mfma_f32_16x16x32_bf16 v[80:83], v[128:131], v[210:213], v[80:83]
	v_mfma_f32_16x16x32_bf16 v[76:79], v[136:139], v[210:213], v[76:79]
	v_mfma_f32_16x16x32_bf16 v[124:127], v[132:135], v[182:185], v[124:127]
	v_mfma_f32_16x16x32_bf16 v[120:123], v[140:143], v[182:185], v[120:123]
	v_mfma_f32_16x16x32_bf16 v[112:115], v[132:135], v[190:193], v[112:115]
	v_mfma_f32_16x16x32_bf16 v[108:111], v[140:143], v[190:193], v[108:111]
	v_mfma_f32_16x16x32_bf16 v[96:99], v[132:135], v[206:209], v[96:99]
	v_mfma_f32_16x16x32_bf16 v[92:95], v[140:143], v[206:209], v[92:95]
	v_mfma_f32_16x16x32_bf16 v[80:83], v[132:135], v[214:217], v[80:83]
	v_mfma_f32_16x16x32_bf16 v[76:79], v[140:143], v[214:217], v[76:79]
	v_mfma_f32_16x16x32_bf16 v[116:119], v[160:163], v[178:181], v[116:119]
	v_mfma_f32_16x16x32_bf16 v[104:107], v[168:171], v[178:181], v[104:107]
	v_mfma_f32_16x16x32_bf16 v[100:103], v[160:163], v[186:189], v[100:103]
	v_mfma_f32_16x16x32_bf16 v[88:91], v[168:171], v[186:189], v[88:91]
	v_mfma_f32_16x16x32_bf16 v[84:87], v[160:163], v[194:197], v[84:87]
	v_mfma_f32_16x16x32_bf16 v[72:75], v[168:171], v[194:197], v[72:75]
	v_mfma_f32_16x16x32_bf16 v[68:71], v[160:163], v[210:213], v[68:71]
	v_mfma_f32_16x16x32_bf16 v[64:67], v[168:171], v[210:213], v[64:67]
	v_mfma_f32_16x16x32_bf16 v[116:119], v[164:167], v[182:185], v[116:119]
	v_mfma_f32_16x16x32_bf16 v[104:107], v[172:175], v[182:185], v[104:107]
	v_mfma_f32_16x16x32_bf16 v[100:103], v[164:167], v[190:193], v[100:103]
	v_mfma_f32_16x16x32_bf16 v[88:91], v[172:175], v[190:193], v[88:91]
	v_mfma_f32_16x16x32_bf16 v[84:87], v[164:167], v[206:209], v[84:87]
	v_mfma_f32_16x16x32_bf16 v[72:75], v[172:175], v[206:209], v[72:75]
	v_mfma_f32_16x16x32_bf16 v[68:71], v[164:167], v[214:217], v[68:71]
	v_mfma_f32_16x16x32_bf16 v[64:67], v[172:175], v[214:217], v[64:67]
	s_setprio 0
	s_barrier
	ds_read_b128 v[178:181], v159 offset:49152
	ds_read_b128 v[182:185], v159 offset:50176
	ds_read_b128 v[186:189], v159 offset:51200
	ds_read_b128 v[190:193], v159 offset:52224
	ds_read_b128 v[194:197], v159 offset:53248
	ds_read_b128 v[206:209], v159 offset:54272
	ds_read_b128 v[210:213], v159 offset:55296
	ds_read_b128 v[214:217], v159 offset:56320
	s_add_i32 s0, s2, s65
	s_mov_b32 m0, s0
	v_lshl_add_u64 v[152:153], v[152:153], 0, s[10:11]
	global_load_lds_dwordx4 v[152:153], off
	s_add_i32 m0, s0, 0x2000
	s_add_u32 s0, s60, 0x160080
	v_lshl_add_u64 v[152:153], v[198:199], 0, s[10:11]
	s_addc_u32 s1, s61, 0
	s_add_i32 s2, s3, s65
	global_load_lds_dwordx4 v[152:153], off
	s_mov_b32 m0, s2
	v_lshl_add_u64 v[152:153], s[0:1], 0, v[146:147]
	global_load_lds_dwordx4 v[152:153], off
	s_add_i32 m0, s2, 0x2000
	v_lshl_add_u64 v[152:153], s[0:1], 0, v[144:145]
	global_load_lds_dwordx4 v[152:153], off
	s_mov_b32 m0, s77
	v_lshl_add_u64 v[152:153], v[202:203], 0, s[10:11]
	global_load_lds_dwordx4 v[152:153], off
	s_mov_b32 m0, s78
	v_lshl_add_u64 v[152:153], v[218:219], 0, s[10:11]
	global_load_lds_dwordx4 v[152:153], off
	s_waitcnt vmcnt(8) lgkmcnt(0)
	s_setprio 1
	s_barrier
	v_mfma_f32_16x16x32_bf16 v[60:63], v[128:131], v[178:181], v[60:63]
	v_mfma_f32_16x16x32_bf16 v[56:59], v[136:139], v[178:181], v[56:59]
	v_mfma_f32_16x16x32_bf16 v[48:51], v[128:131], v[186:189], v[48:51]
	v_mfma_f32_16x16x32_bf16 v[44:47], v[136:139], v[186:189], v[44:47]
	v_mfma_f32_16x16x32_bf16 v[32:35], v[128:131], v[194:197], v[32:35]
	v_mfma_f32_16x16x32_bf16 v[28:31], v[136:139], v[194:197], v[28:31]
	v_mfma_f32_16x16x32_bf16 v[16:19], v[128:131], v[210:213], v[16:19]
	v_mfma_f32_16x16x32_bf16 v[12:15], v[136:139], v[210:213], v[12:15]
	v_mfma_f32_16x16x32_bf16 v[60:63], v[132:135], v[182:185], v[60:63]
	v_mfma_f32_16x16x32_bf16 v[56:59], v[140:143], v[182:185], v[56:59]
	v_mfma_f32_16x16x32_bf16 v[48:51], v[132:135], v[190:193], v[48:51]
	v_mfma_f32_16x16x32_bf16 v[44:47], v[140:143], v[190:193], v[44:47]
	v_mfma_f32_16x16x32_bf16 v[32:35], v[132:135], v[206:209], v[32:35]
	v_mfma_f32_16x16x32_bf16 v[28:31], v[140:143], v[206:209], v[28:31]
	v_mfma_f32_16x16x32_bf16 v[16:19], v[132:135], v[214:217], v[16:19]
	v_mfma_f32_16x16x32_bf16 v[12:15], v[140:143], v[214:217], v[12:15]
	v_mfma_f32_16x16x32_bf16 v[52:55], v[160:163], v[178:181], v[52:55]
	v_mfma_f32_16x16x32_bf16 v[40:43], v[168:171], v[178:181], v[40:43]
	v_mfma_f32_16x16x32_bf16 v[36:39], v[160:163], v[186:189], v[36:39]
	v_mfma_f32_16x16x32_bf16 v[24:27], v[168:171], v[186:189], v[24:27]
	v_mfma_f32_16x16x32_bf16 v[20:23], v[160:163], v[194:197], v[20:23]
	v_mfma_f32_16x16x32_bf16 v[8:11], v[168:171], v[194:197], v[8:11]
	v_mfma_f32_16x16x32_bf16 v[4:7], v[160:163], v[210:213], v[4:7]
	v_mfma_f32_16x16x32_bf16 v[0:3], v[168:171], v[210:213], v[0:3]
	v_mfma_f32_16x16x32_bf16 v[52:55], v[164:167], v[182:185], v[52:55]
	v_mfma_f32_16x16x32_bf16 v[40:43], v[172:175], v[182:185], v[40:43]
	v_mfma_f32_16x16x32_bf16 v[36:39], v[164:167], v[190:193], v[36:39]
	v_mfma_f32_16x16x32_bf16 v[24:27], v[172:175], v[190:193], v[24:27]
	v_mfma_f32_16x16x32_bf16 v[20:23], v[164:167], v[206:209], v[20:23]
	v_mfma_f32_16x16x32_bf16 v[8:11], v[172:175], v[206:209], v[8:11]
	v_mfma_f32_16x16x32_bf16 v[4:7], v[164:167], v[214:217], v[4:7]
	v_mfma_f32_16x16x32_bf16 v[0:3], v[172:175], v[214:217], v[0:3]
	s_setprio 0
	s_barrier
	s_add_i32 s89, s89, 2
	s_add_u32 s87, s87, 0x100
	s_addc_u32 s88, s88, 0
	s_cmpk_gt_u32 s89, 0x55
	s_mov_b64 s[56:57], s[58:59]
	s_cbranch_scc0 .LBB0_541
	s_and_b64 vcc, exec, s[14:15]
	s_cbranch_vccz .LBB0_544
	s_barrier

.LBB0_666:
	ds_read_b128 v[140:143], v147
	ds_read_b128 v[150:153], v147 offset:1024
	ds_read_b128 v[154:157], v147 offset:2048
	ds_read_b128 v[158:161], v147 offset:3072
	ds_read_b128 v[162:165], v148
	ds_read_b128 v[166:169], v148 offset:1024
	ds_read_b128 v[170:173], v148 offset:2048
	ds_read_b128 v[178:181], v148 offset:3072
	ds_read_b128 v[182:185], v149
	ds_read_b128 v[186:189], v149 offset:1024
	ds_read_b128 v[190:193], v149 offset:2048
	ds_read_b128 v[194:197], v149 offset:3072
	ds_read_b128 v[206:209], v149 offset:4096
	ds_read_b128 v[210:213], v149 offset:5120
	ds_read_b128 v[214:217], v149 offset:6144
	ds_read_b128 v[218:221], v149 offset:7168
	s_add_u32 s0, s28, 0xfff80080
	s_addc_u32 s1, s29, -1
	s_cmp_eq_u32 s71, 28
	s_cselect_b32 s35, s15, s1
	s_cselect_b32 s34, s66, s0
	s_cselect_b32 s31, s67, s70
	s_cselect_b32 s30, s68, s69
	s_add_i32 m0, s27, 0xc000
	v_lshl_add_u64 v[174:175], s[28:29], 0, v[136:137]
	global_load_lds_dwordx4 v[174:175], off
	s_add_i32 m0, s27, 0xe000
	v_lshl_add_u64 v[174:175], s[28:29], 0, v[138:139]
	global_load_lds_dwordx4 v[174:175], off
	s_waitcnt vmcnt(8) lgkmcnt(0)
	s_setprio 1
	s_barrier
	v_mfma_f32_16x16x32_bf16 v[124:127], v[140:143], v[182:185], v[124:127]
	v_mfma_f32_16x16x32_bf16 v[120:123], v[154:157], v[182:185], v[120:123]
	v_mfma_f32_16x16x32_bf16 v[116:119], v[140:143], v[190:193], v[116:119]
	v_mfma_f32_16x16x32_bf16 v[108:111], v[154:157], v[190:193], v[108:111]
	v_mfma_f32_16x16x32_bf16 v[100:103], v[140:143], v[206:209], v[100:103]
	v_mfma_f32_16x16x32_bf16 v[92:95], v[154:157], v[206:209], v[92:95]
	v_mfma_f32_16x16x32_bf16 v[84:87], v[140:143], v[214:217], v[84:87]
	v_mfma_f32_16x16x32_bf16 v[76:79], v[154:157], v[214:217], v[76:79]
	v_mfma_f32_16x16x32_bf16 v[124:127], v[150:153], v[186:189], v[124:127]
	v_mfma_f32_16x16x32_bf16 v[120:123], v[158:161], v[186:189], v[120:123]
	v_mfma_f32_16x16x32_bf16 v[116:119], v[150:153], v[194:197], v[116:119]
	v_mfma_f32_16x16x32_bf16 v[108:111], v[158:161], v[194:197], v[108:111]
	v_mfma_f32_16x16x32_bf16 v[100:103], v[150:153], v[210:213], v[100:103]
	v_mfma_f32_16x16x32_bf16 v[92:95], v[158:161], v[210:213], v[92:95]
	v_mfma_f32_16x16x32_bf16 v[84:87], v[150:153], v[218:221], v[84:87]
	v_mfma_f32_16x16x32_bf16 v[76:79], v[158:161], v[218:221], v[76:79]
	v_mfma_f32_16x16x32_bf16 v[112:115], v[162:165], v[182:185], v[112:115]
	v_mfma_f32_16x16x32_bf16 v[104:107], v[170:173], v[182:185], v[104:107]
	v_mfma_f32_16x16x32_bf16 v[96:99], v[162:165], v[190:193], v[96:99]
	v_mfma_f32_16x16x32_bf16 v[88:91], v[170:173], v[190:193], v[88:91]
	v_mfma_f32_16x16x32_bf16 v[80:83], v[162:165], v[206:209], v[80:83]
	v_mfma_f32_16x16x32_bf16 v[72:75], v[170:173], v[206:209], v[72:75]
	v_mfma_f32_16x16x32_bf16 v[68:71], v[162:165], v[214:217], v[68:71]
	v_mfma_f32_16x16x32_bf16 v[64:67], v[170:173], v[214:217], v[64:67]
	v_mfma_f32_16x16x32_bf16 v[112:115], v[166:169], v[186:189], v[112:115]
	v_mfma_f32_16x16x32_bf16 v[104:107], v[178:181], v[186:189], v[104:107]
	v_mfma_f32_16x16x32_bf16 v[96:99], v[166:169], v[194:197], v[96:99]
	v_mfma_f32_16x16x32_bf16 v[88:91], v[178:181], v[194:197], v[88:91]
	v_mfma_f32_16x16x32_bf16 v[80:83], v[166:169], v[210:213], v[80:83]
	v_mfma_f32_16x16x32_bf16 v[72:75], v[178:181], v[210:213], v[72:75]
	v_mfma_f32_16x16x32_bf16 v[68:71], v[166:169], v[218:221], v[68:71]
	v_mfma_f32_16x16x32_bf16 v[64:67], v[178:181], v[218:221], v[64:67]
	s_setprio 0
	s_barrier
	ds_read_b128 v[182:185], v149 offset:16384
	ds_read_b128 v[186:189], v149 offset:17408
	ds_read_b128 v[190:193], v149 offset:18432
	ds_read_b128 v[194:197], v149 offset:19456
	ds_read_b128 v[206:209], v149 offset:20480
	ds_read_b128 v[210:213], v149 offset:21504
	ds_read_b128 v[214:217], v149 offset:22528
	ds_read_b128 v[218:221], v149 offset:23552
	s_add_i32 s0, s62, s53
	s_mov_b32 m0, s0
	v_lshl_add_u64 v[174:175], s[30:31], 0, v[132:133]
	global_load_lds_dwordx4 v[174:175], off
	s_add_i32 m0, s0, 0x2000
	s_add_u32 s0, s30, 0x80000
	v_lshl_add_u64 v[198:199], s[30:31], 0, v[128:129]
	s_addc_u32 s1, s31, 0
	s_add_i32 s2, s63, s53
	global_load_lds_dwordx4 v[198:199], off
	v_lshl_add_u64 v[202:203], s[0:1], 0, v[132:133]
	s_mov_b32 m0, s2
	v_lshl_add_u64 v[222:223], s[34:35], 0, v[130:131]
	global_load_lds_dwordx4 v[202:203], off
	s_add_i32 m0, s2, 0x2000
	v_lshl_add_u64 v[202:203], s[0:1], 0, v[128:129]
	global_load_lds_dwordx4 v[202:203], off
	s_mov_b32 m0, s27
	v_lshl_add_u64 v[202:203], s[34:35], 0, v[134:135]
	global_load_lds_dwordx4 v[202:203], off
	s_mov_b32 m0, s55
	s_nop 0
	global_load_lds_dwordx4 v[222:223], off
	s_waitcnt vmcnt(8) lgkmcnt(0)
	s_setprio 1
	s_barrier
	v_mfma_f32_16x16x32_bf16 v[60:63], v[140:143], v[182:185], v[60:63]
	v_mfma_f32_16x16x32_bf16 v[56:59], v[154:157], v[182:185], v[56:59]
	v_mfma_f32_16x16x32_bf16 v[52:55], v[140:143], v[190:193], v[52:55]
	v_mfma_f32_16x16x32_bf16 v[44:47], v[154:157], v[190:193], v[44:47]
	v_mfma_f32_16x16x32_bf16 v[36:39], v[140:143], v[206:209], v[36:39]
	v_mfma_f32_16x16x32_bf16 v[28:31], v[154:157], v[206:209], v[28:31]
	v_mfma_f32_16x16x32_bf16 v[20:23], v[140:143], v[214:217], v[20:23]
	v_mfma_f32_16x16x32_bf16 v[12:15], v[154:157], v[214:217], v[12:15]
	v_mfma_f32_16x16x32_bf16 v[60:63], v[150:153], v[186:189], v[60:63]
	v_mfma_f32_16x16x32_bf16 v[56:59], v[158:161], v[186:189], v[56:59]
	v_mfma_f32_16x16x32_bf16 v[52:55], v[150:153], v[194:197], v[52:55]
	v_mfma_f32_16x16x32_bf16 v[44:47], v[158:161], v[194:197], v[44:47]
	v_mfma_f32_16x16x32_bf16 v[36:39], v[150:153], v[210:213], v[36:39]
	v_mfma_f32_16x16x32_bf16 v[28:31], v[158:161], v[210:213], v[28:31]
	v_mfma_f32_16x16x32_bf16 v[20:23], v[150:153], v[218:221], v[20:23]
	v_mfma_f32_16x16x32_bf16 v[12:15], v[158:161], v[218:221], v[12:15]
	v_mfma_f32_16x16x32_bf16 v[48:51], v[162:165], v[182:185], v[48:51]
	v_mfma_f32_16x16x32_bf16 v[40:43], v[170:173], v[182:185], v[40:43]
	v_mfma_f32_16x16x32_bf16 v[32:35], v[162:165], v[190:193], v[32:35]
	v_mfma_f32_16x16x32_bf16 v[24:27], v[170:173], v[190:193], v[24:27]
	v_mfma_f32_16x16x32_bf16 v[16:19], v[162:165], v[206:209], v[16:19]
	v_mfma_f32_16x16x32_bf16 v[8:11], v[170:173], v[206:209], v[8:11]
	v_mfma_f32_16x16x32_bf16 v[4:7], v[162:165], v[214:217], v[4:7]
	v_mfma_f32_16x16x32_bf16 v[0:3], v[170:173], v[214:217], v[0:3]
	v_mfma_f32_16x16x32_bf16 v[48:51], v[166:169], v[186:189], v[48:51]
	v_mfma_f32_16x16x32_bf16 v[40:43], v[178:181], v[186:189], v[40:43]
	v_mfma_f32_16x16x32_bf16 v[32:35], v[166:169], v[194:197], v[32:35]
	v_mfma_f32_16x16x32_bf16 v[24:27], v[178:181], v[194:197], v[24:27]
	v_mfma_f32_16x16x32_bf16 v[16:19], v[166:169], v[210:213], v[16:19]
	v_mfma_f32_16x16x32_bf16 v[8:11], v[178:181], v[210:213], v[8:11]
	v_mfma_f32_16x16x32_bf16 v[4:7], v[166:169], v[218:221], v[4:7]
	v_mfma_f32_16x16x32_bf16 v[0:3], v[178:181], v[218:221], v[0:3]
	s_setprio 0
	s_barrier
	ds_read_b128 v[182:185], v149 offset:32768
	ds_read_b128 v[186:189], v149 offset:33792
	ds_read_b128 v[190:193], v149 offset:34816
	ds_read_b128 v[194:197], v149 offset:35840
	ds_read_b128 v[206:209], v149 offset:36864
	ds_read_b128 v[210:213], v149 offset:37888
	ds_read_b128 v[214:217], v149 offset:38912
	ds_read_b128 v[218:221], v149 offset:39936
	s_add_i32 s2, 0, 0x18000
	s_add_i32 s3, 0, 0x1c000
	v_add_u32_e32 v158, s2, v146
	v_add_u32_e32 v177, s3, v146
	ds_read_b128 v[140:143], v158
	ds_read_b128 v[150:153], v158 offset:1024
	ds_read_b128 v[154:157], v158 offset:2048
	ds_read_b128 v[158:161], v158 offset:3072
	ds_read_b128 v[162:165], v177
	ds_read_b128 v[166:169], v177 offset:1024
	ds_read_b128 v[170:173], v177 offset:2048
	ds_read_b128 v[178:181], v177 offset:3072
	s_add_u32 s0, s34, 0x80000
	s_addc_u32 s1, s35, 0
	s_mov_b32 m0, s56
	v_lshl_add_u64 v[224:225], s[0:1], 0, v[134:135]
	global_load_lds_dwordx4 v[224:225], off
	s_mov_b32 m0, s57
	v_lshl_add_u64 v[224:225], s[0:1], 0, v[130:131]
	global_load_lds_dwordx4 v[224:225], off
	s_waitcnt vmcnt(8) lgkmcnt(0)
	s_setprio 1
	s_barrier
	v_mfma_f32_16x16x32_bf16 v[124:127], v[140:143], v[182:185], v[124:127]
	v_mfma_f32_16x16x32_bf16 v[120:123], v[154:157], v[182:185], v[120:123]
	v_mfma_f32_16x16x32_bf16 v[116:119], v[140:143], v[190:193], v[116:119]
	v_mfma_f32_16x16x32_bf16 v[108:111], v[154:157], v[190:193], v[108:111]
	v_mfma_f32_16x16x32_bf16 v[100:103], v[140:143], v[206:209], v[100:103]
	v_mfma_f32_16x16x32_bf16 v[92:95], v[154:157], v[206:209], v[92:95]
	v_mfma_f32_16x16x32_bf16 v[84:87], v[140:143], v[214:217], v[84:87]
	v_mfma_f32_16x16x32_bf16 v[76:79], v[154:157], v[214:217], v[76:79]
	v_mfma_f32_16x16x32_bf16 v[124:127], v[150:153], v[186:189], v[124:127]
	v_mfma_f32_16x16x32_bf16 v[120:123], v[158:161], v[186:189], v[120:123]
	v_mfma_f32_16x16x32_bf16 v[116:119], v[150:153], v[194:197], v[116:119]
	v_mfma_f32_16x16x32_bf16 v[108:111], v[158:161], v[194:197], v[108:111]
	v_mfma_f32_16x16x32_bf16 v[100:103], v[150:153], v[210:213], v[100:103]
	v_mfma_f32_16x16x32_bf16 v[92:95], v[158:161], v[210:213], v[92:95]
	v_mfma_f32_16x16x32_bf16 v[84:87], v[150:153], v[218:221], v[84:87]
	v_mfma_f32_16x16x32_bf16 v[76:79], v[158:161], v[218:221], v[76:79]
	v_mfma_f32_16x16x32_bf16 v[112:115], v[162:165], v[182:185], v[112:115]
	v_mfma_f32_16x16x32_bf16 v[104:107], v[170:173], v[182:185], v[104:107]
	v_mfma_f32_16x16x32_bf16 v[96:99], v[162:165], v[190:193], v[96:99]
	v_mfma_f32_16x16x32_bf16 v[88:91], v[170:173], v[190:193], v[88:91]
	v_mfma_f32_16x16x32_bf16 v[80:83], v[162:165], v[206:209], v[80:83]
	v_mfma_f32_16x16x32_bf16 v[72:75], v[170:173], v[206:209], v[72:75]
	v_mfma_f32_16x16x32_bf16 v[68:71], v[162:165], v[214:217], v[68:71]
	v_mfma_f32_16x16x32_bf16 v[64:67], v[170:173], v[214:217], v[64:67]
	v_mfma_f32_16x16x32_bf16 v[112:115], v[166:169], v[186:189], v[112:115]
	v_mfma_f32_16x16x32_bf16 v[104:107], v[178:181], v[186:189], v[104:107]
	v_mfma_f32_16x16x32_bf16 v[96:99], v[166:169], v[194:197], v[96:99]
	v_mfma_f32_16x16x32_bf16 v[88:91], v[178:181], v[194:197], v[88:91]
	v_mfma_f32_16x16x32_bf16 v[80:83], v[166:169], v[210:213], v[80:83]
	v_mfma_f32_16x16x32_bf16 v[72:75], v[178:181], v[210:213], v[72:75]
	v_mfma_f32_16x16x32_bf16 v[68:71], v[166:169], v[218:221], v[68:71]
	v_mfma_f32_16x16x32_bf16 v[64:67], v[178:181], v[218:221], v[64:67]
	s_setprio 0
	s_barrier
	ds_read_b128 v[182:185], v149 offset:49152
	ds_read_b128 v[186:189], v149 offset:50176
	ds_read_b128 v[190:193], v149 offset:51200
	ds_read_b128 v[194:197], v149 offset:52224
	ds_read_b128 v[206:209], v149 offset:53248
	ds_read_b128 v[210:213], v149 offset:54272
	ds_read_b128 v[214:217], v149 offset:55296
	ds_read_b128 v[218:221], v149 offset:56320
	s_add_i32 s0, s2, s53
	s_mov_b32 m0, s0
	v_lshl_add_u64 v[174:175], v[174:175], 0, s[8:9]
	global_load_lds_dwordx4 v[174:175], off
	s_add_i32 m0, s0, 0x2000
	s_add_u32 s0, s30, 0x80080
	v_lshl_add_u64 v[174:175], v[198:199], 0, s[8:9]
	s_addc_u32 s1, s31, 0
	s_add_i32 s2, s3, s53
	global_load_lds_dwordx4 v[174:175], off
	s_mov_b32 m0, s2
	v_lshl_add_u64 v[174:175], s[0:1], 0, v[132:133]
	global_load_lds_dwordx4 v[174:175], off
	s_add_i32 m0, s2, 0x2000
	v_lshl_add_u64 v[174:175], s[0:1], 0, v[128:129]
	global_load_lds_dwordx4 v[174:175], off
	s_mov_b32 m0, s60
	v_lshl_add_u64 v[174:175], v[202:203], 0, s[8:9]
	global_load_lds_dwordx4 v[174:175], off
	s_mov_b32 m0, s61
	v_lshl_add_u64 v[174:175], v[222:223], 0, s[8:9]
	global_load_lds_dwordx4 v[174:175], off
	s_waitcnt vmcnt(8) lgkmcnt(0)
	s_setprio 1
	s_barrier
	v_mfma_f32_16x16x32_bf16 v[60:63], v[140:143], v[182:185], v[60:63]
	v_mfma_f32_16x16x32_bf16 v[56:59], v[154:157], v[182:185], v[56:59]
	v_mfma_f32_16x16x32_bf16 v[52:55], v[140:143], v[190:193], v[52:55]
	v_mfma_f32_16x16x32_bf16 v[44:47], v[154:157], v[190:193], v[44:47]
	v_mfma_f32_16x16x32_bf16 v[36:39], v[140:143], v[206:209], v[36:39]
	v_mfma_f32_16x16x32_bf16 v[28:31], v[154:157], v[206:209], v[28:31]
	v_mfma_f32_16x16x32_bf16 v[20:23], v[140:143], v[214:217], v[20:23]
	v_mfma_f32_16x16x32_bf16 v[12:15], v[154:157], v[214:217], v[12:15]
	v_mfma_f32_16x16x32_bf16 v[60:63], v[150:153], v[186:189], v[60:63]
	v_mfma_f32_16x16x32_bf16 v[56:59], v[158:161], v[186:189], v[56:59]
	v_mfma_f32_16x16x32_bf16 v[52:55], v[150:153], v[194:197], v[52:55]
	v_mfma_f32_16x16x32_bf16 v[44:47], v[158:161], v[194:197], v[44:47]
	v_mfma_f32_16x16x32_bf16 v[36:39], v[150:153], v[210:213], v[36:39]
	v_mfma_f32_16x16x32_bf16 v[28:31], v[158:161], v[210:213], v[28:31]
	v_mfma_f32_16x16x32_bf16 v[20:23], v[150:153], v[218:221], v[20:23]
	v_mfma_f32_16x16x32_bf16 v[12:15], v[158:161], v[218:221], v[12:15]
	v_mfma_f32_16x16x32_bf16 v[48:51], v[162:165], v[182:185], v[48:51]
	v_mfma_f32_16x16x32_bf16 v[40:43], v[170:173], v[182:185], v[40:43]
	v_mfma_f32_16x16x32_bf16 v[32:35], v[162:165], v[190:193], v[32:35]
	v_mfma_f32_16x16x32_bf16 v[24:27], v[170:173], v[190:193], v[24:27]
	v_mfma_f32_16x16x32_bf16 v[16:19], v[162:165], v[206:209], v[16:19]
	v_mfma_f32_16x16x32_bf16 v[8:11], v[170:173], v[206:209], v[8:11]
	v_mfma_f32_16x16x32_bf16 v[4:7], v[162:165], v[214:217], v[4:7]
	v_mfma_f32_16x16x32_bf16 v[0:3], v[170:173], v[214:217], v[0:3]
	v_mfma_f32_16x16x32_bf16 v[48:51], v[166:169], v[186:189], v[48:51]
	v_mfma_f32_16x16x32_bf16 v[40:43], v[178:181], v[186:189], v[40:43]
	v_mfma_f32_16x16x32_bf16 v[32:35], v[166:169], v[194:197], v[32:35]
	v_mfma_f32_16x16x32_bf16 v[24:27], v[178:181], v[194:197], v[24:27]
	v_mfma_f32_16x16x32_bf16 v[16:19], v[166:169], v[210:213], v[16:19]
	v_mfma_f32_16x16x32_bf16 v[8:11], v[178:181], v[210:213], v[8:11]
	v_mfma_f32_16x16x32_bf16 v[4:7], v[166:169], v[218:221], v[4:7]
	v_mfma_f32_16x16x32_bf16 v[0:3], v[178:181], v[218:221], v[0:3]
	s_setprio 0
	s_barrier
	s_add_i32 s71, s71, 2
	s_add_u32 s28, s28, 0x100
	s_addc_u32 s29, s29, 0
	s_add_u32 s69, s69, 0x100
	s_addc_u32 s70, s70, 0
	s_cmp_gt_u32 s71, 29
	s_cbranch_scc0 .LBB0_666
	s_and_b64 vcc, exec, s[12:13]
	s_cbranch_vccz .LBB0_669
	s_barrier

.LBB0_828:
	ds_read_b128 v[138:141], v145
	ds_read_b128 v[150:153], v145 offset:1024
	ds_read_b128 v[154:157], v145 offset:2048
	ds_read_b128 v[158:161], v145 offset:3072
	ds_read_b128 v[162:165], v146
	ds_read_b128 v[166:169], v146 offset:1024
	ds_read_b128 v[170:173], v146 offset:2048
	ds_read_b128 v[178:181], v146 offset:3072
	ds_read_b128 v[182:185], v147
	ds_read_b128 v[186:189], v147 offset:1024
	ds_read_b128 v[190:193], v147 offset:2048
	ds_read_b128 v[194:197], v147 offset:3072
	ds_read_b128 v[206:209], v147 offset:4096
	ds_read_b128 v[210:213], v147 offset:5120
	ds_read_b128 v[214:217], v147 offset:6144
	ds_read_b128 v[218:221], v147 offset:7168
	s_add_u32 s2, s58, s62
	s_addc_u32 s3, s59, s63
	s_add_u32 s9, s2, 0x100
	s_addc_u32 s38, s3, 0
	s_and_b64 s[0:1], s[60:61], exec
	v_cndmask_b32_e64 v137, 0, 1, s[64:65]
	s_cselect_b32 s65, s23, s38
	s_cselect_b32 s64, s12, s9
	s_add_u32 s0, s56, s62
	s_addc_u32 s1, s57, s63
	s_add_u32 s9, s0, 0x100
	s_addc_u32 s38, s1, 0
	s_and_b64 s[0:1], s[60:61], exec
	s_cselect_b32 s67, s13, s38
	s_cselect_b32 s66, s8, s9
	s_add_u32 s70, s2, 0x80080
	s_addc_u32 s71, s3, 0
	s_add_i32 s39, s87, s79
	s_add_i32 m0, s74, 0xc000
	s_add_i32 s53, s74, 0xe000
	s_add_i32 s50, s39, 0x2000
	s_add_u32 s68, s66, 0x80000
	s_addc_u32 s69, s67, 0
	s_add_i32 s51, s88, s79
	s_add_i32 s38, s51, 0x2000
	s_add_i32 s1, 0, 0x18000
	s_add_i32 s9, 0, 0x1c000
	s_add_u32 s62, s64, 0x80000
	s_addc_u32 s63, s65, 0
	s_add_i32 s3, s1, s79
	s_add_i32 s76, s3, 0x2000
	s_add_u32 s60, s66, 0x80080
	s_addc_u32 s61, s67, 0
	s_add_i32 s2, s9, s79
	s_add_i32 s0, s2, 0x2000
	v_cmp_ne_u32_e32 vcc, 1, v137
	v_lshl_add_u64 v[174:175], s[70:71], 0, v[128:129]
	global_load_lds_dwordx4 v[174:175], off
	s_mov_b32 m0, s53
	v_lshl_add_u64 v[174:175], s[70:71], 0, v[132:133]
	global_load_lds_dwordx4 v[174:175], off
	s_waitcnt vmcnt(8) lgkmcnt(0)
	s_setprio 1
	s_barrier
	v_mfma_f32_16x16x32_bf16 v[124:127], v[138:141], v[182:185], v[124:127]
	v_mfma_f32_16x16x32_bf16 v[120:123], v[154:157], v[182:185], v[120:123]
	v_mfma_f32_16x16x32_bf16 v[108:111], v[138:141], v[190:193], v[108:111]
	v_mfma_f32_16x16x32_bf16 v[104:107], v[154:157], v[190:193], v[104:107]
	v_mfma_f32_16x16x32_bf16 v[92:95], v[138:141], v[206:209], v[92:95]
	v_mfma_f32_16x16x32_bf16 v[88:91], v[154:157], v[206:209], v[88:91]
	v_mfma_f32_16x16x32_bf16 v[76:79], v[138:141], v[214:217], v[76:79]
	v_mfma_f32_16x16x32_bf16 v[72:75], v[154:157], v[214:217], v[72:75]
	v_mfma_f32_16x16x32_bf16 v[124:127], v[150:153], v[186:189], v[124:127]
	v_mfma_f32_16x16x32_bf16 v[120:123], v[158:161], v[186:189], v[120:123]
	v_mfma_f32_16x16x32_bf16 v[108:111], v[150:153], v[194:197], v[108:111]
	v_mfma_f32_16x16x32_bf16 v[104:107], v[158:161], v[194:197], v[104:107]
	v_mfma_f32_16x16x32_bf16 v[92:95], v[150:153], v[210:213], v[92:95]
	v_mfma_f32_16x16x32_bf16 v[88:91], v[158:161], v[210:213], v[88:91]
	v_mfma_f32_16x16x32_bf16 v[76:79], v[150:153], v[218:221], v[76:79]
	v_mfma_f32_16x16x32_bf16 v[72:75], v[158:161], v[218:221], v[72:75]
	v_mfma_f32_16x16x32_bf16 v[116:119], v[162:165], v[182:185], v[116:119]
	v_mfma_f32_16x16x32_bf16 v[112:115], v[170:173], v[182:185], v[112:115]
	v_mfma_f32_16x16x32_bf16 v[100:103], v[162:165], v[190:193], v[100:103]
	v_mfma_f32_16x16x32_bf16 v[96:99], v[170:173], v[190:193], v[96:99]
	v_mfma_f32_16x16x32_bf16 v[84:87], v[162:165], v[206:209], v[84:87]
	v_mfma_f32_16x16x32_bf16 v[80:83], v[170:173], v[206:209], v[80:83]
	v_mfma_f32_16x16x32_bf16 v[68:71], v[162:165], v[214:217], v[68:71]
	v_mfma_f32_16x16x32_bf16 v[64:67], v[170:173], v[214:217], v[64:67]
	v_mfma_f32_16x16x32_bf16 v[116:119], v[166:169], v[186:189], v[116:119]
	v_mfma_f32_16x16x32_bf16 v[112:115], v[178:181], v[186:189], v[112:115]
	v_mfma_f32_16x16x32_bf16 v[100:103], v[166:169], v[194:197], v[100:103]
	v_mfma_f32_16x16x32_bf16 v[96:99], v[178:181], v[194:197], v[96:99]
	v_mfma_f32_16x16x32_bf16 v[84:87], v[166:169], v[210:213], v[84:87]
	v_mfma_f32_16x16x32_bf16 v[80:83], v[178:181], v[210:213], v[80:83]
	v_mfma_f32_16x16x32_bf16 v[68:71], v[166:169], v[218:221], v[68:71]
	v_mfma_f32_16x16x32_bf16 v[64:67], v[178:181], v[218:221], v[64:67]
	s_setprio 0
	s_barrier
	ds_read_b128 v[182:185], v147 offset:16384
	ds_read_b128 v[186:189], v147 offset:17408
	ds_read_b128 v[190:193], v147 offset:18432
	ds_read_b128 v[194:197], v147 offset:19456
	ds_read_b128 v[206:209], v147 offset:20480
	ds_read_b128 v[210:213], v147 offset:21504
	ds_read_b128 v[214:217], v147 offset:22528
	ds_read_b128 v[218:221], v147 offset:23552
	s_mov_b32 m0, s39
	v_lshl_add_u64 v[174:175], s[66:67], 0, v[130:131]
	global_load_lds_dwordx4 v[174:175], off
	v_lshl_add_u64 v[198:199], s[66:67], 0, v[134:135]
	s_mov_b32 m0, s50
	v_lshl_add_u64 v[202:203], s[68:69], 0, v[130:131]
	global_load_lds_dwordx4 v[198:199], off
	s_mov_b32 m0, s51
	v_lshl_add_u64 v[222:223], s[64:65], 0, v[132:133]
	global_load_lds_dwordx4 v[202:203], off
	s_mov_b32 m0, s38
	v_lshl_add_u64 v[202:203], s[68:69], 0, v[134:135]
	global_load_lds_dwordx4 v[202:203], off
	s_mov_b32 m0, s74
	v_lshl_add_u64 v[202:203], s[64:65], 0, v[128:129]
	global_load_lds_dwordx4 v[202:203], off
	s_mov_b32 m0, s55
	s_nop 0
	global_load_lds_dwordx4 v[222:223], off
	s_waitcnt vmcnt(8) lgkmcnt(0)
	s_setprio 1
	s_barrier
	v_mfma_f32_16x16x32_bf16 v[60:63], v[138:141], v[182:185], v[60:63]
	v_mfma_f32_16x16x32_bf16 v[56:59], v[154:157], v[182:185], v[56:59]
	v_mfma_f32_16x16x32_bf16 v[44:47], v[138:141], v[190:193], v[44:47]
	v_mfma_f32_16x16x32_bf16 v[40:43], v[154:157], v[190:193], v[40:43]
	v_mfma_f32_16x16x32_bf16 v[28:31], v[138:141], v[206:209], v[28:31]
	v_mfma_f32_16x16x32_bf16 v[24:27], v[154:157], v[206:209], v[24:27]
	v_mfma_f32_16x16x32_bf16 v[12:15], v[138:141], v[214:217], v[12:15]
	v_mfma_f32_16x16x32_bf16 v[8:11], v[154:157], v[214:217], v[8:11]
	v_mfma_f32_16x16x32_bf16 v[60:63], v[150:153], v[186:189], v[60:63]
	v_mfma_f32_16x16x32_bf16 v[56:59], v[158:161], v[186:189], v[56:59]
	v_mfma_f32_16x16x32_bf16 v[44:47], v[150:153], v[194:197], v[44:47]
	v_mfma_f32_16x16x32_bf16 v[40:43], v[158:161], v[194:197], v[40:43]
	v_mfma_f32_16x16x32_bf16 v[28:31], v[150:153], v[210:213], v[28:31]
	v_mfma_f32_16x16x32_bf16 v[24:27], v[158:161], v[210:213], v[24:27]
	v_mfma_f32_16x16x32_bf16 v[12:15], v[150:153], v[218:221], v[12:15]
	v_mfma_f32_16x16x32_bf16 v[8:11], v[158:161], v[218:221], v[8:11]
	v_mfma_f32_16x16x32_bf16 v[52:55], v[162:165], v[182:185], v[52:55]
	v_mfma_f32_16x16x32_bf16 v[48:51], v[170:173], v[182:185], v[48:51]
	v_mfma_f32_16x16x32_bf16 v[36:39], v[162:165], v[190:193], v[36:39]
	v_mfma_f32_16x16x32_bf16 v[32:35], v[170:173], v[190:193], v[32:35]
	v_mfma_f32_16x16x32_bf16 v[20:23], v[162:165], v[206:209], v[20:23]
	v_mfma_f32_16x16x32_bf16 v[16:19], v[170:173], v[206:209], v[16:19]
	v_mfma_f32_16x16x32_bf16 v[4:7], v[162:165], v[214:217], v[4:7]
	v_mfma_f32_16x16x32_bf16 v[0:3], v[170:173], v[214:217], v[0:3]
	v_mfma_f32_16x16x32_bf16 v[52:55], v[166:169], v[186:189], v[52:55]
	v_mfma_f32_16x16x32_bf16 v[48:51], v[178:181], v[186:189], v[48:51]
	v_mfma_f32_16x16x32_bf16 v[36:39], v[166:169], v[194:197], v[36:39]
	v_mfma_f32_16x16x32_bf16 v[32:35], v[178:181], v[194:197], v[32:35]
	v_mfma_f32_16x16x32_bf16 v[20:23], v[166:169], v[210:213], v[20:23]
	v_mfma_f32_16x16x32_bf16 v[16:19], v[178:181], v[210:213], v[16:19]
	v_mfma_f32_16x16x32_bf16 v[4:7], v[166:169], v[218:221], v[4:7]
	v_mfma_f32_16x16x32_bf16 v[0:3], v[178:181], v[218:221], v[0:3]
	s_setprio 0
	s_barrier
	ds_read_b128 v[182:185], v147 offset:32768
	ds_read_b128 v[186:189], v147 offset:33792
	ds_read_b128 v[190:193], v147 offset:34816
	ds_read_b128 v[194:197], v147 offset:35840
	ds_read_b128 v[206:209], v147 offset:36864
	ds_read_b128 v[210:213], v147 offset:37888
	ds_read_b128 v[214:217], v147 offset:38912
	ds_read_b128 v[218:221], v147 offset:39936
	v_add_u32_e32 v137, s1, v144
	ds_read_b128 v[138:141], v137
	ds_read_b128 v[150:153], v137 offset:1024
	ds_read_b128 v[154:157], v137 offset:2048
	ds_read_b128 v[158:161], v137 offset:3072
	v_add_u32_e32 v137, s9, v144
	ds_read_b128 v[162:165], v137
	ds_read_b128 v[166:169], v137 offset:1024
	ds_read_b128 v[170:173], v137 offset:2048
	ds_read_b128 v[178:181], v137 offset:3072
	s_mov_b32 m0, s80
	v_lshl_add_u64 v[224:225], s[62:63], 0, v[128:129]
	global_load_lds_dwordx4 v[224:225], off
	s_mov_b32 m0, s81
	v_lshl_add_u64 v[224:225], s[62:63], 0, v[132:133]
	global_load_lds_dwordx4 v[224:225], off
	s_waitcnt vmcnt(8) lgkmcnt(0)
	s_setprio 1
	s_barrier
	v_mfma_f32_16x16x32_bf16 v[124:127], v[138:141], v[182:185], v[124:127]
	v_mfma_f32_16x16x32_bf16 v[120:123], v[154:157], v[182:185], v[120:123]
	v_mfma_f32_16x16x32_bf16 v[108:111], v[138:141], v[190:193], v[108:111]
	v_mfma_f32_16x16x32_bf16 v[104:107], v[154:157], v[190:193], v[104:107]
	v_mfma_f32_16x16x32_bf16 v[92:95], v[138:141], v[206:209], v[92:95]
	v_mfma_f32_16x16x32_bf16 v[88:91], v[154:157], v[206:209], v[88:91]
	v_mfma_f32_16x16x32_bf16 v[76:79], v[138:141], v[214:217], v[76:79]
	v_mfma_f32_16x16x32_bf16 v[72:75], v[154:157], v[214:217], v[72:75]
	v_mfma_f32_16x16x32_bf16 v[124:127], v[150:153], v[186:189], v[124:127]
	v_mfma_f32_16x16x32_bf16 v[120:123], v[158:161], v[186:189], v[120:123]
	v_mfma_f32_16x16x32_bf16 v[108:111], v[150:153], v[194:197], v[108:111]
	v_mfma_f32_16x16x32_bf16 v[104:107], v[158:161], v[194:197], v[104:107]
	v_mfma_f32_16x16x32_bf16 v[92:95], v[150:153], v[210:213], v[92:95]
	v_mfma_f32_16x16x32_bf16 v[88:91], v[158:161], v[210:213], v[88:91]
	v_mfma_f32_16x16x32_bf16 v[76:79], v[150:153], v[218:221], v[76:79]
	v_mfma_f32_16x16x32_bf16 v[72:75], v[158:161], v[218:221], v[72:75]
	v_mfma_f32_16x16x32_bf16 v[116:119], v[162:165], v[182:185], v[116:119]
	v_mfma_f32_16x16x32_bf16 v[112:115], v[170:173], v[182:185], v[112:115]
	v_mfma_f32_16x16x32_bf16 v[100:103], v[162:165], v[190:193], v[100:103]
	v_mfma_f32_16x16x32_bf16 v[96:99], v[170:173], v[190:193], v[96:99]
	v_mfma_f32_16x16x32_bf16 v[84:87], v[162:165], v[206:209], v[84:87]
	v_mfma_f32_16x16x32_bf16 v[80:83], v[170:173], v[206:209], v[80:83]
	v_mfma_f32_16x16x32_bf16 v[68:71], v[162:165], v[214:217], v[68:71]
	v_mfma_f32_16x16x32_bf16 v[64:67], v[170:173], v[214:217], v[64:67]
	v_mfma_f32_16x16x32_bf16 v[116:119], v[166:169], v[186:189], v[116:119]
	v_mfma_f32_16x16x32_bf16 v[112:115], v[178:181], v[186:189], v[112:115]
	v_mfma_f32_16x16x32_bf16 v[100:103], v[166:169], v[194:197], v[100:103]
	v_mfma_f32_16x16x32_bf16 v[96:99], v[178:181], v[194:197], v[96:99]
	v_mfma_f32_16x16x32_bf16 v[84:87], v[166:169], v[210:213], v[84:87]
	v_mfma_f32_16x16x32_bf16 v[80:83], v[178:181], v[210:213], v[80:83]
	v_mfma_f32_16x16x32_bf16 v[68:71], v[166:169], v[218:221], v[68:71]
	v_mfma_f32_16x16x32_bf16 v[64:67], v[178:181], v[218:221], v[64:67]
	s_setprio 0
	s_barrier
	ds_read_b128 v[182:185], v147 offset:49152
	ds_read_b128 v[186:189], v147 offset:50176
	ds_read_b128 v[190:193], v147 offset:51200
	ds_read_b128 v[194:197], v147 offset:52224
	ds_read_b128 v[206:209], v147 offset:53248
	ds_read_b128 v[210:213], v147 offset:54272
	ds_read_b128 v[214:217], v147 offset:55296
	ds_read_b128 v[218:221], v147 offset:56320
	s_mov_b32 m0, s3
	v_lshl_add_u64 v[174:175], v[174:175], 0, s[16:17]
	global_load_lds_dwordx4 v[174:175], off
	s_mov_b32 m0, s76
	v_lshl_add_u64 v[174:175], v[198:199], 0, s[16:17]
	global_load_lds_dwordx4 v[174:175], off
	s_mov_b32 m0, s2
	v_lshl_add_u64 v[174:175], s[60:61], 0, v[130:131]
	global_load_lds_dwordx4 v[174:175], off
	s_mov_b32 m0, s0
	v_lshl_add_u64 v[174:175], s[60:61], 0, v[134:135]
	global_load_lds_dwordx4 v[174:175], off
	s_mov_b32 m0, s85
	v_lshl_add_u64 v[174:175], v[202:203], 0, s[16:17]
	global_load_lds_dwordx4 v[174:175], off
	s_mov_b32 m0, s86
	v_lshl_add_u64 v[174:175], v[222:223], 0, s[16:17]
	global_load_lds_dwordx4 v[174:175], off
	s_waitcnt vmcnt(8) lgkmcnt(0)
	s_setprio 1
	s_barrier
	v_mfma_f32_16x16x32_bf16 v[60:63], v[138:141], v[182:185], v[60:63]
	v_mfma_f32_16x16x32_bf16 v[56:59], v[154:157], v[182:185], v[56:59]
	v_mfma_f32_16x16x32_bf16 v[44:47], v[138:141], v[190:193], v[44:47]
	v_mfma_f32_16x16x32_bf16 v[40:43], v[154:157], v[190:193], v[40:43]
	v_mfma_f32_16x16x32_bf16 v[28:31], v[138:141], v[206:209], v[28:31]
	v_mfma_f32_16x16x32_bf16 v[24:27], v[154:157], v[206:209], v[24:27]
	v_mfma_f32_16x16x32_bf16 v[12:15], v[138:141], v[214:217], v[12:15]
	v_mfma_f32_16x16x32_bf16 v[8:11], v[154:157], v[214:217], v[8:11]
	v_mfma_f32_16x16x32_bf16 v[60:63], v[150:153], v[186:189], v[60:63]
	v_mfma_f32_16x16x32_bf16 v[56:59], v[158:161], v[186:189], v[56:59]
	v_mfma_f32_16x16x32_bf16 v[44:47], v[150:153], v[194:197], v[44:47]
	v_mfma_f32_16x16x32_bf16 v[40:43], v[158:161], v[194:197], v[40:43]
	v_mfma_f32_16x16x32_bf16 v[28:31], v[150:153], v[210:213], v[28:31]
	v_mfma_f32_16x16x32_bf16 v[24:27], v[158:161], v[210:213], v[24:27]
	v_mfma_f32_16x16x32_bf16 v[12:15], v[150:153], v[218:221], v[12:15]
	v_mfma_f32_16x16x32_bf16 v[8:11], v[158:161], v[218:221], v[8:11]
	v_mfma_f32_16x16x32_bf16 v[52:55], v[162:165], v[182:185], v[52:55]
	v_mfma_f32_16x16x32_bf16 v[48:51], v[170:173], v[182:185], v[48:51]
	v_mfma_f32_16x16x32_bf16 v[36:39], v[162:165], v[190:193], v[36:39]
	v_mfma_f32_16x16x32_bf16 v[32:35], v[170:173], v[190:193], v[32:35]
	v_mfma_f32_16x16x32_bf16 v[20:23], v[162:165], v[206:209], v[20:23]
	v_mfma_f32_16x16x32_bf16 v[16:19], v[170:173], v[206:209], v[16:19]
	v_mfma_f32_16x16x32_bf16 v[4:7], v[162:165], v[214:217], v[4:7]
	v_mfma_f32_16x16x32_bf16 v[0:3], v[170:173], v[214:217], v[0:3]
	v_mfma_f32_16x16x32_bf16 v[52:55], v[166:169], v[186:189], v[52:55]
	v_mfma_f32_16x16x32_bf16 v[48:51], v[178:181], v[186:189], v[48:51]
	v_mfma_f32_16x16x32_bf16 v[36:39], v[166:169], v[194:197], v[36:39]
	v_mfma_f32_16x16x32_bf16 v[32:35], v[178:181], v[194:197], v[32:35]
	v_mfma_f32_16x16x32_bf16 v[20:23], v[166:169], v[210:213], v[20:23]
	v_mfma_f32_16x16x32_bf16 v[16:19], v[178:181], v[210:213], v[16:19]
	v_mfma_f32_16x16x32_bf16 v[4:7], v[166:169], v[218:221], v[4:7]
	v_mfma_f32_16x16x32_bf16 v[0:3], v[178:181], v[218:221], v[0:3]
	s_setprio 0
	s_barrier
	s_mov_b64 s[64:65], 0
	s_mov_b64 s[60:61], -1
	s_mov_b64 s[62:63], 0x100
	s_cbranch_vccz .LBB0_828
	s_and_b64 vcc, exec, s[18:19]
	s_cbranch_vccz .LBB0_831
	s_barrier

.LBB0_849:
	ds_read_b128 v[138:141], v147
	ds_read_b128 v[152:155], v147 offset:1024
	ds_read_b128 v[156:159], v147 offset:2048
	ds_read_b128 v[160:163], v147 offset:3072
	ds_read_b128 v[164:167], v148
	ds_read_b128 v[168:171], v148 offset:1024
	ds_read_b128 v[172:175], v148 offset:2048
	ds_read_b128 v[178:181], v148 offset:3072
	ds_read_b128 v[182:185], v149
	ds_read_b128 v[186:189], v149 offset:1024
	ds_read_b128 v[190:193], v149 offset:2048
	ds_read_b128 v[194:197], v149 offset:3072
	ds_read_b128 v[206:209], v149 offset:4096
	ds_read_b128 v[210:213], v149 offset:5120
	ds_read_b128 v[214:217], v149 offset:6144
	ds_read_b128 v[218:221], v149 offset:7168
	s_add_u32 s2, s30, s52
	s_addc_u32 s3, s31, s53
	s_add_u32 s9, s2, 0x100
	s_addc_u32 s38, s3, 0
	s_and_b64 s[0:1], s[34:35], exec
	v_cndmask_b32_e64 v137, 0, 1, s[54:55]
	s_cselect_b32 s55, s27, s38
	s_cselect_b32 s54, s89, s9
	s_add_u32 s0, s28, s52
	s_addc_u32 s1, s29, s53
	s_add_u32 s9, s0, 0x100
	s_addc_u32 s38, s1, 0
	s_and_b64 s[0:1], s[34:35], exec
	s_cselect_b32 s57, s90, s38
	s_cselect_b32 s56, s8, s9
	s_add_u32 s60, s2, 0x80080
	s_addc_u32 s61, s3, 0
	s_add_i32 s39, s79, s36
	s_add_i32 m0, s63, 0xc000
	s_add_i32 s74, s63, 0xe000
	s_add_i32 s50, s39, 0x2000
	s_add_u32 s58, s56, 0x80000
	s_addc_u32 s59, s57, 0
	s_add_i32 s38, s80, s36
	s_add_i32 s51, s38, 0x2000
	s_add_i32 s76, 0, 0x18000
	s_add_i32 s0, 0, 0x1c000
	s_add_u32 s52, s54, 0x80000
	s_addc_u32 s53, s55, 0
	s_add_i32 s3, s76, s36
	s_add_i32 s1, s3, 0x2000
	s_add_u32 s34, s56, 0x80080
	s_addc_u32 s35, s57, 0
	s_add_i32 s2, s0, s36
	s_add_i32 s9, s2, 0x2000
	v_cmp_ne_u32_e32 vcc, 1, v137
	v_lshl_add_u64 v[142:143], s[60:61], 0, v[134:135]
	global_load_lds_dwordx4 v[142:143], off
	s_mov_b32 m0, s74
	v_lshl_add_u64 v[142:143], s[60:61], 0, v[130:131]
	global_load_lds_dwordx4 v[142:143], off
	s_waitcnt vmcnt(8) lgkmcnt(0)
	s_setprio 1
	s_barrier
	v_mfma_f32_16x16x32_bf16 v[124:127], v[138:141], v[182:185], v[124:127]
	v_mfma_f32_16x16x32_bf16 v[120:123], v[156:159], v[182:185], v[120:123]
	v_mfma_f32_16x16x32_bf16 v[108:111], v[138:141], v[190:193], v[108:111]
	v_mfma_f32_16x16x32_bf16 v[104:107], v[156:159], v[190:193], v[104:107]
	v_mfma_f32_16x16x32_bf16 v[92:95], v[138:141], v[206:209], v[92:95]
	v_mfma_f32_16x16x32_bf16 v[88:91], v[156:159], v[206:209], v[88:91]
	v_mfma_f32_16x16x32_bf16 v[76:79], v[138:141], v[214:217], v[76:79]
	v_mfma_f32_16x16x32_bf16 v[72:75], v[156:159], v[214:217], v[72:75]
	v_mfma_f32_16x16x32_bf16 v[124:127], v[152:155], v[186:189], v[124:127]
	v_mfma_f32_16x16x32_bf16 v[120:123], v[160:163], v[186:189], v[120:123]
	v_mfma_f32_16x16x32_bf16 v[108:111], v[152:155], v[194:197], v[108:111]
	v_mfma_f32_16x16x32_bf16 v[104:107], v[160:163], v[194:197], v[104:107]
	v_mfma_f32_16x16x32_bf16 v[92:95], v[152:155], v[210:213], v[92:95]
	v_mfma_f32_16x16x32_bf16 v[88:91], v[160:163], v[210:213], v[88:91]
	v_mfma_f32_16x16x32_bf16 v[76:79], v[152:155], v[218:221], v[76:79]
	v_mfma_f32_16x16x32_bf16 v[72:75], v[160:163], v[218:221], v[72:75]
	v_mfma_f32_16x16x32_bf16 v[116:119], v[164:167], v[182:185], v[116:119]
	v_mfma_f32_16x16x32_bf16 v[112:115], v[172:175], v[182:185], v[112:115]
	v_mfma_f32_16x16x32_bf16 v[100:103], v[164:167], v[190:193], v[100:103]
	v_mfma_f32_16x16x32_bf16 v[96:99], v[172:175], v[190:193], v[96:99]
	v_mfma_f32_16x16x32_bf16 v[84:87], v[164:167], v[206:209], v[84:87]
	v_mfma_f32_16x16x32_bf16 v[80:83], v[172:175], v[206:209], v[80:83]
	v_mfma_f32_16x16x32_bf16 v[68:71], v[164:167], v[214:217], v[68:71]
	v_mfma_f32_16x16x32_bf16 v[64:67], v[172:175], v[214:217], v[64:67]
	v_mfma_f32_16x16x32_bf16 v[116:119], v[168:171], v[186:189], v[116:119]
	v_mfma_f32_16x16x32_bf16 v[112:115], v[178:181], v[186:189], v[112:115]
	v_mfma_f32_16x16x32_bf16 v[100:103], v[168:171], v[194:197], v[100:103]
	v_mfma_f32_16x16x32_bf16 v[96:99], v[178:181], v[194:197], v[96:99]
	v_mfma_f32_16x16x32_bf16 v[84:87], v[168:171], v[210:213], v[84:87]
	v_mfma_f32_16x16x32_bf16 v[80:83], v[178:181], v[210:213], v[80:83]
	v_mfma_f32_16x16x32_bf16 v[68:71], v[168:171], v[218:221], v[68:71]
	v_mfma_f32_16x16x32_bf16 v[64:67], v[178:181], v[218:221], v[64:67]
	s_setprio 0
	s_barrier
	ds_read_b128 v[182:185], v149 offset:16384
	ds_read_b128 v[186:189], v149 offset:17408
	ds_read_b128 v[190:193], v149 offset:18432
	ds_read_b128 v[194:197], v149 offset:19456
	ds_read_b128 v[206:209], v149 offset:20480
	ds_read_b128 v[210:213], v149 offset:21504
	ds_read_b128 v[214:217], v149 offset:22528
	ds_read_b128 v[218:221], v149 offset:23552
	s_mov_b32 m0, s39
	v_lshl_add_u64 v[142:143], s[56:57], 0, v[132:133]
	global_load_lds_dwordx4 v[142:143], off
	v_lshl_add_u64 v[198:199], s[56:57], 0, v[128:129]
	s_mov_b32 m0, s50
	v_lshl_add_u64 v[202:203], s[58:59], 0, v[132:133]
	global_load_lds_dwordx4 v[198:199], off
	s_mov_b32 m0, s38
	v_lshl_add_u64 v[222:223], s[54:55], 0, v[130:131]
	global_load_lds_dwordx4 v[202:203], off
	s_mov_b32 m0, s51
	v_lshl_add_u64 v[202:203], s[58:59], 0, v[128:129]
	global_load_lds_dwordx4 v[202:203], off
	s_mov_b32 m0, s63
	v_lshl_add_u64 v[202:203], s[54:55], 0, v[134:135]
	global_load_lds_dwordx4 v[202:203], off
	s_mov_b32 m0, s64
	s_nop 0
	global_load_lds_dwordx4 v[222:223], off
	s_waitcnt vmcnt(8) lgkmcnt(0)
	s_setprio 1
	s_barrier
	v_mfma_f32_16x16x32_bf16 v[60:63], v[138:141], v[182:185], v[60:63]
	v_mfma_f32_16x16x32_bf16 v[56:59], v[156:159], v[182:185], v[56:59]
	v_mfma_f32_16x16x32_bf16 v[44:47], v[138:141], v[190:193], v[44:47]
	v_mfma_f32_16x16x32_bf16 v[40:43], v[156:159], v[190:193], v[40:43]
	v_mfma_f32_16x16x32_bf16 v[28:31], v[138:141], v[206:209], v[28:31]
	v_mfma_f32_16x16x32_bf16 v[24:27], v[156:159], v[206:209], v[24:27]
	v_mfma_f32_16x16x32_bf16 v[12:15], v[138:141], v[214:217], v[12:15]
	v_mfma_f32_16x16x32_bf16 v[8:11], v[156:159], v[214:217], v[8:11]
	v_mfma_f32_16x16x32_bf16 v[60:63], v[152:155], v[186:189], v[60:63]
	v_mfma_f32_16x16x32_bf16 v[56:59], v[160:163], v[186:189], v[56:59]
	v_mfma_f32_16x16x32_bf16 v[44:47], v[152:155], v[194:197], v[44:47]
	v_mfma_f32_16x16x32_bf16 v[40:43], v[160:163], v[194:197], v[40:43]
	v_mfma_f32_16x16x32_bf16 v[28:31], v[152:155], v[210:213], v[28:31]
	v_mfma_f32_16x16x32_bf16 v[24:27], v[160:163], v[210:213], v[24:27]
	v_mfma_f32_16x16x32_bf16 v[12:15], v[152:155], v[218:221], v[12:15]
	v_mfma_f32_16x16x32_bf16 v[8:11], v[160:163], v[218:221], v[8:11]
	v_mfma_f32_16x16x32_bf16 v[52:55], v[164:167], v[182:185], v[52:55]
	v_mfma_f32_16x16x32_bf16 v[48:51], v[172:175], v[182:185], v[48:51]
	v_mfma_f32_16x16x32_bf16 v[36:39], v[164:167], v[190:193], v[36:39]
	v_mfma_f32_16x16x32_bf16 v[32:35], v[172:175], v[190:193], v[32:35]
	v_mfma_f32_16x16x32_bf16 v[20:23], v[164:167], v[206:209], v[20:23]
	v_mfma_f32_16x16x32_bf16 v[16:19], v[172:175], v[206:209], v[16:19]
	v_mfma_f32_16x16x32_bf16 v[4:7], v[164:167], v[214:217], v[4:7]
	v_mfma_f32_16x16x32_bf16 v[0:3], v[172:175], v[214:217], v[0:3]
	v_mfma_f32_16x16x32_bf16 v[52:55], v[168:171], v[186:189], v[52:55]
	v_mfma_f32_16x16x32_bf16 v[48:51], v[178:181], v[186:189], v[48:51]
	v_mfma_f32_16x16x32_bf16 v[36:39], v[168:171], v[194:197], v[36:39]
	v_mfma_f32_16x16x32_bf16 v[32:35], v[178:181], v[194:197], v[32:35]
	v_mfma_f32_16x16x32_bf16 v[20:23], v[168:171], v[210:213], v[20:23]
	v_mfma_f32_16x16x32_bf16 v[16:19], v[178:181], v[210:213], v[16:19]
	v_mfma_f32_16x16x32_bf16 v[4:7], v[168:171], v[218:221], v[4:7]
	v_mfma_f32_16x16x32_bf16 v[0:3], v[178:181], v[218:221], v[0:3]
	s_setprio 0
	s_barrier
	ds_read_b128 v[182:185], v149 offset:32768
	ds_read_b128 v[186:189], v149 offset:33792
	ds_read_b128 v[190:193], v149 offset:34816
	ds_read_b128 v[194:197], v149 offset:35840
	ds_read_b128 v[206:209], v149 offset:36864
	ds_read_b128 v[210:213], v149 offset:37888
	ds_read_b128 v[214:217], v149 offset:38912
	ds_read_b128 v[218:221], v149 offset:39936
	v_add_u32_e32 v137, s76, v146
	ds_read_b128 v[138:141], v137
	ds_read_b128 v[152:155], v137 offset:1024
	ds_read_b128 v[156:159], v137 offset:2048
	ds_read_b128 v[160:163], v137 offset:3072
	v_add_u32_e32 v137, s0, v146
	ds_read_b128 v[164:167], v137
	ds_read_b128 v[168:171], v137 offset:1024
	ds_read_b128 v[172:175], v137 offset:2048
	ds_read_b128 v[178:181], v137 offset:3072
	s_mov_b32 m0, s65
	v_lshl_add_u64 v[224:225], s[52:53], 0, v[134:135]
	global_load_lds_dwordx4 v[224:225], off
	s_mov_b32 m0, s66
	v_lshl_add_u64 v[224:225], s[52:53], 0, v[130:131]
	global_load_lds_dwordx4 v[224:225], off
	s_waitcnt vmcnt(8) lgkmcnt(0)
	s_setprio 1
	s_barrier
	v_mfma_f32_16x16x32_bf16 v[124:127], v[138:141], v[182:185], v[124:127]
	v_mfma_f32_16x16x32_bf16 v[120:123], v[156:159], v[182:185], v[120:123]
	v_mfma_f32_16x16x32_bf16 v[108:111], v[138:141], v[190:193], v[108:111]
	v_mfma_f32_16x16x32_bf16 v[104:107], v[156:159], v[190:193], v[104:107]
	v_mfma_f32_16x16x32_bf16 v[92:95], v[138:141], v[206:209], v[92:95]
	v_mfma_f32_16x16x32_bf16 v[88:91], v[156:159], v[206:209], v[88:91]
	v_mfma_f32_16x16x32_bf16 v[76:79], v[138:141], v[214:217], v[76:79]
	v_mfma_f32_16x16x32_bf16 v[72:75], v[156:159], v[214:217], v[72:75]
	v_mfma_f32_16x16x32_bf16 v[124:127], v[152:155], v[186:189], v[124:127]
	v_mfma_f32_16x16x32_bf16 v[120:123], v[160:163], v[186:189], v[120:123]
	v_mfma_f32_16x16x32_bf16 v[108:111], v[152:155], v[194:197], v[108:111]
	v_mfma_f32_16x16x32_bf16 v[104:107], v[160:163], v[194:197], v[104:107]
	v_mfma_f32_16x16x32_bf16 v[92:95], v[152:155], v[210:213], v[92:95]
	v_mfma_f32_16x16x32_bf16 v[88:91], v[160:163], v[210:213], v[88:91]
	v_mfma_f32_16x16x32_bf16 v[76:79], v[152:155], v[218:221], v[76:79]
	v_mfma_f32_16x16x32_bf16 v[72:75], v[160:163], v[218:221], v[72:75]
	v_mfma_f32_16x16x32_bf16 v[116:119], v[164:167], v[182:185], v[116:119]
	v_mfma_f32_16x16x32_bf16 v[112:115], v[172:175], v[182:185], v[112:115]
	v_mfma_f32_16x16x32_bf16 v[100:103], v[164:167], v[190:193], v[100:103]
	v_mfma_f32_16x16x32_bf16 v[96:99], v[172:175], v[190:193], v[96:99]
	v_mfma_f32_16x16x32_bf16 v[84:87], v[164:167], v[206:209], v[84:87]
	v_mfma_f32_16x16x32_bf16 v[80:83], v[172:175], v[206:209], v[80:83]
	v_mfma_f32_16x16x32_bf16 v[68:71], v[164:167], v[214:217], v[68:71]
	v_mfma_f32_16x16x32_bf16 v[64:67], v[172:175], v[214:217], v[64:67]
	v_mfma_f32_16x16x32_bf16 v[116:119], v[168:171], v[186:189], v[116:119]
	v_mfma_f32_16x16x32_bf16 v[112:115], v[178:181], v[186:189], v[112:115]
	v_mfma_f32_16x16x32_bf16 v[100:103], v[168:171], v[194:197], v[100:103]
	v_mfma_f32_16x16x32_bf16 v[96:99], v[178:181], v[194:197], v[96:99]
	v_mfma_f32_16x16x32_bf16 v[84:87], v[168:171], v[210:213], v[84:87]
	v_mfma_f32_16x16x32_bf16 v[80:83], v[178:181], v[210:213], v[80:83]
	v_mfma_f32_16x16x32_bf16 v[68:71], v[168:171], v[218:221], v[68:71]
	v_mfma_f32_16x16x32_bf16 v[64:67], v[178:181], v[218:221], v[64:67]
	s_setprio 0
	s_barrier
	ds_read_b128 v[182:185], v149 offset:49152
	ds_read_b128 v[186:189], v149 offset:50176
	ds_read_b128 v[190:193], v149 offset:51200
	ds_read_b128 v[194:197], v149 offset:52224
	ds_read_b128 v[206:209], v149 offset:53248
	ds_read_b128 v[210:213], v149 offset:54272
	ds_read_b128 v[214:217], v149 offset:55296
	ds_read_b128 v[218:221], v149 offset:56320
	s_mov_b32 m0, s3
	v_lshl_add_u64 v[142:143], v[142:143], 0, s[14:15]
	global_load_lds_dwordx4 v[142:143], off
	s_mov_b32 m0, s1
	v_lshl_add_u64 v[142:143], v[198:199], 0, s[14:15]
	global_load_lds_dwordx4 v[142:143], off
	s_mov_b32 m0, s2
	v_lshl_add_u64 v[142:143], s[34:35], 0, v[132:133]
	global_load_lds_dwordx4 v[142:143], off
	s_mov_b32 m0, s9
	v_lshl_add_u64 v[142:143], s[34:35], 0, v[128:129]
	global_load_lds_dwordx4 v[142:143], off
	s_mov_b32 m0, s77
	v_lshl_add_u64 v[142:143], v[202:203], 0, s[14:15]
	global_load_lds_dwordx4 v[142:143], off
	s_mov_b32 m0, s78
	v_lshl_add_u64 v[142:143], v[222:223], 0, s[14:15]
	global_load_lds_dwordx4 v[142:143], off
	s_waitcnt vmcnt(8) lgkmcnt(0)
	s_setprio 1
	s_barrier
	v_mfma_f32_16x16x32_bf16 v[60:63], v[138:141], v[182:185], v[60:63]
	v_mfma_f32_16x16x32_bf16 v[56:59], v[156:159], v[182:185], v[56:59]
	v_mfma_f32_16x16x32_bf16 v[44:47], v[138:141], v[190:193], v[44:47]
	v_mfma_f32_16x16x32_bf16 v[40:43], v[156:159], v[190:193], v[40:43]
	v_mfma_f32_16x16x32_bf16 v[28:31], v[138:141], v[206:209], v[28:31]
	v_mfma_f32_16x16x32_bf16 v[24:27], v[156:159], v[206:209], v[24:27]
	v_mfma_f32_16x16x32_bf16 v[12:15], v[138:141], v[214:217], v[12:15]
	v_mfma_f32_16x16x32_bf16 v[8:11], v[156:159], v[214:217], v[8:11]
	v_mfma_f32_16x16x32_bf16 v[60:63], v[152:155], v[186:189], v[60:63]
	v_mfma_f32_16x16x32_bf16 v[56:59], v[160:163], v[186:189], v[56:59]
	v_mfma_f32_16x16x32_bf16 v[44:47], v[152:155], v[194:197], v[44:47]
	v_mfma_f32_16x16x32_bf16 v[40:43], v[160:163], v[194:197], v[40:43]
	v_mfma_f32_16x16x32_bf16 v[28:31], v[152:155], v[210:213], v[28:31]
	v_mfma_f32_16x16x32_bf16 v[24:27], v[160:163], v[210:213], v[24:27]
	v_mfma_f32_16x16x32_bf16 v[12:15], v[152:155], v[218:221], v[12:15]
	v_mfma_f32_16x16x32_bf16 v[8:11], v[160:163], v[218:221], v[8:11]
	v_mfma_f32_16x16x32_bf16 v[52:55], v[164:167], v[182:185], v[52:55]
	v_mfma_f32_16x16x32_bf16 v[48:51], v[172:175], v[182:185], v[48:51]
	v_mfma_f32_16x16x32_bf16 v[36:39], v[164:167], v[190:193], v[36:39]
	v_mfma_f32_16x16x32_bf16 v[32:35], v[172:175], v[190:193], v[32:35]
	v_mfma_f32_16x16x32_bf16 v[20:23], v[164:167], v[206:209], v[20:23]
	v_mfma_f32_16x16x32_bf16 v[16:19], v[172:175], v[206:209], v[16:19]
	v_mfma_f32_16x16x32_bf16 v[4:7], v[164:167], v[214:217], v[4:7]
	v_mfma_f32_16x16x32_bf16 v[0:3], v[172:175], v[214:217], v[0:3]
	v_mfma_f32_16x16x32_bf16 v[52:55], v[168:171], v[186:189], v[52:55]
	v_mfma_f32_16x16x32_bf16 v[48:51], v[178:181], v[186:189], v[48:51]
	v_mfma_f32_16x16x32_bf16 v[36:39], v[168:171], v[194:197], v[36:39]
	v_mfma_f32_16x16x32_bf16 v[32:35], v[178:181], v[194:197], v[32:35]
	v_mfma_f32_16x16x32_bf16 v[20:23], v[168:171], v[210:213], v[20:23]
	v_mfma_f32_16x16x32_bf16 v[16:19], v[178:181], v[210:213], v[16:19]
	v_mfma_f32_16x16x32_bf16 v[4:7], v[168:171], v[218:221], v[4:7]
	v_mfma_f32_16x16x32_bf16 v[0:3], v[178:181], v[218:221], v[0:3]
	s_setprio 0
	s_barrier
	s_mov_b64 s[54:55], 0
	s_mov_b64 s[34:35], -1
	s_mov_b64 s[52:53], 0x100
	s_cbranch_vccz .LBB0_849
	s_and_b64 vcc, exec, s[16:17]
	s_cbranch_vccz .LBB0_852
	s_barrier

.LBB0_877:
	ds_read_b128 v[142:145], v135 offset:1024
	ds_read_b128 v[146:149], v135 offset:2048
	ds_read_b128 v[150:153], v135 offset:3072
	ds_read_b128 v[154:157], v136
	ds_read_b128 v[158:161], v136 offset:1024
	ds_read_b128 v[162:165], v136 offset:2048
	ds_read_b128 v[166:169], v136 offset:3072
	ds_read_b128 v[170:173], v137
	ds_read_b128 v[178:181], v137 offset:1024
	ds_read_b128 v[182:185], v137 offset:2048
	ds_read_b128 v[186:189], v137 offset:3072
	ds_read_b128 v[190:193], v137 offset:4096
	ds_read_b128 v[194:197], v137 offset:5120
	ds_read_b128 v[206:209], v137 offset:6144
	ds_read_b128 v[210:213], v137 offset:7168
	s_add_u32 s2, s54, s64
	s_addc_u32 s3, s55, s65
	s_add_u32 s8, s2, 0x100
	s_addc_u32 s9, s3, 0
	s_and_b64 s[0:1], s[62:63], exec
	v_cndmask_b32_e64 v138, 0, 1, s[66:67]
	s_cselect_b32 s67, s21, s9
	s_cselect_b32 s66, s23, s8
	s_add_u32 s0, s30, s64
	s_addc_u32 s1, s31, s65
	s_add_u32 s8, s0, 0x100
	s_addc_u32 s9, s1, 0
	s_and_b64 s[0:1], s[62:63], exec
	s_cselect_b32 s69, s95, s9
	s_cselect_b32 s68, s96, s8
	s_add_u32 s72, s2, 0x10080
	v_cmp_ne_u32_e32 vcc, 1, v138
	ds_read_b128 v[138:141], v135
	s_addc_u32 s73, s3, 0
	s_add_i32 s19, s91, s77
	s_add_i32 m0, s80, 0xc000
	s_add_i32 s38, s80, 0xe000
	s_add_i32 s0, s19, 0x2000
	s_add_u32 s70, s68, 0x10000
	s_addc_u32 s71, s69, 0
	s_add_i32 s76, s92, s77
	s_add_i32 s18, s76, 0x2000
	s_add_i32 s3, 0, 0x18000
	s_add_i32 s2, 0, 0x1c000
	s_add_u32 s64, s66, 0x10000
	s_addc_u32 s65, s67, 0
	s_add_i32 s1, s3, s77
	s_add_i32 s9, s1, 0x2000
	s_add_u32 s62, s68, 0x10080
	s_addc_u32 s63, s69, 0
	s_add_i32 s97, s2, s77
	s_add_i32 s8, s97, 0x2000
	v_lshl_add_u64 v[174:175], s[72:73], 0, v[128:129]
	global_load_lds_dwordx4 v[174:175], off
	s_mov_b32 m0, s38
	v_lshl_add_u64 v[174:175], s[72:73], 0, v[130:131]
	global_load_lds_dwordx4 v[174:175], off
	s_waitcnt vmcnt(8) lgkmcnt(0)
	s_setprio 1
	s_barrier
	v_mfma_f32_16x16x32_bf16 v[124:127], v[138:141], v[170:173], v[124:127]
	v_mfma_f32_16x16x32_bf16 v[120:123], v[146:149], v[170:173], v[120:123]
	v_mfma_f32_16x16x32_bf16 v[116:119], v[138:141], v[182:185], v[116:119]
	v_mfma_f32_16x16x32_bf16 v[112:115], v[146:149], v[182:185], v[112:115]
	v_mfma_f32_16x16x32_bf16 v[104:107], v[138:141], v[190:193], v[104:107]
	v_mfma_f32_16x16x32_bf16 v[96:99], v[146:149], v[190:193], v[96:99]
	v_mfma_f32_16x16x32_bf16 v[88:91], v[138:141], v[206:209], v[88:91]
	v_mfma_f32_16x16x32_bf16 v[80:83], v[146:149], v[206:209], v[80:83]
	v_mfma_f32_16x16x32_bf16 v[124:127], v[142:145], v[178:181], v[124:127]
	v_mfma_f32_16x16x32_bf16 v[120:123], v[150:153], v[178:181], v[120:123]
	v_mfma_f32_16x16x32_bf16 v[116:119], v[142:145], v[186:189], v[116:119]
	v_mfma_f32_16x16x32_bf16 v[112:115], v[150:153], v[186:189], v[112:115]
	v_mfma_f32_16x16x32_bf16 v[104:107], v[142:145], v[194:197], v[104:107]
	v_mfma_f32_16x16x32_bf16 v[96:99], v[150:153], v[194:197], v[96:99]
	v_mfma_f32_16x16x32_bf16 v[88:91], v[142:145], v[210:213], v[88:91]
	v_mfma_f32_16x16x32_bf16 v[80:83], v[150:153], v[210:213], v[80:83]
	v_mfma_f32_16x16x32_bf16 v[108:111], v[154:157], v[170:173], v[108:111]
	v_mfma_f32_16x16x32_bf16 v[100:103], v[162:165], v[170:173], v[100:103]
	v_mfma_f32_16x16x32_bf16 v[92:95], v[154:157], v[182:185], v[92:95]
	v_mfma_f32_16x16x32_bf16 v[84:87], v[162:165], v[182:185], v[84:87]
	v_mfma_f32_16x16x32_bf16 v[76:79], v[154:157], v[190:193], v[76:79]
	v_mfma_f32_16x16x32_bf16 v[72:75], v[162:165], v[190:193], v[72:75]
	v_mfma_f32_16x16x32_bf16 v[68:71], v[154:157], v[206:209], v[68:71]
	v_mfma_f32_16x16x32_bf16 v[64:67], v[162:165], v[206:209], v[64:67]
	v_mfma_f32_16x16x32_bf16 v[108:111], v[158:161], v[178:181], v[108:111]
	v_mfma_f32_16x16x32_bf16 v[100:103], v[166:169], v[178:181], v[100:103]
	v_mfma_f32_16x16x32_bf16 v[92:95], v[158:161], v[186:189], v[92:95]
	v_mfma_f32_16x16x32_bf16 v[84:87], v[166:169], v[186:189], v[84:87]
	v_mfma_f32_16x16x32_bf16 v[76:79], v[158:161], v[194:197], v[76:79]
	v_mfma_f32_16x16x32_bf16 v[72:75], v[166:169], v[194:197], v[72:75]
	v_mfma_f32_16x16x32_bf16 v[68:71], v[158:161], v[210:213], v[68:71]
	v_mfma_f32_16x16x32_bf16 v[64:67], v[166:169], v[210:213], v[64:67]
	s_setprio 0
	s_barrier
	ds_read_b128 v[170:173], v137 offset:16384
	ds_read_b128 v[178:181], v137 offset:17408
	ds_read_b128 v[182:185], v137 offset:18432
	ds_read_b128 v[186:189], v137 offset:19456
	ds_read_b128 v[190:193], v137 offset:20480
	ds_read_b128 v[194:197], v137 offset:21504
	ds_read_b128 v[206:209], v137 offset:22528
	ds_read_b128 v[210:213], v137 offset:23552
	s_mov_b32 m0, s19
	v_lshl_add_u64 v[174:175], s[68:69], 0, v[128:129]
	global_load_lds_dwordx4 v[174:175], off
	v_lshl_add_u64 v[198:199], s[68:69], 0, v[130:131]
	s_mov_b32 m0, s0
	v_lshl_add_u64 v[202:203], s[70:71], 0, v[128:129]
	global_load_lds_dwordx4 v[198:199], off
	s_mov_b32 m0, s76
	v_lshl_add_u64 v[214:215], s[66:67], 0, v[130:131]
	global_load_lds_dwordx4 v[202:203], off
	s_mov_b32 m0, s18
	v_lshl_add_u64 v[202:203], s[70:71], 0, v[130:131]
	global_load_lds_dwordx4 v[202:203], off
	s_mov_b32 m0, s80
	v_lshl_add_u64 v[202:203], s[66:67], 0, v[128:129]
	global_load_lds_dwordx4 v[202:203], off
	s_mov_b32 m0, s81
	s_nop 0
	global_load_lds_dwordx4 v[214:215], off
	s_waitcnt vmcnt(8) lgkmcnt(0)
	s_setprio 1
	s_barrier
	v_mfma_f32_16x16x32_bf16 v[60:63], v[138:141], v[170:173], v[60:63]
	v_mfma_f32_16x16x32_bf16 v[56:59], v[146:149], v[170:173], v[56:59]
	v_mfma_f32_16x16x32_bf16 v[52:55], v[138:141], v[182:185], v[52:55]
	v_mfma_f32_16x16x32_bf16 v[48:51], v[146:149], v[182:185], v[48:51]
	v_mfma_f32_16x16x32_bf16 v[40:43], v[138:141], v[190:193], v[40:43]
	v_mfma_f32_16x16x32_bf16 v[32:35], v[146:149], v[190:193], v[32:35]
	v_mfma_f32_16x16x32_bf16 v[24:27], v[138:141], v[206:209], v[24:27]
	v_mfma_f32_16x16x32_bf16 v[16:19], v[146:149], v[206:209], v[16:19]
	v_mfma_f32_16x16x32_bf16 v[60:63], v[142:145], v[178:181], v[60:63]
	v_mfma_f32_16x16x32_bf16 v[56:59], v[150:153], v[178:181], v[56:59]
	v_mfma_f32_16x16x32_bf16 v[52:55], v[142:145], v[186:189], v[52:55]
	v_mfma_f32_16x16x32_bf16 v[48:51], v[150:153], v[186:189], v[48:51]
	v_mfma_f32_16x16x32_bf16 v[40:43], v[142:145], v[194:197], v[40:43]
	v_mfma_f32_16x16x32_bf16 v[32:35], v[150:153], v[194:197], v[32:35]
	v_mfma_f32_16x16x32_bf16 v[24:27], v[142:145], v[210:213], v[24:27]
	v_mfma_f32_16x16x32_bf16 v[16:19], v[150:153], v[210:213], v[16:19]
	v_mfma_f32_16x16x32_bf16 v[44:47], v[154:157], v[170:173], v[44:47]
	v_mfma_f32_16x16x32_bf16 v[36:39], v[162:165], v[170:173], v[36:39]
	v_mfma_f32_16x16x32_bf16 v[28:31], v[154:157], v[182:185], v[28:31]
	v_mfma_f32_16x16x32_bf16 v[20:23], v[162:165], v[182:185], v[20:23]
	v_mfma_f32_16x16x32_bf16 v[12:15], v[154:157], v[190:193], v[12:15]
	v_mfma_f32_16x16x32_bf16 v[8:11], v[162:165], v[190:193], v[8:11]
	v_mfma_f32_16x16x32_bf16 v[4:7], v[154:157], v[206:209], v[4:7]
	v_mfma_f32_16x16x32_bf16 v[0:3], v[162:165], v[206:209], v[0:3]
	v_mfma_f32_16x16x32_bf16 v[44:47], v[158:161], v[178:181], v[44:47]
	v_mfma_f32_16x16x32_bf16 v[36:39], v[166:169], v[178:181], v[36:39]
	v_mfma_f32_16x16x32_bf16 v[28:31], v[158:161], v[186:189], v[28:31]
	v_mfma_f32_16x16x32_bf16 v[20:23], v[166:169], v[186:189], v[20:23]
	v_mfma_f32_16x16x32_bf16 v[12:15], v[158:161], v[194:197], v[12:15]
	v_mfma_f32_16x16x32_bf16 v[8:11], v[166:169], v[194:197], v[8:11]
	v_mfma_f32_16x16x32_bf16 v[4:7], v[158:161], v[210:213], v[4:7]
	v_mfma_f32_16x16x32_bf16 v[0:3], v[166:169], v[210:213], v[0:3]
	s_setprio 0
	s_barrier
	ds_read_b128 v[170:173], v137 offset:32768
	ds_read_b128 v[178:181], v137 offset:33792
	ds_read_b128 v[182:185], v137 offset:34816
	ds_read_b128 v[186:189], v137 offset:35840
	ds_read_b128 v[190:193], v137 offset:36864
	ds_read_b128 v[194:197], v137 offset:37888
	ds_read_b128 v[206:209], v137 offset:38912
	ds_read_b128 v[210:213], v137 offset:39936
	v_add_u32_e32 v150, s3, v134
	v_add_u32_e32 v166, s2, v134
	ds_read_b128 v[138:141], v150
	ds_read_b128 v[142:145], v150 offset:1024
	ds_read_b128 v[146:149], v150 offset:2048
	ds_read_b128 v[150:153], v150 offset:3072
	ds_read_b128 v[154:157], v166
	ds_read_b128 v[158:161], v166 offset:1024
	ds_read_b128 v[162:165], v166 offset:2048
	ds_read_b128 v[166:169], v166 offset:3072
	s_mov_b32 m0, s82
	v_lshl_add_u64 v[216:217], s[64:65], 0, v[128:129]
	global_load_lds_dwordx4 v[216:217], off
	s_mov_b32 m0, s83
	v_lshl_add_u64 v[216:217], s[64:65], 0, v[130:131]
	global_load_lds_dwordx4 v[216:217], off
	s_waitcnt vmcnt(8) lgkmcnt(0)
	s_setprio 1
	s_barrier
	v_mfma_f32_16x16x32_bf16 v[124:127], v[138:141], v[170:173], v[124:127]
	v_mfma_f32_16x16x32_bf16 v[120:123], v[146:149], v[170:173], v[120:123]
	v_mfma_f32_16x16x32_bf16 v[116:119], v[138:141], v[182:185], v[116:119]
	v_mfma_f32_16x16x32_bf16 v[112:115], v[146:149], v[182:185], v[112:115]
	v_mfma_f32_16x16x32_bf16 v[104:107], v[138:141], v[190:193], v[104:107]
	v_mfma_f32_16x16x32_bf16 v[96:99], v[146:149], v[190:193], v[96:99]
	v_mfma_f32_16x16x32_bf16 v[88:91], v[138:141], v[206:209], v[88:91]
	v_mfma_f32_16x16x32_bf16 v[80:83], v[146:149], v[206:209], v[80:83]
	v_mfma_f32_16x16x32_bf16 v[124:127], v[142:145], v[178:181], v[124:127]
	v_mfma_f32_16x16x32_bf16 v[120:123], v[150:153], v[178:181], v[120:123]
	v_mfma_f32_16x16x32_bf16 v[116:119], v[142:145], v[186:189], v[116:119]
	v_mfma_f32_16x16x32_bf16 v[112:115], v[150:153], v[186:189], v[112:115]
	v_mfma_f32_16x16x32_bf16 v[104:107], v[142:145], v[194:197], v[104:107]
	v_mfma_f32_16x16x32_bf16 v[96:99], v[150:153], v[194:197], v[96:99]
	v_mfma_f32_16x16x32_bf16 v[88:91], v[142:145], v[210:213], v[88:91]
	v_mfma_f32_16x16x32_bf16 v[80:83], v[150:153], v[210:213], v[80:83]
	v_mfma_f32_16x16x32_bf16 v[108:111], v[154:157], v[170:173], v[108:111]
	v_mfma_f32_16x16x32_bf16 v[100:103], v[162:165], v[170:173], v[100:103]
	v_mfma_f32_16x16x32_bf16 v[92:95], v[154:157], v[182:185], v[92:95]
	v_mfma_f32_16x16x32_bf16 v[84:87], v[162:165], v[182:185], v[84:87]
	v_mfma_f32_16x16x32_bf16 v[76:79], v[154:157], v[190:193], v[76:79]
	v_mfma_f32_16x16x32_bf16 v[72:75], v[162:165], v[190:193], v[72:75]
	v_mfma_f32_16x16x32_bf16 v[68:71], v[154:157], v[206:209], v[68:71]
	v_mfma_f32_16x16x32_bf16 v[64:67], v[162:165], v[206:209], v[64:67]
	v_mfma_f32_16x16x32_bf16 v[108:111], v[158:161], v[178:181], v[108:111]
	v_mfma_f32_16x16x32_bf16 v[100:103], v[166:169], v[178:181], v[100:103]
	v_mfma_f32_16x16x32_bf16 v[92:95], v[158:161], v[186:189], v[92:95]
	v_mfma_f32_16x16x32_bf16 v[84:87], v[166:169], v[186:189], v[84:87]
	v_mfma_f32_16x16x32_bf16 v[76:79], v[158:161], v[194:197], v[76:79]
	v_mfma_f32_16x16x32_bf16 v[72:75], v[166:169], v[194:197], v[72:75]
	v_mfma_f32_16x16x32_bf16 v[68:71], v[158:161], v[210:213], v[68:71]
	v_mfma_f32_16x16x32_bf16 v[64:67], v[166:169], v[210:213], v[64:67]
	s_setprio 0
	s_barrier
	ds_read_b128 v[170:173], v137 offset:49152
	ds_read_b128 v[178:181], v137 offset:50176
	ds_read_b128 v[182:185], v137 offset:51200
	ds_read_b128 v[186:189], v137 offset:52224
	ds_read_b128 v[190:193], v137 offset:53248
	ds_read_b128 v[194:197], v137 offset:54272
	ds_read_b128 v[206:209], v137 offset:55296
	ds_read_b128 v[210:213], v137 offset:56320
	s_mov_b32 m0, s1
	v_lshl_add_u64 v[174:175], v[174:175], 0, s[26:27]
	global_load_lds_dwordx4 v[174:175], off
	s_mov_b32 m0, s9
	v_lshl_add_u64 v[174:175], v[198:199], 0, s[26:27]
	global_load_lds_dwordx4 v[174:175], off
	s_mov_b32 m0, s97
	v_lshl_add_u64 v[174:175], s[62:63], 0, v[128:129]
	global_load_lds_dwordx4 v[174:175], off
	s_mov_b32 m0, s8
	v_lshl_add_u64 v[174:175], s[62:63], 0, v[130:131]
	global_load_lds_dwordx4 v[174:175], off
	s_mov_b32 m0, s89
	v_lshl_add_u64 v[174:175], v[202:203], 0, s[26:27]
	global_load_lds_dwordx4 v[174:175], off
	s_mov_b32 m0, s90
	v_lshl_add_u64 v[174:175], v[214:215], 0, s[26:27]
	global_load_lds_dwordx4 v[174:175], off
	s_waitcnt vmcnt(8) lgkmcnt(0)
	s_setprio 1
	s_barrier
	v_mfma_f32_16x16x32_bf16 v[60:63], v[138:141], v[170:173], v[60:63]
	v_mfma_f32_16x16x32_bf16 v[56:59], v[146:149], v[170:173], v[56:59]
	v_mfma_f32_16x16x32_bf16 v[52:55], v[138:141], v[182:185], v[52:55]
	v_mfma_f32_16x16x32_bf16 v[48:51], v[146:149], v[182:185], v[48:51]
	v_mfma_f32_16x16x32_bf16 v[40:43], v[138:141], v[190:193], v[40:43]
	v_mfma_f32_16x16x32_bf16 v[32:35], v[146:149], v[190:193], v[32:35]
	v_mfma_f32_16x16x32_bf16 v[24:27], v[138:141], v[206:209], v[24:27]
	v_mfma_f32_16x16x32_bf16 v[16:19], v[146:149], v[206:209], v[16:19]
	v_mfma_f32_16x16x32_bf16 v[60:63], v[142:145], v[178:181], v[60:63]
	v_mfma_f32_16x16x32_bf16 v[56:59], v[150:153], v[178:181], v[56:59]
	v_mfma_f32_16x16x32_bf16 v[52:55], v[142:145], v[186:189], v[52:55]
	v_mfma_f32_16x16x32_bf16 v[48:51], v[150:153], v[186:189], v[48:51]
	v_mfma_f32_16x16x32_bf16 v[40:43], v[142:145], v[194:197], v[40:43]
	v_mfma_f32_16x16x32_bf16 v[32:35], v[150:153], v[194:197], v[32:35]
	v_mfma_f32_16x16x32_bf16 v[24:27], v[142:145], v[210:213], v[24:27]
	v_mfma_f32_16x16x32_bf16 v[16:19], v[150:153], v[210:213], v[16:19]
	v_mfma_f32_16x16x32_bf16 v[44:47], v[154:157], v[170:173], v[44:47]
	v_mfma_f32_16x16x32_bf16 v[36:39], v[162:165], v[170:173], v[36:39]
	v_mfma_f32_16x16x32_bf16 v[28:31], v[154:157], v[182:185], v[28:31]
	v_mfma_f32_16x16x32_bf16 v[20:23], v[162:165], v[182:185], v[20:23]
	v_mfma_f32_16x16x32_bf16 v[12:15], v[154:157], v[190:193], v[12:15]
	v_mfma_f32_16x16x32_bf16 v[8:11], v[162:165], v[190:193], v[8:11]
	v_mfma_f32_16x16x32_bf16 v[4:7], v[154:157], v[206:209], v[4:7]
	v_mfma_f32_16x16x32_bf16 v[0:3], v[162:165], v[206:209], v[0:3]
	v_mfma_f32_16x16x32_bf16 v[44:47], v[158:161], v[178:181], v[44:47]
	v_mfma_f32_16x16x32_bf16 v[36:39], v[166:169], v[178:181], v[36:39]
	v_mfma_f32_16x16x32_bf16 v[28:31], v[158:161], v[186:189], v[28:31]
	v_mfma_f32_16x16x32_bf16 v[20:23], v[166:169], v[186:189], v[20:23]
	v_mfma_f32_16x16x32_bf16 v[12:15], v[158:161], v[194:197], v[12:15]
	v_mfma_f32_16x16x32_bf16 v[8:11], v[166:169], v[194:197], v[8:11]
	v_mfma_f32_16x16x32_bf16 v[4:7], v[158:161], v[210:213], v[4:7]
	v_mfma_f32_16x16x32_bf16 v[0:3], v[166:169], v[210:213], v[0:3]
	s_setprio 0
	s_barrier
	s_mov_b64 s[66:67], 0
	s_mov_b64 s[62:63], -1
	s_mov_b64 s[64:65], 0x100
	s_cbranch_vccz .LBB0_877
	s_and_b64 vcc, exec, s[28:29]
	s_cbranch_vccz .LBB0_880
	s_barrier

.LBB0_904:
	ds_read_b128 v[142:145], v135 offset:1024
	ds_read_b128 v[146:149], v135 offset:2048
	ds_read_b128 v[150:153], v135 offset:3072
	ds_read_b128 v[154:157], v136
	ds_read_b128 v[158:161], v136 offset:1024
	ds_read_b128 v[162:165], v136 offset:2048
	ds_read_b128 v[166:169], v136 offset:3072
	ds_read_b128 v[170:173], v137
	ds_read_b128 v[178:181], v137 offset:1024
	ds_read_b128 v[182:185], v137 offset:2048
	ds_read_b128 v[186:189], v137 offset:3072
	ds_read_b128 v[190:193], v137 offset:4096
	ds_read_b128 v[194:197], v137 offset:5120
	ds_read_b128 v[206:209], v137 offset:6144
	ds_read_b128 v[210:213], v137 offset:7168
	s_add_u32 s2, s28, s56
	s_addc_u32 s3, s29, s57
	s_add_u32 s8, s2, 0x100
	s_addc_u32 s9, s3, 0
	s_and_b64 s[0:1], s[54:55], exec
	v_cndmask_b32_e64 v138, 0, 1, s[58:59]
	s_cselect_b32 s59, s13, s9
	s_cselect_b32 s58, s15, s8
	s_add_u32 s0, s22, s56
	s_addc_u32 s1, s23, s57
	s_add_u32 s8, s0, 0x100
	s_addc_u32 s9, s1, 0
	s_and_b64 s[0:1], s[54:55], exec
	s_cselect_b32 s61, s87, s9
	s_cselect_b32 s60, s88, s8
	s_add_u32 s64, s2, 0x10080
	v_cmp_ne_u32_e32 vcc, 1, v138
	ds_read_b128 v[138:141], v135
	s_addc_u32 s65, s3, 0
	s_add_i32 s38, s83, s66
	s_add_i32 m0, s69, 0xc000
	s_add_i32 s39, s69, 0xe000
	s_add_i32 s0, s38, 0x2000
	s_add_u32 s62, s60, 0x10000
	s_addc_u32 s63, s61, 0
	s_add_i32 s90, s84, s66
	s_add_i32 s76, s90, 0x2000
	s_add_i32 s3, 0, 0x18000
	s_add_i32 s2, 0, 0x1c000
	s_add_u32 s56, s58, 0x10000
	s_addc_u32 s57, s59, 0
	s_add_i32 s1, s3, s66
	s_add_i32 s9, s1, 0x2000
	s_add_u32 s54, s60, 0x10080
	s_addc_u32 s55, s61, 0
	s_add_i32 s89, s2, s66
	s_add_i32 s8, s89, 0x2000
	v_lshl_add_u64 v[174:175], s[64:65], 0, v[128:129]
	global_load_lds_dwordx4 v[174:175], off
	s_mov_b32 m0, s39
	v_lshl_add_u64 v[174:175], s[64:65], 0, v[130:131]
	global_load_lds_dwordx4 v[174:175], off
	s_waitcnt vmcnt(8) lgkmcnt(0)
	s_setprio 1
	s_barrier
	v_mfma_f32_16x16x32_bf16 v[124:127], v[138:141], v[170:173], v[124:127]
	v_mfma_f32_16x16x32_bf16 v[120:123], v[146:149], v[170:173], v[120:123]
	v_mfma_f32_16x16x32_bf16 v[116:119], v[138:141], v[182:185], v[116:119]
	v_mfma_f32_16x16x32_bf16 v[112:115], v[146:149], v[182:185], v[112:115]
	v_mfma_f32_16x16x32_bf16 v[104:107], v[138:141], v[190:193], v[104:107]
	v_mfma_f32_16x16x32_bf16 v[96:99], v[146:149], v[190:193], v[96:99]
	v_mfma_f32_16x16x32_bf16 v[88:91], v[138:141], v[206:209], v[88:91]
	v_mfma_f32_16x16x32_bf16 v[80:83], v[146:149], v[206:209], v[80:83]
	v_mfma_f32_16x16x32_bf16 v[124:127], v[142:145], v[178:181], v[124:127]
	v_mfma_f32_16x16x32_bf16 v[120:123], v[150:153], v[178:181], v[120:123]
	v_mfma_f32_16x16x32_bf16 v[116:119], v[142:145], v[186:189], v[116:119]
	v_mfma_f32_16x16x32_bf16 v[112:115], v[150:153], v[186:189], v[112:115]
	v_mfma_f32_16x16x32_bf16 v[104:107], v[142:145], v[194:197], v[104:107]
	v_mfma_f32_16x16x32_bf16 v[96:99], v[150:153], v[194:197], v[96:99]
	v_mfma_f32_16x16x32_bf16 v[88:91], v[142:145], v[210:213], v[88:91]
	v_mfma_f32_16x16x32_bf16 v[80:83], v[150:153], v[210:213], v[80:83]
	v_mfma_f32_16x16x32_bf16 v[108:111], v[154:157], v[170:173], v[108:111]
	v_mfma_f32_16x16x32_bf16 v[100:103], v[162:165], v[170:173], v[100:103]
	v_mfma_f32_16x16x32_bf16 v[92:95], v[154:157], v[182:185], v[92:95]
	v_mfma_f32_16x16x32_bf16 v[84:87], v[162:165], v[182:185], v[84:87]
	v_mfma_f32_16x16x32_bf16 v[76:79], v[154:157], v[190:193], v[76:79]
	v_mfma_f32_16x16x32_bf16 v[72:75], v[162:165], v[190:193], v[72:75]
	v_mfma_f32_16x16x32_bf16 v[68:71], v[154:157], v[206:209], v[68:71]
	v_mfma_f32_16x16x32_bf16 v[64:67], v[162:165], v[206:209], v[64:67]
	v_mfma_f32_16x16x32_bf16 v[108:111], v[158:161], v[178:181], v[108:111]
	v_mfma_f32_16x16x32_bf16 v[100:103], v[166:169], v[178:181], v[100:103]
	v_mfma_f32_16x16x32_bf16 v[92:95], v[158:161], v[186:189], v[92:95]
	v_mfma_f32_16x16x32_bf16 v[84:87], v[166:169], v[186:189], v[84:87]
	v_mfma_f32_16x16x32_bf16 v[76:79], v[158:161], v[194:197], v[76:79]
	v_mfma_f32_16x16x32_bf16 v[72:75], v[166:169], v[194:197], v[72:75]
	v_mfma_f32_16x16x32_bf16 v[68:71], v[158:161], v[210:213], v[68:71]
	v_mfma_f32_16x16x32_bf16 v[64:67], v[166:169], v[210:213], v[64:67]
	s_setprio 0
	s_barrier
	ds_read_b128 v[170:173], v137 offset:16384
	ds_read_b128 v[178:181], v137 offset:17408
	ds_read_b128 v[182:185], v137 offset:18432
	ds_read_b128 v[186:189], v137 offset:19456
	ds_read_b128 v[190:193], v137 offset:20480
	ds_read_b128 v[194:197], v137 offset:21504
	ds_read_b128 v[206:209], v137 offset:22528
	ds_read_b128 v[210:213], v137 offset:23552
	s_mov_b32 m0, s38
	v_lshl_add_u64 v[174:175], s[60:61], 0, v[128:129]
	global_load_lds_dwordx4 v[174:175], off
	v_lshl_add_u64 v[198:199], s[60:61], 0, v[130:131]
	s_mov_b32 m0, s0
	v_lshl_add_u64 v[202:203], s[62:63], 0, v[128:129]
	global_load_lds_dwordx4 v[198:199], off
	s_mov_b32 m0, s90
	v_lshl_add_u64 v[214:215], s[58:59], 0, v[130:131]
	global_load_lds_dwordx4 v[202:203], off
	s_mov_b32 m0, s76
	v_lshl_add_u64 v[202:203], s[62:63], 0, v[130:131]
	global_load_lds_dwordx4 v[202:203], off
	s_mov_b32 m0, s69
	v_lshl_add_u64 v[202:203], s[58:59], 0, v[128:129]
	global_load_lds_dwordx4 v[202:203], off
	s_mov_b32 m0, s70
	s_nop 0
	global_load_lds_dwordx4 v[214:215], off
	s_waitcnt vmcnt(8) lgkmcnt(0)
	s_setprio 1
	s_barrier
	v_mfma_f32_16x16x32_bf16 v[60:63], v[138:141], v[170:173], v[60:63]
	v_mfma_f32_16x16x32_bf16 v[56:59], v[146:149], v[170:173], v[56:59]
	v_mfma_f32_16x16x32_bf16 v[52:55], v[138:141], v[182:185], v[52:55]
	v_mfma_f32_16x16x32_bf16 v[48:51], v[146:149], v[182:185], v[48:51]
	v_mfma_f32_16x16x32_bf16 v[40:43], v[138:141], v[190:193], v[40:43]
	v_mfma_f32_16x16x32_bf16 v[32:35], v[146:149], v[190:193], v[32:35]
	v_mfma_f32_16x16x32_bf16 v[24:27], v[138:141], v[206:209], v[24:27]
	v_mfma_f32_16x16x32_bf16 v[16:19], v[146:149], v[206:209], v[16:19]
	v_mfma_f32_16x16x32_bf16 v[60:63], v[142:145], v[178:181], v[60:63]
	v_mfma_f32_16x16x32_bf16 v[56:59], v[150:153], v[178:181], v[56:59]
	v_mfma_f32_16x16x32_bf16 v[52:55], v[142:145], v[186:189], v[52:55]
	v_mfma_f32_16x16x32_bf16 v[48:51], v[150:153], v[186:189], v[48:51]
	v_mfma_f32_16x16x32_bf16 v[40:43], v[142:145], v[194:197], v[40:43]
	v_mfma_f32_16x16x32_bf16 v[32:35], v[150:153], v[194:197], v[32:35]
	v_mfma_f32_16x16x32_bf16 v[24:27], v[142:145], v[210:213], v[24:27]
	v_mfma_f32_16x16x32_bf16 v[16:19], v[150:153], v[210:213], v[16:19]
	v_mfma_f32_16x16x32_bf16 v[44:47], v[154:157], v[170:173], v[44:47]
	v_mfma_f32_16x16x32_bf16 v[36:39], v[162:165], v[170:173], v[36:39]
	v_mfma_f32_16x16x32_bf16 v[28:31], v[154:157], v[182:185], v[28:31]
	v_mfma_f32_16x16x32_bf16 v[20:23], v[162:165], v[182:185], v[20:23]
	v_mfma_f32_16x16x32_bf16 v[12:15], v[154:157], v[190:193], v[12:15]
	v_mfma_f32_16x16x32_bf16 v[8:11], v[162:165], v[190:193], v[8:11]
	v_mfma_f32_16x16x32_bf16 v[4:7], v[154:157], v[206:209], v[4:7]
	v_mfma_f32_16x16x32_bf16 v[0:3], v[162:165], v[206:209], v[0:3]
	v_mfma_f32_16x16x32_bf16 v[44:47], v[158:161], v[178:181], v[44:47]
	v_mfma_f32_16x16x32_bf16 v[36:39], v[166:169], v[178:181], v[36:39]
	v_mfma_f32_16x16x32_bf16 v[28:31], v[158:161], v[186:189], v[28:31]
	v_mfma_f32_16x16x32_bf16 v[20:23], v[166:169], v[186:189], v[20:23]
	v_mfma_f32_16x16x32_bf16 v[12:15], v[158:161], v[194:197], v[12:15]
	v_mfma_f32_16x16x32_bf16 v[8:11], v[166:169], v[194:197], v[8:11]
	v_mfma_f32_16x16x32_bf16 v[4:7], v[158:161], v[210:213], v[4:7]
	v_mfma_f32_16x16x32_bf16 v[0:3], v[166:169], v[210:213], v[0:3]
	s_setprio 0
	s_barrier
	ds_read_b128 v[170:173], v137 offset:32768
	ds_read_b128 v[178:181], v137 offset:33792
	ds_read_b128 v[182:185], v137 offset:34816
	ds_read_b128 v[186:189], v137 offset:35840
	ds_read_b128 v[190:193], v137 offset:36864
	ds_read_b128 v[194:197], v137 offset:37888
	ds_read_b128 v[206:209], v137 offset:38912
	ds_read_b128 v[210:213], v137 offset:39936
	v_add_u32_e32 v150, s3, v134
	v_add_u32_e32 v166, s2, v134
	ds_read_b128 v[138:141], v150
	ds_read_b128 v[142:145], v150 offset:1024
	ds_read_b128 v[146:149], v150 offset:2048
	ds_read_b128 v[150:153], v150 offset:3072
	ds_read_b128 v[154:157], v166
	ds_read_b128 v[158:161], v166 offset:1024
	ds_read_b128 v[162:165], v166 offset:2048
	ds_read_b128 v[166:169], v166 offset:3072
	s_mov_b32 m0, s71
	v_lshl_add_u64 v[216:217], s[56:57], 0, v[128:129]
	global_load_lds_dwordx4 v[216:217], off
	s_mov_b32 m0, s72
	v_lshl_add_u64 v[216:217], s[56:57], 0, v[130:131]
	global_load_lds_dwordx4 v[216:217], off
	s_waitcnt vmcnt(8) lgkmcnt(0)
	s_setprio 1
	s_barrier
	v_mfma_f32_16x16x32_bf16 v[124:127], v[138:141], v[170:173], v[124:127]
	v_mfma_f32_16x16x32_bf16 v[120:123], v[146:149], v[170:173], v[120:123]
	v_mfma_f32_16x16x32_bf16 v[116:119], v[138:141], v[182:185], v[116:119]
	v_mfma_f32_16x16x32_bf16 v[112:115], v[146:149], v[182:185], v[112:115]
	v_mfma_f32_16x16x32_bf16 v[104:107], v[138:141], v[190:193], v[104:107]
	v_mfma_f32_16x16x32_bf16 v[96:99], v[146:149], v[190:193], v[96:99]
	v_mfma_f32_16x16x32_bf16 v[88:91], v[138:141], v[206:209], v[88:91]
	v_mfma_f32_16x16x32_bf16 v[80:83], v[146:149], v[206:209], v[80:83]
	v_mfma_f32_16x16x32_bf16 v[124:127], v[142:145], v[178:181], v[124:127]
	v_mfma_f32_16x16x32_bf16 v[120:123], v[150:153], v[178:181], v[120:123]
	v_mfma_f32_16x16x32_bf16 v[116:119], v[142:145], v[186:189], v[116:119]
	v_mfma_f32_16x16x32_bf16 v[112:115], v[150:153], v[186:189], v[112:115]
	v_mfma_f32_16x16x32_bf16 v[104:107], v[142:145], v[194:197], v[104:107]
	v_mfma_f32_16x16x32_bf16 v[96:99], v[150:153], v[194:197], v[96:99]
	v_mfma_f32_16x16x32_bf16 v[88:91], v[142:145], v[210:213], v[88:91]
	v_mfma_f32_16x16x32_bf16 v[80:83], v[150:153], v[210:213], v[80:83]
	v_mfma_f32_16x16x32_bf16 v[108:111], v[154:157], v[170:173], v[108:111]
	v_mfma_f32_16x16x32_bf16 v[100:103], v[162:165], v[170:173], v[100:103]
	v_mfma_f32_16x16x32_bf16 v[92:95], v[154:157], v[182:185], v[92:95]
	v_mfma_f32_16x16x32_bf16 v[84:87], v[162:165], v[182:185], v[84:87]
	v_mfma_f32_16x16x32_bf16 v[76:79], v[154:157], v[190:193], v[76:79]
	v_mfma_f32_16x16x32_bf16 v[72:75], v[162:165], v[190:193], v[72:75]
	v_mfma_f32_16x16x32_bf16 v[68:71], v[154:157], v[206:209], v[68:71]
	v_mfma_f32_16x16x32_bf16 v[64:67], v[162:165], v[206:209], v[64:67]
	v_mfma_f32_16x16x32_bf16 v[108:111], v[158:161], v[178:181], v[108:111]
	v_mfma_f32_16x16x32_bf16 v[100:103], v[166:169], v[178:181], v[100:103]
	v_mfma_f32_16x16x32_bf16 v[92:95], v[158:161], v[186:189], v[92:95]
	v_mfma_f32_16x16x32_bf16 v[84:87], v[166:169], v[186:189], v[84:87]
	v_mfma_f32_16x16x32_bf16 v[76:79], v[158:161], v[194:197], v[76:79]
	v_mfma_f32_16x16x32_bf16 v[72:75], v[166:169], v[194:197], v[72:75]
	v_mfma_f32_16x16x32_bf16 v[68:71], v[158:161], v[210:213], v[68:71]
	v_mfma_f32_16x16x32_bf16 v[64:67], v[166:169], v[210:213], v[64:67]
	s_setprio 0
	s_barrier
	ds_read_b128 v[170:173], v137 offset:49152
	ds_read_b128 v[178:181], v137 offset:50176
	ds_read_b128 v[182:185], v137 offset:51200
	ds_read_b128 v[186:189], v137 offset:52224
	ds_read_b128 v[190:193], v137 offset:53248
	ds_read_b128 v[194:197], v137 offset:54272
	ds_read_b128 v[206:209], v137 offset:55296
	ds_read_b128 v[210:213], v137 offset:56320
	s_mov_b32 m0, s1
	v_lshl_add_u64 v[174:175], v[174:175], 0, s[18:19]
	global_load_lds_dwordx4 v[174:175], off
	s_mov_b32 m0, s9
	v_lshl_add_u64 v[174:175], v[198:199], 0, s[18:19]
	global_load_lds_dwordx4 v[174:175], off
	s_mov_b32 m0, s89
	v_lshl_add_u64 v[174:175], s[54:55], 0, v[128:129]
	global_load_lds_dwordx4 v[174:175], off
	s_mov_b32 m0, s8
	v_lshl_add_u64 v[174:175], s[54:55], 0, v[130:131]
	global_load_lds_dwordx4 v[174:175], off
	s_mov_b32 m0, s81
	v_lshl_add_u64 v[174:175], v[202:203], 0, s[18:19]
	global_load_lds_dwordx4 v[174:175], off
	s_mov_b32 m0, s82
	v_lshl_add_u64 v[174:175], v[214:215], 0, s[18:19]
	global_load_lds_dwordx4 v[174:175], off
	s_waitcnt vmcnt(8) lgkmcnt(0)
	s_setprio 1
	s_barrier
	v_mfma_f32_16x16x32_bf16 v[60:63], v[138:141], v[170:173], v[60:63]
	v_mfma_f32_16x16x32_bf16 v[56:59], v[146:149], v[170:173], v[56:59]
	v_mfma_f32_16x16x32_bf16 v[52:55], v[138:141], v[182:185], v[52:55]
	v_mfma_f32_16x16x32_bf16 v[48:51], v[146:149], v[182:185], v[48:51]
	v_mfma_f32_16x16x32_bf16 v[40:43], v[138:141], v[190:193], v[40:43]
	v_mfma_f32_16x16x32_bf16 v[32:35], v[146:149], v[190:193], v[32:35]
	v_mfma_f32_16x16x32_bf16 v[24:27], v[138:141], v[206:209], v[24:27]
	v_mfma_f32_16x16x32_bf16 v[16:19], v[146:149], v[206:209], v[16:19]
	v_mfma_f32_16x16x32_bf16 v[60:63], v[142:145], v[178:181], v[60:63]
	v_mfma_f32_16x16x32_bf16 v[56:59], v[150:153], v[178:181], v[56:59]
	v_mfma_f32_16x16x32_bf16 v[52:55], v[142:145], v[186:189], v[52:55]
	v_mfma_f32_16x16x32_bf16 v[48:51], v[150:153], v[186:189], v[48:51]
	v_mfma_f32_16x16x32_bf16 v[40:43], v[142:145], v[194:197], v[40:43]
	v_mfma_f32_16x16x32_bf16 v[32:35], v[150:153], v[194:197], v[32:35]
	v_mfma_f32_16x16x32_bf16 v[24:27], v[142:145], v[210:213], v[24:27]
	v_mfma_f32_16x16x32_bf16 v[16:19], v[150:153], v[210:213], v[16:19]
	v_mfma_f32_16x16x32_bf16 v[44:47], v[154:157], v[170:173], v[44:47]
	v_mfma_f32_16x16x32_bf16 v[36:39], v[162:165], v[170:173], v[36:39]
	v_mfma_f32_16x16x32_bf16 v[28:31], v[154:157], v[182:185], v[28:31]
	v_mfma_f32_16x16x32_bf16 v[20:23], v[162:165], v[182:185], v[20:23]
	v_mfma_f32_16x16x32_bf16 v[12:15], v[154:157], v[190:193], v[12:15]
	v_mfma_f32_16x16x32_bf16 v[8:11], v[162:165], v[190:193], v[8:11]
	v_mfma_f32_16x16x32_bf16 v[4:7], v[154:157], v[206:209], v[4:7]
	v_mfma_f32_16x16x32_bf16 v[0:3], v[162:165], v[206:209], v[0:3]
	v_mfma_f32_16x16x32_bf16 v[44:47], v[158:161], v[178:181], v[44:47]
	v_mfma_f32_16x16x32_bf16 v[36:39], v[166:169], v[178:181], v[36:39]
	v_mfma_f32_16x16x32_bf16 v[28:31], v[158:161], v[186:189], v[28:31]
	v_mfma_f32_16x16x32_bf16 v[20:23], v[166:169], v[186:189], v[20:23]
	v_mfma_f32_16x16x32_bf16 v[12:15], v[158:161], v[194:197], v[12:15]
	v_mfma_f32_16x16x32_bf16 v[8:11], v[166:169], v[194:197], v[8:11]
	v_mfma_f32_16x16x32_bf16 v[4:7], v[158:161], v[210:213], v[4:7]
	v_mfma_f32_16x16x32_bf16 v[0:3], v[166:169], v[210:213], v[0:3]
	s_setprio 0
	s_barrier
	s_mov_b64 s[58:59], 0
	s_mov_b64 s[54:55], -1
	s_mov_b64 s[56:57], 0x100
	s_cbranch_vccz .LBB0_904
	s_and_b64 vcc, exec, s[20:21]
	s_cbranch_vccz .LBB0_907
	s_barrier

.LBB0_953:
	ds_read_b128 v[148:151], v145
	ds_read_b128 v[152:155], v145 offset:1024
	ds_read_b128 v[156:159], v145 offset:2048
	ds_read_b128 v[160:163], v145 offset:3072
	ds_read_b128 v[164:167], v146
	ds_read_b128 v[168:171], v146 offset:1024
	ds_read_b128 v[172:175], v146 offset:2048
	ds_read_b128 v[178:181], v146 offset:3072
	ds_read_b128 v[182:185], v147
	ds_read_b128 v[186:189], v147 offset:1024
	ds_read_b128 v[190:193], v147 offset:2048
	ds_read_b128 v[194:197], v147 offset:3072
	ds_read_b128 v[206:209], v147 offset:4096
	ds_read_b128 v[210:213], v147 offset:5120
	ds_read_b128 v[214:217], v147 offset:6144
	ds_read_b128 v[218:221], v147 offset:7168
	s_add_u32 s56, s54, 0x100
	s_addc_u32 s57, s55, 0
	s_cmp_eq_u32 vcc_hi, 20
	s_cselect_b32 s61, s93, s57
	s_cselect_b32 s60, s94, s56
	s_cselect_b32 s59, s95, vcc_lo
	s_cselect_b32 s58, s96, s97
	s_add_i32 m0, s67, 0xc000
	v_lshl_add_u64 v[140:141], s[54:55], 0, v[136:137]
	global_load_lds_dwordx4 v[140:141], off
	s_add_i32 m0, s67, 0xe000
	v_lshl_add_u64 v[140:141], s[54:55], 0, v[138:139]
	global_load_lds_dwordx4 v[140:141], off
	s_waitcnt vmcnt(8) lgkmcnt(0)
	s_setprio 1
	s_barrier
	v_mfma_f32_16x16x32_bf16 v[124:127], v[148:151], v[182:185], v[124:127]
	v_mfma_f32_16x16x32_bf16 v[120:123], v[156:159], v[182:185], v[120:123]
	v_mfma_f32_16x16x32_bf16 v[116:119], v[148:151], v[190:193], v[116:119]
	v_mfma_f32_16x16x32_bf16 v[108:111], v[156:159], v[190:193], v[108:111]
	v_mfma_f32_16x16x32_bf16 v[100:103], v[148:151], v[206:209], v[100:103]
	v_mfma_f32_16x16x32_bf16 v[92:95], v[156:159], v[206:209], v[92:95]
	v_mfma_f32_16x16x32_bf16 v[84:87], v[148:151], v[214:217], v[84:87]
	v_mfma_f32_16x16x32_bf16 v[76:79], v[156:159], v[214:217], v[76:79]
	v_mfma_f32_16x16x32_bf16 v[124:127], v[152:155], v[186:189], v[124:127]
	v_mfma_f32_16x16x32_bf16 v[120:123], v[160:163], v[186:189], v[120:123]
	v_mfma_f32_16x16x32_bf16 v[116:119], v[152:155], v[194:197], v[116:119]
	v_mfma_f32_16x16x32_bf16 v[108:111], v[160:163], v[194:197], v[108:111]
	v_mfma_f32_16x16x32_bf16 v[100:103], v[152:155], v[210:213], v[100:103]
	v_mfma_f32_16x16x32_bf16 v[92:95], v[160:163], v[210:213], v[92:95]
	v_mfma_f32_16x16x32_bf16 v[84:87], v[152:155], v[218:221], v[84:87]
	v_mfma_f32_16x16x32_bf16 v[76:79], v[160:163], v[218:221], v[76:79]
	v_mfma_f32_16x16x32_bf16 v[112:115], v[164:167], v[182:185], v[112:115]
	v_mfma_f32_16x16x32_bf16 v[104:107], v[172:175], v[182:185], v[104:107]
	v_mfma_f32_16x16x32_bf16 v[96:99], v[164:167], v[190:193], v[96:99]
	v_mfma_f32_16x16x32_bf16 v[88:91], v[172:175], v[190:193], v[88:91]
	v_mfma_f32_16x16x32_bf16 v[80:83], v[164:167], v[206:209], v[80:83]
	v_mfma_f32_16x16x32_bf16 v[72:75], v[172:175], v[206:209], v[72:75]
	v_mfma_f32_16x16x32_bf16 v[68:71], v[164:167], v[214:217], v[68:71]
	v_mfma_f32_16x16x32_bf16 v[64:67], v[172:175], v[214:217], v[64:67]
	v_mfma_f32_16x16x32_bf16 v[112:115], v[168:171], v[186:189], v[112:115]
	v_mfma_f32_16x16x32_bf16 v[104:107], v[178:181], v[186:189], v[104:107]
	v_mfma_f32_16x16x32_bf16 v[96:99], v[168:171], v[194:197], v[96:99]
	v_mfma_f32_16x16x32_bf16 v[88:91], v[178:181], v[194:197], v[88:91]
	v_mfma_f32_16x16x32_bf16 v[80:83], v[168:171], v[210:213], v[80:83]
	v_mfma_f32_16x16x32_bf16 v[72:75], v[178:181], v[210:213], v[72:75]
	v_mfma_f32_16x16x32_bf16 v[68:71], v[168:171], v[218:221], v[68:71]
	v_mfma_f32_16x16x32_bf16 v[64:67], v[178:181], v[218:221], v[64:67]
	s_setprio 0
	s_barrier
	ds_read_b128 v[182:185], v147 offset:16384
	ds_read_b128 v[186:189], v147 offset:17408
	ds_read_b128 v[190:193], v147 offset:18432
	ds_read_b128 v[194:197], v147 offset:19456
	ds_read_b128 v[206:209], v147 offset:20480
	ds_read_b128 v[210:213], v147 offset:21504
	ds_read_b128 v[214:217], v147 offset:22528
	ds_read_b128 v[218:221], v147 offset:23552
	s_add_i32 s0, s79, s66
	s_mov_b32 m0, s0
	v_lshl_add_u64 v[140:141], s[58:59], 0, v[130:131]
	global_load_lds_dwordx4 v[140:141], off
	s_add_i32 m0, s0, 0x2000
	s_add_u32 s0, s58, 0x60000
	v_lshl_add_u64 v[198:199], s[58:59], 0, v[134:135]
	s_addc_u32 s1, s59, 0
	s_add_i32 s2, s80, s66
	global_load_lds_dwordx4 v[198:199], off
	v_lshl_add_u64 v[202:203], s[0:1], 0, v[130:131]
	s_mov_b32 m0, s2
	v_lshl_add_u64 v[222:223], s[60:61], 0, v[132:133]
	global_load_lds_dwordx4 v[202:203], off
	s_add_i32 m0, s2, 0x2000
	v_lshl_add_u64 v[202:203], s[0:1], 0, v[134:135]
	global_load_lds_dwordx4 v[202:203], off
	s_mov_b32 m0, s67
	v_lshl_add_u64 v[202:203], s[60:61], 0, v[128:129]
	global_load_lds_dwordx4 v[202:203], off
	s_mov_b32 m0, s68
	s_nop 0
	global_load_lds_dwordx4 v[222:223], off
	s_waitcnt vmcnt(8) lgkmcnt(0)
	s_setprio 1
	s_barrier
	v_mfma_f32_16x16x32_bf16 v[60:63], v[148:151], v[182:185], v[60:63]
	v_mfma_f32_16x16x32_bf16 v[56:59], v[156:159], v[182:185], v[56:59]
	v_mfma_f32_16x16x32_bf16 v[52:55], v[148:151], v[190:193], v[52:55]
	v_mfma_f32_16x16x32_bf16 v[44:47], v[156:159], v[190:193], v[44:47]
	v_mfma_f32_16x16x32_bf16 v[36:39], v[148:151], v[206:209], v[36:39]
	v_mfma_f32_16x16x32_bf16 v[28:31], v[156:159], v[206:209], v[28:31]
	v_mfma_f32_16x16x32_bf16 v[20:23], v[148:151], v[214:217], v[20:23]
	v_mfma_f32_16x16x32_bf16 v[12:15], v[156:159], v[214:217], v[12:15]
	v_mfma_f32_16x16x32_bf16 v[60:63], v[152:155], v[186:189], v[60:63]
	v_mfma_f32_16x16x32_bf16 v[56:59], v[160:163], v[186:189], v[56:59]
	v_mfma_f32_16x16x32_bf16 v[52:55], v[152:155], v[194:197], v[52:55]
	v_mfma_f32_16x16x32_bf16 v[44:47], v[160:163], v[194:197], v[44:47]
	v_mfma_f32_16x16x32_bf16 v[36:39], v[152:155], v[210:213], v[36:39]
	v_mfma_f32_16x16x32_bf16 v[28:31], v[160:163], v[210:213], v[28:31]
	v_mfma_f32_16x16x32_bf16 v[20:23], v[152:155], v[218:221], v[20:23]
	v_mfma_f32_16x16x32_bf16 v[12:15], v[160:163], v[218:221], v[12:15]
	v_mfma_f32_16x16x32_bf16 v[48:51], v[164:167], v[182:185], v[48:51]
	v_mfma_f32_16x16x32_bf16 v[40:43], v[172:175], v[182:185], v[40:43]
	v_mfma_f32_16x16x32_bf16 v[32:35], v[164:167], v[190:193], v[32:35]
	v_mfma_f32_16x16x32_bf16 v[24:27], v[172:175], v[190:193], v[24:27]
	v_mfma_f32_16x16x32_bf16 v[16:19], v[164:167], v[206:209], v[16:19]
	v_mfma_f32_16x16x32_bf16 v[8:11], v[172:175], v[206:209], v[8:11]
	v_mfma_f32_16x16x32_bf16 v[4:7], v[164:167], v[214:217], v[4:7]
	v_mfma_f32_16x16x32_bf16 v[0:3], v[172:175], v[214:217], v[0:3]
	v_mfma_f32_16x16x32_bf16 v[48:51], v[168:171], v[186:189], v[48:51]
	v_mfma_f32_16x16x32_bf16 v[40:43], v[178:181], v[186:189], v[40:43]
	v_mfma_f32_16x16x32_bf16 v[32:35], v[168:171], v[194:197], v[32:35]
	v_mfma_f32_16x16x32_bf16 v[24:27], v[178:181], v[194:197], v[24:27]
	v_mfma_f32_16x16x32_bf16 v[16:19], v[168:171], v[210:213], v[16:19]
	v_mfma_f32_16x16x32_bf16 v[8:11], v[178:181], v[210:213], v[8:11]
	v_mfma_f32_16x16x32_bf16 v[4:7], v[168:171], v[218:221], v[4:7]
	v_mfma_f32_16x16x32_bf16 v[0:3], v[178:181], v[218:221], v[0:3]
	s_setprio 0
	s_barrier
	ds_read_b128 v[182:185], v147 offset:32768
	ds_read_b128 v[186:189], v147 offset:33792
	ds_read_b128 v[190:193], v147 offset:34816
	ds_read_b128 v[194:197], v147 offset:35840
	ds_read_b128 v[206:209], v147 offset:36864
	ds_read_b128 v[210:213], v147 offset:37888
	ds_read_b128 v[214:217], v147 offset:38912
	ds_read_b128 v[218:221], v147 offset:39936
	s_add_i32 s2, 0, 0x18000
	s_add_i32 s3, 0, 0x1c000
	v_add_u32_e32 v160, s2, v144
	v_add_u32_e32 v177, s3, v144
	ds_read_b128 v[148:151], v160
	ds_read_b128 v[152:155], v160 offset:1024
	ds_read_b128 v[156:159], v160 offset:2048
	ds_read_b128 v[160:163], v160 offset:3072
	ds_read_b128 v[164:167], v177
	ds_read_b128 v[168:171], v177 offset:1024
	ds_read_b128 v[172:175], v177 offset:2048
	ds_read_b128 v[178:181], v177 offset:3072
	s_add_u32 s0, s60, 0x60000
	s_addc_u32 s1, s61, 0
	s_mov_b32 m0, s69
	v_lshl_add_u64 v[224:225], s[0:1], 0, v[128:129]
	global_load_lds_dwordx4 v[224:225], off
	s_mov_b32 m0, s70
	v_lshl_add_u64 v[224:225], s[0:1], 0, v[132:133]
	global_load_lds_dwordx4 v[224:225], off
	s_waitcnt vmcnt(8) lgkmcnt(0)
	s_setprio 1
	s_barrier
	v_mfma_f32_16x16x32_bf16 v[124:127], v[148:151], v[182:185], v[124:127]
	v_mfma_f32_16x16x32_bf16 v[120:123], v[156:159], v[182:185], v[120:123]
	v_mfma_f32_16x16x32_bf16 v[116:119], v[148:151], v[190:193], v[116:119]
	v_mfma_f32_16x16x32_bf16 v[108:111], v[156:159], v[190:193], v[108:111]
	v_mfma_f32_16x16x32_bf16 v[100:103], v[148:151], v[206:209], v[100:103]
	v_mfma_f32_16x16x32_bf16 v[92:95], v[156:159], v[206:209], v[92:95]
	v_mfma_f32_16x16x32_bf16 v[84:87], v[148:151], v[214:217], v[84:87]
	v_mfma_f32_16x16x32_bf16 v[76:79], v[156:159], v[214:217], v[76:79]
	v_mfma_f32_16x16x32_bf16 v[124:127], v[152:155], v[186:189], v[124:127]
	v_mfma_f32_16x16x32_bf16 v[120:123], v[160:163], v[186:189], v[120:123]
	v_mfma_f32_16x16x32_bf16 v[116:119], v[152:155], v[194:197], v[116:119]
	v_mfma_f32_16x16x32_bf16 v[108:111], v[160:163], v[194:197], v[108:111]
	v_mfma_f32_16x16x32_bf16 v[100:103], v[152:155], v[210:213], v[100:103]
	v_mfma_f32_16x16x32_bf16 v[92:95], v[160:163], v[210:213], v[92:95]
	v_mfma_f32_16x16x32_bf16 v[84:87], v[152:155], v[218:221], v[84:87]
	v_mfma_f32_16x16x32_bf16 v[76:79], v[160:163], v[218:221], v[76:79]
	v_mfma_f32_16x16x32_bf16 v[112:115], v[164:167], v[182:185], v[112:115]
	v_mfma_f32_16x16x32_bf16 v[104:107], v[172:175], v[182:185], v[104:107]
	v_mfma_f32_16x16x32_bf16 v[96:99], v[164:167], v[190:193], v[96:99]
	v_mfma_f32_16x16x32_bf16 v[88:91], v[172:175], v[190:193], v[88:91]
	v_mfma_f32_16x16x32_bf16 v[80:83], v[164:167], v[206:209], v[80:83]
	v_mfma_f32_16x16x32_bf16 v[72:75], v[172:175], v[206:209], v[72:75]
	v_mfma_f32_16x16x32_bf16 v[68:71], v[164:167], v[214:217], v[68:71]
	v_mfma_f32_16x16x32_bf16 v[64:67], v[172:175], v[214:217], v[64:67]
	v_mfma_f32_16x16x32_bf16 v[112:115], v[168:171], v[186:189], v[112:115]
	v_mfma_f32_16x16x32_bf16 v[104:107], v[178:181], v[186:189], v[104:107]
	v_mfma_f32_16x16x32_bf16 v[96:99], v[168:171], v[194:197], v[96:99]
	v_mfma_f32_16x16x32_bf16 v[88:91], v[178:181], v[194:197], v[88:91]
	v_mfma_f32_16x16x32_bf16 v[80:83], v[168:171], v[210:213], v[80:83]
	v_mfma_f32_16x16x32_bf16 v[72:75], v[178:181], v[210:213], v[72:75]
	v_mfma_f32_16x16x32_bf16 v[68:71], v[168:171], v[218:221], v[68:71]
	v_mfma_f32_16x16x32_bf16 v[64:67], v[178:181], v[218:221], v[64:67]
	s_setprio 0
	s_barrier
	ds_read_b128 v[182:185], v147 offset:49152
	ds_read_b128 v[186:189], v147 offset:50176
	ds_read_b128 v[190:193], v147 offset:51200
	ds_read_b128 v[194:197], v147 offset:52224
	ds_read_b128 v[206:209], v147 offset:53248
	ds_read_b128 v[210:213], v147 offset:54272
	ds_read_b128 v[214:217], v147 offset:55296
	ds_read_b128 v[218:221], v147 offset:56320
	s_add_i32 s0, s2, s66
	s_mov_b32 m0, s0
	v_lshl_add_u64 v[140:141], v[140:141], 0, s[12:13]
	global_load_lds_dwordx4 v[140:141], off
	s_add_i32 m0, s0, 0x2000
	s_add_u32 s0, s58, 0x60080
	v_lshl_add_u64 v[140:141], v[198:199], 0, s[12:13]
	s_addc_u32 s1, s59, 0
	s_add_i32 s2, s3, s66
	global_load_lds_dwordx4 v[140:141], off
	s_mov_b32 m0, s2
	v_lshl_add_u64 v[140:141], s[0:1], 0, v[130:131]
	global_load_lds_dwordx4 v[140:141], off
	s_add_i32 m0, s2, 0x2000
	v_lshl_add_u64 v[140:141], s[0:1], 0, v[134:135]
	global_load_lds_dwordx4 v[140:141], off
	s_mov_b32 m0, s77
	v_lshl_add_u64 v[140:141], v[202:203], 0, s[12:13]
	global_load_lds_dwordx4 v[140:141], off
	s_mov_b32 m0, s78
	v_lshl_add_u64 v[140:141], v[222:223], 0, s[12:13]
	global_load_lds_dwordx4 v[140:141], off
	s_waitcnt vmcnt(8) lgkmcnt(0)
	s_setprio 1
	s_barrier
	v_mfma_f32_16x16x32_bf16 v[60:63], v[148:151], v[182:185], v[60:63]
	v_mfma_f32_16x16x32_bf16 v[56:59], v[156:159], v[182:185], v[56:59]
	v_mfma_f32_16x16x32_bf16 v[52:55], v[148:151], v[190:193], v[52:55]
	v_mfma_f32_16x16x32_bf16 v[44:47], v[156:159], v[190:193], v[44:47]
	v_mfma_f32_16x16x32_bf16 v[36:39], v[148:151], v[206:209], v[36:39]
	v_mfma_f32_16x16x32_bf16 v[28:31], v[156:159], v[206:209], v[28:31]
	v_mfma_f32_16x16x32_bf16 v[20:23], v[148:151], v[214:217], v[20:23]
	v_mfma_f32_16x16x32_bf16 v[12:15], v[156:159], v[214:217], v[12:15]
	v_mfma_f32_16x16x32_bf16 v[60:63], v[152:155], v[186:189], v[60:63]
	v_mfma_f32_16x16x32_bf16 v[56:59], v[160:163], v[186:189], v[56:59]
	v_mfma_f32_16x16x32_bf16 v[52:55], v[152:155], v[194:197], v[52:55]
	v_mfma_f32_16x16x32_bf16 v[44:47], v[160:163], v[194:197], v[44:47]
	v_mfma_f32_16x16x32_bf16 v[36:39], v[152:155], v[210:213], v[36:39]
	v_mfma_f32_16x16x32_bf16 v[28:31], v[160:163], v[210:213], v[28:31]
	v_mfma_f32_16x16x32_bf16 v[20:23], v[152:155], v[218:221], v[20:23]
	v_mfma_f32_16x16x32_bf16 v[12:15], v[160:163], v[218:221], v[12:15]
	v_mfma_f32_16x16x32_bf16 v[48:51], v[164:167], v[182:185], v[48:51]
	v_mfma_f32_16x16x32_bf16 v[40:43], v[172:175], v[182:185], v[40:43]
	v_mfma_f32_16x16x32_bf16 v[32:35], v[164:167], v[190:193], v[32:35]
	v_mfma_f32_16x16x32_bf16 v[24:27], v[172:175], v[190:193], v[24:27]
	v_mfma_f32_16x16x32_bf16 v[16:19], v[164:167], v[206:209], v[16:19]
	v_mfma_f32_16x16x32_bf16 v[8:11], v[172:175], v[206:209], v[8:11]
	v_mfma_f32_16x16x32_bf16 v[4:7], v[164:167], v[214:217], v[4:7]
	v_mfma_f32_16x16x32_bf16 v[0:3], v[172:175], v[214:217], v[0:3]
	v_mfma_f32_16x16x32_bf16 v[48:51], v[168:171], v[186:189], v[48:51]
	v_mfma_f32_16x16x32_bf16 v[40:43], v[178:181], v[186:189], v[40:43]
	v_mfma_f32_16x16x32_bf16 v[32:35], v[168:171], v[194:197], v[32:35]
	v_mfma_f32_16x16x32_bf16 v[24:27], v[178:181], v[194:197], v[24:27]
	v_mfma_f32_16x16x32_bf16 v[16:19], v[168:171], v[210:213], v[16:19]
	v_mfma_f32_16x16x32_bf16 v[8:11], v[178:181], v[210:213], v[8:11]
	v_mfma_f32_16x16x32_bf16 v[4:7], v[168:171], v[218:221], v[4:7]
	v_mfma_f32_16x16x32_bf16 v[0:3], v[178:181], v[218:221], v[0:3]
	s_setprio 0
	s_barrier
	s_add_i32 vcc_hi, vcc_hi, 2
	s_add_u32 s97, s97, 0x100
	s_addc_u32 vcc_lo, vcc_lo, 0
	s_cmp_gt_u32 vcc_hi, 21
	s_mov_b64 s[54:55], s[56:57]
	s_cbranch_scc0 .LBB0_953
	s_and_b64 vcc, exec, s[14:15]
	s_cbranch_vccz .LBB0_956
	s_barrier

.LBB0_979:
	ds_read_b128 v[144:147], v141
	ds_read_b128 v[148:151], v141 offset:1024
	ds_read_b128 v[152:155], v141 offset:2048
	ds_read_b128 v[156:159], v141 offset:3072
	ds_read_b128 v[160:163], v142
	ds_read_b128 v[164:167], v142 offset:1024
	ds_read_b128 v[168:171], v142 offset:2048
	ds_read_b128 v[172:175], v142 offset:3072
	ds_read_b128 v[178:181], v143
	ds_read_b128 v[182:185], v143 offset:1024
	ds_read_b128 v[186:189], v143 offset:2048
	ds_read_b128 v[190:193], v143 offset:3072
	ds_read_b128 v[194:197], v143 offset:4096
	ds_read_b128 v[206:209], v143 offset:5120
	ds_read_b128 v[210:213], v143 offset:6144
	ds_read_b128 v[214:217], v143 offset:7168
	s_add_u32 s2, s46, s58
	s_addc_u32 s3, s47, 0
	s_add_u32 s38, s2, 0x100
	s_addc_u32 s39, s3, 0
	s_and_b64 s[0:1], s[52:53], exec
	s_cselect_b32 s57, s23, s39
	s_cselect_b32 s56, s85, s38
	s_add_u32 s0, s34, s58
	s_addc_u32 s1, s35, 0
	s_add_u32 s38, s0, 0x100
	s_addc_u32 s39, s1, 0
	s_and_b64 s[0:1], s[52:53], exec
	s_cselect_b32 s59, s86, s39
	s_cselect_b32 s58, s87, s38
	s_add_u32 s62, s2, 0x10080
	s_addc_u32 s63, s3, 0
	s_add_i32 s38, s78, s66
	s_add_i32 m0, s25, 0xc000
	s_add_i32 s39, s25, 0xe000
	s_add_i32 s0, s38, 0x2000
	s_add_u32 s60, s58, 0x10000
	s_addc_u32 s61, s59, 0
	s_add_i32 s91, s79, s66
	s_add_i32 s76, s91, 0x2000
	s_add_i32 s3, 0, 0x18000
	s_add_i32 s2, 0, 0x1c000
	v_cndmask_b32_e64 v136, 0, 1, s[54:55]
	s_add_u32 s54, s56, 0x10000
	s_addc_u32 s55, s57, 0
	s_add_i32 s1, s3, s66
	s_add_i32 s89, s1, 0x2000
	s_add_u32 s52, s58, 0x10080
	s_addc_u32 s53, s59, 0
	s_add_i32 s90, s2, s66
	s_add_i32 s88, s90, 0x2000
	v_cmp_ne_u32_e32 vcc, 1, v136
	v_lshl_add_u64 v[136:137], s[62:63], 0, v[128:129]
	global_load_lds_dwordx4 v[136:137], off
	s_mov_b32 m0, s39
	v_lshl_add_u64 v[136:137], s[62:63], 0, v[132:133]
	global_load_lds_dwordx4 v[136:137], off
	s_waitcnt vmcnt(8) lgkmcnt(0)
	s_setprio 1
	s_barrier
	v_mfma_f32_16x16x32_bf16 v[124:127], v[144:147], v[178:181], v[124:127]
	v_mfma_f32_16x16x32_bf16 v[120:123], v[152:155], v[178:181], v[120:123]
	v_mfma_f32_16x16x32_bf16 v[116:119], v[144:147], v[186:189], v[116:119]
	v_mfma_f32_16x16x32_bf16 v[108:111], v[152:155], v[186:189], v[108:111]
	v_mfma_f32_16x16x32_bf16 v[100:103], v[144:147], v[194:197], v[100:103]
	v_mfma_f32_16x16x32_bf16 v[92:95], v[152:155], v[194:197], v[92:95]
	v_mfma_f32_16x16x32_bf16 v[84:87], v[144:147], v[210:213], v[84:87]
	v_mfma_f32_16x16x32_bf16 v[76:79], v[152:155], v[210:213], v[76:79]
	v_mfma_f32_16x16x32_bf16 v[124:127], v[148:151], v[182:185], v[124:127]
	v_mfma_f32_16x16x32_bf16 v[120:123], v[156:159], v[182:185], v[120:123]
	v_mfma_f32_16x16x32_bf16 v[116:119], v[148:151], v[190:193], v[116:119]
	v_mfma_f32_16x16x32_bf16 v[108:111], v[156:159], v[190:193], v[108:111]
	v_mfma_f32_16x16x32_bf16 v[100:103], v[148:151], v[206:209], v[100:103]
	v_mfma_f32_16x16x32_bf16 v[92:95], v[156:159], v[206:209], v[92:95]
	v_mfma_f32_16x16x32_bf16 v[84:87], v[148:151], v[214:217], v[84:87]
	v_mfma_f32_16x16x32_bf16 v[76:79], v[156:159], v[214:217], v[76:79]
	v_mfma_f32_16x16x32_bf16 v[112:115], v[160:163], v[178:181], v[112:115]
	v_mfma_f32_16x16x32_bf16 v[104:107], v[168:171], v[178:181], v[104:107]
	v_mfma_f32_16x16x32_bf16 v[96:99], v[160:163], v[186:189], v[96:99]
	v_mfma_f32_16x16x32_bf16 v[88:91], v[168:171], v[186:189], v[88:91]
	v_mfma_f32_16x16x32_bf16 v[80:83], v[160:163], v[194:197], v[80:83]
	v_mfma_f32_16x16x32_bf16 v[72:75], v[168:171], v[194:197], v[72:75]
	v_mfma_f32_16x16x32_bf16 v[68:71], v[160:163], v[210:213], v[68:71]
	v_mfma_f32_16x16x32_bf16 v[64:67], v[168:171], v[210:213], v[64:67]
	v_mfma_f32_16x16x32_bf16 v[112:115], v[164:167], v[182:185], v[112:115]
	v_mfma_f32_16x16x32_bf16 v[104:107], v[172:175], v[182:185], v[104:107]
	v_mfma_f32_16x16x32_bf16 v[96:99], v[164:167], v[190:193], v[96:99]
	v_mfma_f32_16x16x32_bf16 v[88:91], v[172:175], v[190:193], v[88:91]
	v_mfma_f32_16x16x32_bf16 v[80:83], v[164:167], v[206:209], v[80:83]
	v_mfma_f32_16x16x32_bf16 v[72:75], v[172:175], v[206:209], v[72:75]
	v_mfma_f32_16x16x32_bf16 v[68:71], v[164:167], v[214:217], v[68:71]
	v_mfma_f32_16x16x32_bf16 v[64:67], v[172:175], v[214:217], v[64:67]
	s_setprio 0
	s_barrier
	ds_read_b128 v[178:181], v143 offset:16384
	ds_read_b128 v[182:185], v143 offset:17408
	ds_read_b128 v[186:189], v143 offset:18432
	ds_read_b128 v[190:193], v143 offset:19456
	ds_read_b128 v[194:197], v143 offset:20480
	ds_read_b128 v[206:209], v143 offset:21504
	ds_read_b128 v[210:213], v143 offset:22528
	ds_read_b128 v[214:217], v143 offset:23552
	s_mov_b32 m0, s38
	v_lshl_add_u64 v[136:137], s[58:59], 0, v[130:131]
	global_load_lds_dwordx4 v[136:137], off
	v_lshl_add_u64 v[198:199], s[58:59], 0, v[134:135]
	s_mov_b32 m0, s0
	v_lshl_add_u64 v[202:203], s[60:61], 0, v[130:131]
	global_load_lds_dwordx4 v[198:199], off
	s_mov_b32 m0, s91
	v_lshl_add_u64 v[218:219], s[56:57], 0, v[132:133]
	global_load_lds_dwordx4 v[202:203], off
	s_mov_b32 m0, s76
	v_lshl_add_u64 v[202:203], s[60:61], 0, v[134:135]
	global_load_lds_dwordx4 v[202:203], off
	s_mov_b32 m0, s25
	v_lshl_add_u64 v[202:203], s[56:57], 0, v[128:129]
	global_load_lds_dwordx4 v[202:203], off
	s_mov_b32 m0, s69
	s_nop 0
	global_load_lds_dwordx4 v[218:219], off
	s_waitcnt vmcnt(8) lgkmcnt(0)
	s_setprio 1
	s_barrier
	v_mfma_f32_16x16x32_bf16 v[60:63], v[144:147], v[178:181], v[60:63]
	v_mfma_f32_16x16x32_bf16 v[56:59], v[152:155], v[178:181], v[56:59]
	v_mfma_f32_16x16x32_bf16 v[52:55], v[144:147], v[186:189], v[52:55]
	v_mfma_f32_16x16x32_bf16 v[44:47], v[152:155], v[186:189], v[44:47]
	v_mfma_f32_16x16x32_bf16 v[36:39], v[144:147], v[194:197], v[36:39]
	v_mfma_f32_16x16x32_bf16 v[28:31], v[152:155], v[194:197], v[28:31]
	v_mfma_f32_16x16x32_bf16 v[20:23], v[144:147], v[210:213], v[20:23]
	v_mfma_f32_16x16x32_bf16 v[12:15], v[152:155], v[210:213], v[12:15]
	v_mfma_f32_16x16x32_bf16 v[60:63], v[148:151], v[182:185], v[60:63]
	v_mfma_f32_16x16x32_bf16 v[56:59], v[156:159], v[182:185], v[56:59]
	v_mfma_f32_16x16x32_bf16 v[52:55], v[148:151], v[190:193], v[52:55]
	v_mfma_f32_16x16x32_bf16 v[44:47], v[156:159], v[190:193], v[44:47]
	v_mfma_f32_16x16x32_bf16 v[36:39], v[148:151], v[206:209], v[36:39]
	v_mfma_f32_16x16x32_bf16 v[28:31], v[156:159], v[206:209], v[28:31]
	v_mfma_f32_16x16x32_bf16 v[20:23], v[148:151], v[214:217], v[20:23]
	v_mfma_f32_16x16x32_bf16 v[12:15], v[156:159], v[214:217], v[12:15]
	v_mfma_f32_16x16x32_bf16 v[48:51], v[160:163], v[178:181], v[48:51]
	v_mfma_f32_16x16x32_bf16 v[40:43], v[168:171], v[178:181], v[40:43]
	v_mfma_f32_16x16x32_bf16 v[32:35], v[160:163], v[186:189], v[32:35]
	v_mfma_f32_16x16x32_bf16 v[24:27], v[168:171], v[186:189], v[24:27]
	v_mfma_f32_16x16x32_bf16 v[16:19], v[160:163], v[194:197], v[16:19]
	v_mfma_f32_16x16x32_bf16 v[8:11], v[168:171], v[194:197], v[8:11]
	v_mfma_f32_16x16x32_bf16 v[4:7], v[160:163], v[210:213], v[4:7]
	v_mfma_f32_16x16x32_bf16 v[0:3], v[168:171], v[210:213], v[0:3]
	v_mfma_f32_16x16x32_bf16 v[48:51], v[164:167], v[182:185], v[48:51]
	v_mfma_f32_16x16x32_bf16 v[40:43], v[172:175], v[182:185], v[40:43]
	v_mfma_f32_16x16x32_bf16 v[32:35], v[164:167], v[190:193], v[32:35]
	v_mfma_f32_16x16x32_bf16 v[24:27], v[172:175], v[190:193], v[24:27]
	v_mfma_f32_16x16x32_bf16 v[16:19], v[164:167], v[206:209], v[16:19]
	v_mfma_f32_16x16x32_bf16 v[8:11], v[172:175], v[206:209], v[8:11]
	v_mfma_f32_16x16x32_bf16 v[4:7], v[164:167], v[214:217], v[4:7]
	v_mfma_f32_16x16x32_bf16 v[0:3], v[172:175], v[214:217], v[0:3]
	s_setprio 0
	s_barrier
	ds_read_b128 v[178:181], v143 offset:32768
	ds_read_b128 v[182:185], v143 offset:33792
	ds_read_b128 v[186:189], v143 offset:34816
	ds_read_b128 v[190:193], v143 offset:35840
	ds_read_b128 v[194:197], v143 offset:36864
	ds_read_b128 v[206:209], v143 offset:37888
	ds_read_b128 v[210:213], v143 offset:38912
	ds_read_b128 v[214:217], v143 offset:39936
	v_add_u32_e32 v156, s3, v140
	v_add_u32_e32 v172, s2, v140
	ds_read_b128 v[144:147], v156
	ds_read_b128 v[148:151], v156 offset:1024
	ds_read_b128 v[152:155], v156 offset:2048
	ds_read_b128 v[156:159], v156 offset:3072
	ds_read_b128 v[160:163], v172
	ds_read_b128 v[164:167], v172 offset:1024
	ds_read_b128 v[168:171], v172 offset:2048
	ds_read_b128 v[172:175], v172 offset:3072
	s_mov_b32 m0, s70
	v_lshl_add_u64 v[220:221], s[54:55], 0, v[128:129]
	global_load_lds_dwordx4 v[220:221], off
	s_mov_b32 m0, s71
	v_lshl_add_u64 v[220:221], s[54:55], 0, v[132:133]
	global_load_lds_dwordx4 v[220:221], off
	s_waitcnt vmcnt(8) lgkmcnt(0)
	s_setprio 1
	s_barrier
	v_mfma_f32_16x16x32_bf16 v[124:127], v[144:147], v[178:181], v[124:127]
	v_mfma_f32_16x16x32_bf16 v[120:123], v[152:155], v[178:181], v[120:123]
	v_mfma_f32_16x16x32_bf16 v[116:119], v[144:147], v[186:189], v[116:119]
	v_mfma_f32_16x16x32_bf16 v[108:111], v[152:155], v[186:189], v[108:111]
	v_mfma_f32_16x16x32_bf16 v[100:103], v[144:147], v[194:197], v[100:103]
	v_mfma_f32_16x16x32_bf16 v[92:95], v[152:155], v[194:197], v[92:95]
	v_mfma_f32_16x16x32_bf16 v[84:87], v[144:147], v[210:213], v[84:87]
	v_mfma_f32_16x16x32_bf16 v[76:79], v[152:155], v[210:213], v[76:79]
	v_mfma_f32_16x16x32_bf16 v[124:127], v[148:151], v[182:185], v[124:127]
	v_mfma_f32_16x16x32_bf16 v[120:123], v[156:159], v[182:185], v[120:123]
	v_mfma_f32_16x16x32_bf16 v[116:119], v[148:151], v[190:193], v[116:119]
	v_mfma_f32_16x16x32_bf16 v[108:111], v[156:159], v[190:193], v[108:111]
	v_mfma_f32_16x16x32_bf16 v[100:103], v[148:151], v[206:209], v[100:103]
	v_mfma_f32_16x16x32_bf16 v[92:95], v[156:159], v[206:209], v[92:95]
	v_mfma_f32_16x16x32_bf16 v[84:87], v[148:151], v[214:217], v[84:87]
	v_mfma_f32_16x16x32_bf16 v[76:79], v[156:159], v[214:217], v[76:79]
	v_mfma_f32_16x16x32_bf16 v[112:115], v[160:163], v[178:181], v[112:115]
	v_mfma_f32_16x16x32_bf16 v[104:107], v[168:171], v[178:181], v[104:107]
	v_mfma_f32_16x16x32_bf16 v[96:99], v[160:163], v[186:189], v[96:99]
	v_mfma_f32_16x16x32_bf16 v[88:91], v[168:171], v[186:189], v[88:91]
	v_mfma_f32_16x16x32_bf16 v[80:83], v[160:163], v[194:197], v[80:83]
	v_mfma_f32_16x16x32_bf16 v[72:75], v[168:171], v[194:197], v[72:75]
	v_mfma_f32_16x16x32_bf16 v[68:71], v[160:163], v[210:213], v[68:71]
	v_mfma_f32_16x16x32_bf16 v[64:67], v[168:171], v[210:213], v[64:67]
	v_mfma_f32_16x16x32_bf16 v[112:115], v[164:167], v[182:185], v[112:115]
	v_mfma_f32_16x16x32_bf16 v[104:107], v[172:175], v[182:185], v[104:107]
	v_mfma_f32_16x16x32_bf16 v[96:99], v[164:167], v[190:193], v[96:99]
	v_mfma_f32_16x16x32_bf16 v[88:91], v[172:175], v[190:193], v[88:91]
	v_mfma_f32_16x16x32_bf16 v[80:83], v[164:167], v[206:209], v[80:83]
	v_mfma_f32_16x16x32_bf16 v[72:75], v[172:175], v[206:209], v[72:75]
	v_mfma_f32_16x16x32_bf16 v[68:71], v[164:167], v[214:217], v[68:71]
	v_mfma_f32_16x16x32_bf16 v[64:67], v[172:175], v[214:217], v[64:67]
	s_setprio 0
	s_barrier
	ds_read_b128 v[178:181], v143 offset:49152
	ds_read_b128 v[182:185], v143 offset:50176
	ds_read_b128 v[186:189], v143 offset:51200
	ds_read_b128 v[190:193], v143 offset:52224
	ds_read_b128 v[194:197], v143 offset:53248
	ds_read_b128 v[206:209], v143 offset:54272
	ds_read_b128 v[210:213], v143 offset:55296
	ds_read_b128 v[214:217], v143 offset:56320
	s_mov_b32 m0, s1
	v_lshl_add_u64 v[136:137], v[136:137], 0, s[10:11]
	global_load_lds_dwordx4 v[136:137], off
	s_mov_b32 m0, s89
	v_lshl_add_u64 v[136:137], v[198:199], 0, s[10:11]
	global_load_lds_dwordx4 v[136:137], off
	s_mov_b32 m0, s90
	v_lshl_add_u64 v[136:137], s[52:53], 0, v[130:131]
	global_load_lds_dwordx4 v[136:137], off
	s_mov_b32 m0, s88
	v_lshl_add_u64 v[136:137], s[52:53], 0, v[134:135]
	global_load_lds_dwordx4 v[136:137], off
	s_mov_b32 m0, s75
	v_lshl_add_u64 v[136:137], v[202:203], 0, s[10:11]
	global_load_lds_dwordx4 v[136:137], off
	s_mov_b32 m0, s77
	v_lshl_add_u64 v[136:137], v[218:219], 0, s[10:11]
	global_load_lds_dwordx4 v[136:137], off
	s_waitcnt vmcnt(8) lgkmcnt(0)
	s_setprio 1
	s_barrier
	v_mfma_f32_16x16x32_bf16 v[60:63], v[144:147], v[178:181], v[60:63]
	v_mfma_f32_16x16x32_bf16 v[56:59], v[152:155], v[178:181], v[56:59]
	v_mfma_f32_16x16x32_bf16 v[52:55], v[144:147], v[186:189], v[52:55]
	v_mfma_f32_16x16x32_bf16 v[44:47], v[152:155], v[186:189], v[44:47]
	v_mfma_f32_16x16x32_bf16 v[36:39], v[144:147], v[194:197], v[36:39]
	v_mfma_f32_16x16x32_bf16 v[28:31], v[152:155], v[194:197], v[28:31]
	v_mfma_f32_16x16x32_bf16 v[20:23], v[144:147], v[210:213], v[20:23]
	v_mfma_f32_16x16x32_bf16 v[12:15], v[152:155], v[210:213], v[12:15]
	v_mfma_f32_16x16x32_bf16 v[60:63], v[148:151], v[182:185], v[60:63]
	v_mfma_f32_16x16x32_bf16 v[56:59], v[156:159], v[182:185], v[56:59]
	v_mfma_f32_16x16x32_bf16 v[52:55], v[148:151], v[190:193], v[52:55]
	v_mfma_f32_16x16x32_bf16 v[44:47], v[156:159], v[190:193], v[44:47]
	v_mfma_f32_16x16x32_bf16 v[36:39], v[148:151], v[206:209], v[36:39]
	v_mfma_f32_16x16x32_bf16 v[28:31], v[156:159], v[206:209], v[28:31]
	v_mfma_f32_16x16x32_bf16 v[20:23], v[148:151], v[214:217], v[20:23]
	v_mfma_f32_16x16x32_bf16 v[12:15], v[156:159], v[214:217], v[12:15]
	v_mfma_f32_16x16x32_bf16 v[48:51], v[160:163], v[178:181], v[48:51]
	v_mfma_f32_16x16x32_bf16 v[40:43], v[168:171], v[178:181], v[40:43]
	v_mfma_f32_16x16x32_bf16 v[32:35], v[160:163], v[186:189], v[32:35]
	v_mfma_f32_16x16x32_bf16 v[24:27], v[168:171], v[186:189], v[24:27]
	v_mfma_f32_16x16x32_bf16 v[16:19], v[160:163], v[194:197], v[16:19]
	v_mfma_f32_16x16x32_bf16 v[8:11], v[168:171], v[194:197], v[8:11]
	v_mfma_f32_16x16x32_bf16 v[4:7], v[160:163], v[210:213], v[4:7]
	v_mfma_f32_16x16x32_bf16 v[0:3], v[168:171], v[210:213], v[0:3]
	v_mfma_f32_16x16x32_bf16 v[48:51], v[164:167], v[182:185], v[48:51]
	v_mfma_f32_16x16x32_bf16 v[40:43], v[172:175], v[182:185], v[40:43]
	v_mfma_f32_16x16x32_bf16 v[32:35], v[164:167], v[190:193], v[32:35]
	v_mfma_f32_16x16x32_bf16 v[24:27], v[172:175], v[190:193], v[24:27]
	v_mfma_f32_16x16x32_bf16 v[16:19], v[164:167], v[206:209], v[16:19]
	v_mfma_f32_16x16x32_bf16 v[8:11], v[172:175], v[206:209], v[8:11]
	v_mfma_f32_16x16x32_bf16 v[4:7], v[164:167], v[214:217], v[4:7]
	v_mfma_f32_16x16x32_bf16 v[0:3], v[172:175], v[214:217], v[0:3]
	s_setprio 0
	s_barrier
	s_movk_i32 s58, 0x100
	s_mov_b64 s[54:55], 0
	s_mov_b64 s[52:53], -1
	s_cbranch_vccz .LBB0_979
	s_and_b64 vcc, exec, s[12:13]
	s_cbranch_vccz .LBB0_982
	s_barrier

.LBB0_1037:
	ds_read_b128 v[128:131], v157
	ds_read_b128 v[132:135], v157 offset:1024
	ds_read_b128 v[136:139], v157 offset:2048
	ds_read_b128 v[140:143], v157 offset:3072
	ds_read_b128 v[160:163], v158
	ds_read_b128 v[164:167], v158 offset:1024
	ds_read_b128 v[168:171], v158 offset:2048
	ds_read_b128 v[172:175], v158 offset:3072
	ds_read_b128 v[178:181], v159
	ds_read_b128 v[182:185], v159 offset:1024
	ds_read_b128 v[186:189], v159 offset:2048
	ds_read_b128 v[190:193], v159 offset:3072
	ds_read_b128 v[194:197], v159 offset:4096
	ds_read_b128 v[206:209], v159 offset:5120
	ds_read_b128 v[210:213], v159 offset:6144
	ds_read_b128 v[214:217], v159 offset:7168
	s_add_u32 s0, s58, 0xfff00080
	s_addc_u32 s1, s59, -1
	s_cmp_eq_u32 s87, 60
	s_cselect_b32 s63, s12, s1
	s_cselect_b32 s62, s29, s0
	s_cselect_b32 s61, s57, s86
	s_cselect_b32 s60, s64, s65
	s_add_i32 m0, s68, 0xc000
	v_lshl_add_u64 v[152:153], s[58:59], 0, v[148:149]
	global_load_lds_dwordx4 v[152:153], off
	s_add_i32 m0, s68, 0xe000
	v_lshl_add_u64 v[152:153], s[58:59], 0, v[150:151]
	global_load_lds_dwordx4 v[152:153], off
	s_waitcnt vmcnt(8) lgkmcnt(0)
	s_setprio 1
	s_barrier
	v_mfma_f32_16x16x32_bf16 v[124:127], v[128:131], v[178:181], v[124:127]
	v_mfma_f32_16x16x32_bf16 v[120:123], v[136:139], v[178:181], v[120:123]
	v_mfma_f32_16x16x32_bf16 v[112:115], v[128:131], v[186:189], v[112:115]
	v_mfma_f32_16x16x32_bf16 v[108:111], v[136:139], v[186:189], v[108:111]
	v_mfma_f32_16x16x32_bf16 v[96:99], v[128:131], v[194:197], v[96:99]
	v_mfma_f32_16x16x32_bf16 v[92:95], v[136:139], v[194:197], v[92:95]
	v_mfma_f32_16x16x32_bf16 v[80:83], v[128:131], v[210:213], v[80:83]
	v_mfma_f32_16x16x32_bf16 v[76:79], v[136:139], v[210:213], v[76:79]
	v_mfma_f32_16x16x32_bf16 v[124:127], v[132:135], v[182:185], v[124:127]
	v_mfma_f32_16x16x32_bf16 v[120:123], v[140:143], v[182:185], v[120:123]
	v_mfma_f32_16x16x32_bf16 v[112:115], v[132:135], v[190:193], v[112:115]
	v_mfma_f32_16x16x32_bf16 v[108:111], v[140:143], v[190:193], v[108:111]
	v_mfma_f32_16x16x32_bf16 v[96:99], v[132:135], v[206:209], v[96:99]
	v_mfma_f32_16x16x32_bf16 v[92:95], v[140:143], v[206:209], v[92:95]
	v_mfma_f32_16x16x32_bf16 v[80:83], v[132:135], v[214:217], v[80:83]
	v_mfma_f32_16x16x32_bf16 v[76:79], v[140:143], v[214:217], v[76:79]
	v_mfma_f32_16x16x32_bf16 v[116:119], v[160:163], v[178:181], v[116:119]
	v_mfma_f32_16x16x32_bf16 v[104:107], v[168:171], v[178:181], v[104:107]
	v_mfma_f32_16x16x32_bf16 v[100:103], v[160:163], v[186:189], v[100:103]
	v_mfma_f32_16x16x32_bf16 v[88:91], v[168:171], v[186:189], v[88:91]
	v_mfma_f32_16x16x32_bf16 v[84:87], v[160:163], v[194:197], v[84:87]
	v_mfma_f32_16x16x32_bf16 v[72:75], v[168:171], v[194:197], v[72:75]
	v_mfma_f32_16x16x32_bf16 v[68:71], v[160:163], v[210:213], v[68:71]
	v_mfma_f32_16x16x32_bf16 v[64:67], v[168:171], v[210:213], v[64:67]
	v_mfma_f32_16x16x32_bf16 v[116:119], v[164:167], v[182:185], v[116:119]
	v_mfma_f32_16x16x32_bf16 v[104:107], v[172:175], v[182:185], v[104:107]
	v_mfma_f32_16x16x32_bf16 v[100:103], v[164:167], v[190:193], v[100:103]
	v_mfma_f32_16x16x32_bf16 v[88:91], v[172:175], v[190:193], v[88:91]
	v_mfma_f32_16x16x32_bf16 v[84:87], v[164:167], v[206:209], v[84:87]
	v_mfma_f32_16x16x32_bf16 v[72:75], v[172:175], v[206:209], v[72:75]
	v_mfma_f32_16x16x32_bf16 v[68:71], v[164:167], v[214:217], v[68:71]
	v_mfma_f32_16x16x32_bf16 v[64:67], v[172:175], v[214:217], v[64:67]
	s_setprio 0
	s_barrier
	ds_read_b128 v[178:181], v159 offset:16384
	ds_read_b128 v[182:185], v159 offset:17408
	ds_read_b128 v[186:189], v159 offset:18432
	ds_read_b128 v[190:193], v159 offset:19456
	ds_read_b128 v[194:197], v159 offset:20480
	ds_read_b128 v[206:209], v159 offset:21504
	ds_read_b128 v[210:213], v159 offset:22528
	ds_read_b128 v[214:217], v159 offset:23552
	s_add_i32 s0, s81, s67
	s_mov_b32 m0, s0
	v_lshl_add_u64 v[152:153], s[60:61], 0, v[146:147]
	global_load_lds_dwordx4 v[152:153], off
	s_add_i32 m0, s0, 0x2000
	s_add_u32 s0, s60, 0x100000
	v_lshl_add_u64 v[198:199], s[60:61], 0, v[144:145]
	s_addc_u32 s1, s61, 0
	s_add_i32 s2, s82, s67
	global_load_lds_dwordx4 v[198:199], off
	v_lshl_add_u64 v[202:203], s[0:1], 0, v[146:147]
	s_mov_b32 m0, s2
	v_lshl_add_u64 v[218:219], s[62:63], 0, v[144:145]
	global_load_lds_dwordx4 v[202:203], off
	s_add_i32 m0, s2, 0x2000
	v_lshl_add_u64 v[202:203], s[0:1], 0, v[144:145]
	global_load_lds_dwordx4 v[202:203], off
	s_mov_b32 m0, s68
	v_lshl_add_u64 v[202:203], s[62:63], 0, v[146:147]
	global_load_lds_dwordx4 v[202:203], off
	s_mov_b32 m0, s69
	s_nop 0
	global_load_lds_dwordx4 v[218:219], off
	s_waitcnt vmcnt(8) lgkmcnt(0)
	s_setprio 1
	s_barrier
	v_mfma_f32_16x16x32_bf16 v[60:63], v[128:131], v[178:181], v[60:63]
	v_mfma_f32_16x16x32_bf16 v[56:59], v[136:139], v[178:181], v[56:59]
	v_mfma_f32_16x16x32_bf16 v[48:51], v[128:131], v[186:189], v[48:51]
	v_mfma_f32_16x16x32_bf16 v[44:47], v[136:139], v[186:189], v[44:47]
	v_mfma_f32_16x16x32_bf16 v[32:35], v[128:131], v[194:197], v[32:35]
	v_mfma_f32_16x16x32_bf16 v[28:31], v[136:139], v[194:197], v[28:31]
	v_mfma_f32_16x16x32_bf16 v[16:19], v[128:131], v[210:213], v[16:19]
	v_mfma_f32_16x16x32_bf16 v[12:15], v[136:139], v[210:213], v[12:15]
	v_mfma_f32_16x16x32_bf16 v[60:63], v[132:135], v[182:185], v[60:63]
	v_mfma_f32_16x16x32_bf16 v[56:59], v[140:143], v[182:185], v[56:59]
	v_mfma_f32_16x16x32_bf16 v[48:51], v[132:135], v[190:193], v[48:51]
	v_mfma_f32_16x16x32_bf16 v[44:47], v[140:143], v[190:193], v[44:47]
	v_mfma_f32_16x16x32_bf16 v[32:35], v[132:135], v[206:209], v[32:35]
	v_mfma_f32_16x16x32_bf16 v[28:31], v[140:143], v[206:209], v[28:31]
	v_mfma_f32_16x16x32_bf16 v[16:19], v[132:135], v[214:217], v[16:19]
	v_mfma_f32_16x16x32_bf16 v[12:15], v[140:143], v[214:217], v[12:15]
	v_mfma_f32_16x16x32_bf16 v[52:55], v[160:163], v[178:181], v[52:55]
	v_mfma_f32_16x16x32_bf16 v[40:43], v[168:171], v[178:181], v[40:43]
	v_mfma_f32_16x16x32_bf16 v[36:39], v[160:163], v[186:189], v[36:39]
	v_mfma_f32_16x16x32_bf16 v[24:27], v[168:171], v[186:189], v[24:27]
	v_mfma_f32_16x16x32_bf16 v[20:23], v[160:163], v[194:197], v[20:23]
	v_mfma_f32_16x16x32_bf16 v[8:11], v[168:171], v[194:197], v[8:11]
	v_mfma_f32_16x16x32_bf16 v[4:7], v[160:163], v[210:213], v[4:7]
	v_mfma_f32_16x16x32_bf16 v[0:3], v[168:171], v[210:213], v[0:3]
	v_mfma_f32_16x16x32_bf16 v[52:55], v[164:167], v[182:185], v[52:55]
	v_mfma_f32_16x16x32_bf16 v[40:43], v[172:175], v[182:185], v[40:43]
	v_mfma_f32_16x16x32_bf16 v[36:39], v[164:167], v[190:193], v[36:39]
	v_mfma_f32_16x16x32_bf16 v[24:27], v[172:175], v[190:193], v[24:27]
	v_mfma_f32_16x16x32_bf16 v[20:23], v[164:167], v[206:209], v[20:23]
	v_mfma_f32_16x16x32_bf16 v[8:11], v[172:175], v[206:209], v[8:11]
	v_mfma_f32_16x16x32_bf16 v[4:7], v[164:167], v[214:217], v[4:7]
	v_mfma_f32_16x16x32_bf16 v[0:3], v[172:175], v[214:217], v[0:3]
	s_setprio 0
	s_barrier
	ds_read_b128 v[178:181], v159 offset:32768
	ds_read_b128 v[182:185], v159 offset:33792
	ds_read_b128 v[186:189], v159 offset:34816
	ds_read_b128 v[190:193], v159 offset:35840
	ds_read_b128 v[194:197], v159 offset:36864
	ds_read_b128 v[206:209], v159 offset:37888
	ds_read_b128 v[210:213], v159 offset:38912
	ds_read_b128 v[214:217], v159 offset:39936
	s_add_i32 s2, 0, 0x18000
	s_add_i32 s3, 0, 0x1c000
	v_add_u32_e32 v140, s2, v156
	v_add_u32_e32 v172, s3, v156
	ds_read_b128 v[128:131], v140
	ds_read_b128 v[132:135], v140 offset:1024
	ds_read_b128 v[136:139], v140 offset:2048
	ds_read_b128 v[140:143], v140 offset:3072
	ds_read_b128 v[160:163], v172
	ds_read_b128 v[164:167], v172 offset:1024
	ds_read_b128 v[168:171], v172 offset:2048
	ds_read_b128 v[172:175], v172 offset:3072
	s_add_u32 s0, s62, 0x100000
	s_addc_u32 s1, s63, 0
	s_mov_b32 m0, s70
	v_lshl_add_u64 v[220:221], s[0:1], 0, v[146:147]
	global_load_lds_dwordx4 v[220:221], off
	s_mov_b32 m0, s71
	v_lshl_add_u64 v[220:221], s[0:1], 0, v[144:145]
	global_load_lds_dwordx4 v[220:221], off
	s_waitcnt vmcnt(8) lgkmcnt(0)
	s_setprio 1
	s_barrier
	v_mfma_f32_16x16x32_bf16 v[124:127], v[128:131], v[178:181], v[124:127]
	v_mfma_f32_16x16x32_bf16 v[120:123], v[136:139], v[178:181], v[120:123]
	v_mfma_f32_16x16x32_bf16 v[112:115], v[128:131], v[186:189], v[112:115]
	v_mfma_f32_16x16x32_bf16 v[108:111], v[136:139], v[186:189], v[108:111]
	v_mfma_f32_16x16x32_bf16 v[96:99], v[128:131], v[194:197], v[96:99]
	v_mfma_f32_16x16x32_bf16 v[92:95], v[136:139], v[194:197], v[92:95]
	v_mfma_f32_16x16x32_bf16 v[80:83], v[128:131], v[210:213], v[80:83]
	v_mfma_f32_16x16x32_bf16 v[76:79], v[136:139], v[210:213], v[76:79]
	v_mfma_f32_16x16x32_bf16 v[124:127], v[132:135], v[182:185], v[124:127]
	v_mfma_f32_16x16x32_bf16 v[120:123], v[140:143], v[182:185], v[120:123]
	v_mfma_f32_16x16x32_bf16 v[112:115], v[132:135], v[190:193], v[112:115]
	v_mfma_f32_16x16x32_bf16 v[108:111], v[140:143], v[190:193], v[108:111]
	v_mfma_f32_16x16x32_bf16 v[96:99], v[132:135], v[206:209], v[96:99]
	v_mfma_f32_16x16x32_bf16 v[92:95], v[140:143], v[206:209], v[92:95]
	v_mfma_f32_16x16x32_bf16 v[80:83], v[132:135], v[214:217], v[80:83]
	v_mfma_f32_16x16x32_bf16 v[76:79], v[140:143], v[214:217], v[76:79]
	v_mfma_f32_16x16x32_bf16 v[116:119], v[160:163], v[178:181], v[116:119]
	v_mfma_f32_16x16x32_bf16 v[104:107], v[168:171], v[178:181], v[104:107]
	v_mfma_f32_16x16x32_bf16 v[100:103], v[160:163], v[186:189], v[100:103]
	v_mfma_f32_16x16x32_bf16 v[88:91], v[168:171], v[186:189], v[88:91]
	v_mfma_f32_16x16x32_bf16 v[84:87], v[160:163], v[194:197], v[84:87]
	v_mfma_f32_16x16x32_bf16 v[72:75], v[168:171], v[194:197], v[72:75]
	v_mfma_f32_16x16x32_bf16 v[68:71], v[160:163], v[210:213], v[68:71]
	v_mfma_f32_16x16x32_bf16 v[64:67], v[168:171], v[210:213], v[64:67]
	v_mfma_f32_16x16x32_bf16 v[116:119], v[164:167], v[182:185], v[116:119]
	v_mfma_f32_16x16x32_bf16 v[104:107], v[172:175], v[182:185], v[104:107]
	v_mfma_f32_16x16x32_bf16 v[100:103], v[164:167], v[190:193], v[100:103]
	v_mfma_f32_16x16x32_bf16 v[88:91], v[172:175], v[190:193], v[88:91]
	v_mfma_f32_16x16x32_bf16 v[84:87], v[164:167], v[206:209], v[84:87]
	v_mfma_f32_16x16x32_bf16 v[72:75], v[172:175], v[206:209], v[72:75]
	v_mfma_f32_16x16x32_bf16 v[68:71], v[164:167], v[214:217], v[68:71]
	v_mfma_f32_16x16x32_bf16 v[64:67], v[172:175], v[214:217], v[64:67]
	s_setprio 0
	s_barrier
	ds_read_b128 v[178:181], v159 offset:49152
	ds_read_b128 v[182:185], v159 offset:50176
	ds_read_b128 v[186:189], v159 offset:51200
	ds_read_b128 v[190:193], v159 offset:52224
	ds_read_b128 v[194:197], v159 offset:53248
	ds_read_b128 v[206:209], v159 offset:54272
	ds_read_b128 v[210:213], v159 offset:55296
	ds_read_b128 v[214:217], v159 offset:56320
	s_add_i32 s0, s2, s67
	s_mov_b32 m0, s0
	v_lshl_add_u64 v[152:153], v[152:153], 0, s[10:11]
	global_load_lds_dwordx4 v[152:153], off
	s_add_i32 m0, s0, 0x2000
	s_add_u32 s0, s60, 0x100080
	v_lshl_add_u64 v[152:153], v[198:199], 0, s[10:11]
	s_addc_u32 s1, s61, 0
	s_add_i32 s2, s3, s67
	global_load_lds_dwordx4 v[152:153], off
	s_mov_b32 m0, s2
	v_lshl_add_u64 v[152:153], s[0:1], 0, v[146:147]
	global_load_lds_dwordx4 v[152:153], off
	s_add_i32 m0, s2, 0x2000
	v_lshl_add_u64 v[152:153], s[0:1], 0, v[144:145]
	global_load_lds_dwordx4 v[152:153], off
	s_mov_b32 m0, s79
	v_lshl_add_u64 v[152:153], v[202:203], 0, s[10:11]
	global_load_lds_dwordx4 v[152:153], off
	s_mov_b32 m0, s80
	v_lshl_add_u64 v[152:153], v[218:219], 0, s[10:11]
	global_load_lds_dwordx4 v[152:153], off
	s_waitcnt vmcnt(8) lgkmcnt(0)
	s_setprio 1
	s_barrier
	v_mfma_f32_16x16x32_bf16 v[60:63], v[128:131], v[178:181], v[60:63]
	v_mfma_f32_16x16x32_bf16 v[56:59], v[136:139], v[178:181], v[56:59]
	v_mfma_f32_16x16x32_bf16 v[48:51], v[128:131], v[186:189], v[48:51]
	v_mfma_f32_16x16x32_bf16 v[44:47], v[136:139], v[186:189], v[44:47]
	v_mfma_f32_16x16x32_bf16 v[32:35], v[128:131], v[194:197], v[32:35]
	v_mfma_f32_16x16x32_bf16 v[28:31], v[136:139], v[194:197], v[28:31]
	v_mfma_f32_16x16x32_bf16 v[16:19], v[128:131], v[210:213], v[16:19]
	v_mfma_f32_16x16x32_bf16 v[12:15], v[136:139], v[210:213], v[12:15]
	v_mfma_f32_16x16x32_bf16 v[60:63], v[132:135], v[182:185], v[60:63]
	v_mfma_f32_16x16x32_bf16 v[56:59], v[140:143], v[182:185], v[56:59]
	v_mfma_f32_16x16x32_bf16 v[48:51], v[132:135], v[190:193], v[48:51]
	v_mfma_f32_16x16x32_bf16 v[44:47], v[140:143], v[190:193], v[44:47]
	v_mfma_f32_16x16x32_bf16 v[32:35], v[132:135], v[206:209], v[32:35]
	v_mfma_f32_16x16x32_bf16 v[28:31], v[140:143], v[206:209], v[28:31]
	v_mfma_f32_16x16x32_bf16 v[16:19], v[132:135], v[214:217], v[16:19]
	v_mfma_f32_16x16x32_bf16 v[12:15], v[140:143], v[214:217], v[12:15]
	v_mfma_f32_16x16x32_bf16 v[52:55], v[160:163], v[178:181], v[52:55]
	v_mfma_f32_16x16x32_bf16 v[40:43], v[168:171], v[178:181], v[40:43]
	v_mfma_f32_16x16x32_bf16 v[36:39], v[160:163], v[186:189], v[36:39]
	v_mfma_f32_16x16x32_bf16 v[24:27], v[168:171], v[186:189], v[24:27]
	v_mfma_f32_16x16x32_bf16 v[20:23], v[160:163], v[194:197], v[20:23]
	v_mfma_f32_16x16x32_bf16 v[8:11], v[168:171], v[194:197], v[8:11]
	v_mfma_f32_16x16x32_bf16 v[4:7], v[160:163], v[210:213], v[4:7]
	v_mfma_f32_16x16x32_bf16 v[0:3], v[168:171], v[210:213], v[0:3]
	v_mfma_f32_16x16x32_bf16 v[52:55], v[164:167], v[182:185], v[52:55]
	v_mfma_f32_16x16x32_bf16 v[40:43], v[172:175], v[182:185], v[40:43]
	v_mfma_f32_16x16x32_bf16 v[36:39], v[164:167], v[190:193], v[36:39]
	v_mfma_f32_16x16x32_bf16 v[24:27], v[172:175], v[190:193], v[24:27]
	v_mfma_f32_16x16x32_bf16 v[20:23], v[164:167], v[206:209], v[20:23]
	v_mfma_f32_16x16x32_bf16 v[8:11], v[172:175], v[206:209], v[8:11]
	v_mfma_f32_16x16x32_bf16 v[4:7], v[164:167], v[214:217], v[4:7]
	v_mfma_f32_16x16x32_bf16 v[0:3], v[172:175], v[214:217], v[0:3]
	s_setprio 0
	s_barrier
	s_add_i32 s87, s87, 2
	s_add_u32 s58, s58, 0x100
	s_addc_u32 s59, s59, 0
	s_add_u32 s65, s65, 0x100
	s_addc_u32 s86, s86, 0
	s_cmp_gt_u32 s87, 61
	s_cbranch_scc0 .LBB0_1037
	s_and_b64 vcc, exec, s[14:15]
	s_cbranch_vccz .LBB0_1040
	s_barrier

.LBB0_1107:
	ds_read_b128 v[128:131], v203
	ds_read_b128 v[132:135], v203 offset:1024
	ds_read_b128 v[136:139], v203 offset:2048
	ds_read_b128 v[140:143], v203 offset:3072
	ds_read_b128 v[144:147], v204
	ds_read_b128 v[148:151], v204 offset:1024
	ds_read_b128 v[152:155], v204 offset:2048
	ds_read_b128 v[156:159], v204 offset:3072
	ds_read_b128 v[160:163], v205
	ds_read_b128 v[164:167], v205 offset:1024
	ds_read_b128 v[168:171], v205 offset:2048
	ds_read_b128 v[172:175], v205 offset:3072
	ds_read_b128 v[190:193], v205 offset:4096
	ds_read_b128 v[194:197], v205 offset:5120
	ds_read_b128 v[206:209], v205 offset:6144
	ds_read_b128 v[210:213], v205 offset:7168
	s_add_u32 s0, s4, 0xfff80080
	s_addc_u32 s1, s5, -1
	s_cmp_eq_u32 s96, 28
	s_cselect_b32 s9, s13, s1
	s_cselect_b32 s8, s15, s0
	s_cselect_b32 s7, s37, s11
	s_cselect_b32 s6, s63, s10
	s_add_i32 m0, s77, 0xc000
	v_lshl_add_u64 v[198:199], s[4:5], 0, v[186:187]
	global_load_lds_dwordx4 v[198:199], off
	s_add_i32 m0, s77, 0xe000
	v_lshl_add_u64 v[198:199], s[4:5], 0, v[188:189]
	global_load_lds_dwordx4 v[198:199], off
	s_waitcnt vmcnt(8) lgkmcnt(0)
	s_setprio 1
	s_barrier
	v_mfma_f32_16x16x32_bf16 v[124:127], v[128:131], v[160:163], v[124:127]
	v_mfma_f32_16x16x32_bf16 v[56:59], v[136:139], v[160:163], v[56:59]
	v_mfma_f32_16x16x32_bf16 v[116:119], v[128:131], v[168:171], v[116:119]
	v_mfma_f32_16x16x32_bf16 v[52:55], v[136:139], v[168:171], v[52:55]
	v_mfma_f32_16x16x32_bf16 v[108:111], v[128:131], v[190:193], v[108:111]
	v_mfma_f32_16x16x32_bf16 v[44:47], v[136:139], v[190:193], v[44:47]
	v_mfma_f32_16x16x32_bf16 v[104:107], v[128:131], v[206:209], v[104:107]
	v_mfma_f32_16x16x32_bf16 v[32:35], v[136:139], v[206:209], v[32:35]
	v_mfma_f32_16x16x32_bf16 v[124:127], v[132:135], v[164:167], v[124:127]
	v_mfma_f32_16x16x32_bf16 v[56:59], v[140:143], v[164:167], v[56:59]
	v_mfma_f32_16x16x32_bf16 v[116:119], v[132:135], v[172:175], v[116:119]
	v_mfma_f32_16x16x32_bf16 v[52:55], v[140:143], v[172:175], v[52:55]
	v_mfma_f32_16x16x32_bf16 v[108:111], v[132:135], v[194:197], v[108:111]
	v_mfma_f32_16x16x32_bf16 v[44:47], v[140:143], v[194:197], v[44:47]
	v_mfma_f32_16x16x32_bf16 v[104:107], v[132:135], v[210:213], v[104:107]
	v_mfma_f32_16x16x32_bf16 v[32:35], v[140:143], v[210:213], v[32:35]
	v_mfma_f32_16x16x32_bf16 v[120:123], v[144:147], v[160:163], v[120:123]
	v_mfma_f32_16x16x32_bf16 v[60:63], v[152:155], v[160:163], v[60:63]
	v_mfma_f32_16x16x32_bf16 v[112:115], v[144:147], v[168:171], v[112:115]
	v_mfma_f32_16x16x32_bf16 v[48:51], v[152:155], v[168:171], v[48:51]
	v_mfma_f32_16x16x32_bf16 v[100:103], v[144:147], v[190:193], v[100:103]
	v_mfma_f32_16x16x32_bf16 v[40:43], v[152:155], v[190:193], v[40:43]
	v_mfma_f32_16x16x32_bf16 v[96:99], v[144:147], v[206:209], v[96:99]
	v_mfma_f32_16x16x32_bf16 v[36:39], v[152:155], v[206:209], v[36:39]
	v_mfma_f32_16x16x32_bf16 v[120:123], v[148:151], v[164:167], v[120:123]
	v_mfma_f32_16x16x32_bf16 v[60:63], v[156:159], v[164:167], v[60:63]
	v_mfma_f32_16x16x32_bf16 v[112:115], v[148:151], v[172:175], v[112:115]
	v_mfma_f32_16x16x32_bf16 v[48:51], v[156:159], v[172:175], v[48:51]
	v_mfma_f32_16x16x32_bf16 v[100:103], v[148:151], v[194:197], v[100:103]
	v_mfma_f32_16x16x32_bf16 v[40:43], v[156:159], v[194:197], v[40:43]
	v_mfma_f32_16x16x32_bf16 v[96:99], v[148:151], v[210:213], v[96:99]
	v_mfma_f32_16x16x32_bf16 v[36:39], v[156:159], v[210:213], v[36:39]
	s_setprio 0
	s_barrier
	ds_read_b128 v[160:163], v205 offset:16384
	ds_read_b128 v[164:167], v205 offset:17408
	ds_read_b128 v[168:171], v205 offset:18432
	ds_read_b128 v[172:175], v205 offset:19456
	ds_read_b128 v[190:193], v205 offset:20480
	ds_read_b128 v[194:197], v205 offset:21504
	ds_read_b128 v[206:209], v205 offset:22528
	ds_read_b128 v[210:213], v205 offset:23552
	s_add_i32 s0, s92, s76
	s_mov_b32 m0, s0
	v_lshl_add_u64 v[198:199], s[6:7], 0, v[180:181]
	global_load_lds_dwordx4 v[198:199], off
	s_add_i32 m0, s0, 0x2000
	s_add_u32 s0, s6, 0x80000
	v_lshl_add_u64 v[214:215], s[6:7], 0, v[184:185]
	s_addc_u32 s1, s7, 0
	s_add_i32 s2, s93, s76
	global_load_lds_dwordx4 v[214:215], off
	v_lshl_add_u64 v[216:217], s[0:1], 0, v[180:181]
	s_mov_b32 m0, s2
	v_lshl_add_u64 v[218:219], s[8:9], 0, v[182:183]
	global_load_lds_dwordx4 v[216:217], off
	s_add_i32 m0, s2, 0x2000
	v_lshl_add_u64 v[216:217], s[0:1], 0, v[184:185]
	global_load_lds_dwordx4 v[216:217], off
	s_mov_b32 m0, s77
	v_lshl_add_u64 v[216:217], s[8:9], 0, v[178:179]
	global_load_lds_dwordx4 v[216:217], off
	s_mov_b32 m0, s78
	s_nop 0
	global_load_lds_dwordx4 v[218:219], off
	s_waitcnt vmcnt(8) lgkmcnt(0)
	s_setprio 1
	s_barrier
	v_mfma_f32_16x16x32_bf16 v[92:95], v[128:131], v[160:163], v[92:95]
	v_mfma_f32_16x16x32_bf16 v[24:27], v[136:139], v[160:163], v[24:27]
	v_mfma_f32_16x16x32_bf16 v[84:87], v[128:131], v[168:171], v[84:87]
	v_mfma_f32_16x16x32_bf16 v[20:23], v[136:139], v[168:171], v[20:23]
	v_mfma_f32_16x16x32_bf16 v[76:79], v[128:131], v[190:193], v[76:79]
	v_mfma_f32_16x16x32_bf16 v[12:15], v[136:139], v[190:193], v[12:15]
	v_mfma_f32_16x16x32_bf16 v[72:75], v[128:131], v[206:209], v[72:75]
	v_mfma_f32_16x16x32_bf16 v[0:3], v[136:139], v[206:209], v[0:3]
	v_mfma_f32_16x16x32_bf16 v[92:95], v[132:135], v[164:167], v[92:95]
	v_mfma_f32_16x16x32_bf16 v[24:27], v[140:143], v[164:167], v[24:27]
	v_mfma_f32_16x16x32_bf16 v[84:87], v[132:135], v[172:175], v[84:87]
	v_mfma_f32_16x16x32_bf16 v[20:23], v[140:143], v[172:175], v[20:23]
	v_mfma_f32_16x16x32_bf16 v[76:79], v[132:135], v[194:197], v[76:79]
	v_mfma_f32_16x16x32_bf16 v[12:15], v[140:143], v[194:197], v[12:15]
	v_mfma_f32_16x16x32_bf16 v[72:75], v[132:135], v[210:213], v[72:75]
	v_mfma_f32_16x16x32_bf16 v[0:3], v[140:143], v[210:213], v[0:3]
	v_mfma_f32_16x16x32_bf16 v[88:91], v[144:147], v[160:163], v[88:91]
	v_mfma_f32_16x16x32_bf16 v[28:31], v[152:155], v[160:163], v[28:31]
	v_mfma_f32_16x16x32_bf16 v[80:83], v[144:147], v[168:171], v[80:83]
	v_mfma_f32_16x16x32_bf16 v[16:19], v[152:155], v[168:171], v[16:19]
	v_mfma_f32_16x16x32_bf16 v[68:71], v[144:147], v[190:193], v[68:71]
	v_mfma_f32_16x16x32_bf16 v[8:11], v[152:155], v[190:193], v[8:11]
	v_mfma_f32_16x16x32_bf16 v[64:67], v[144:147], v[206:209], v[64:67]
	v_mfma_f32_16x16x32_bf16 v[4:7], v[152:155], v[206:209], v[4:7]
	v_mfma_f32_16x16x32_bf16 v[88:91], v[148:151], v[164:167], v[88:91]
	v_mfma_f32_16x16x32_bf16 v[28:31], v[156:159], v[164:167], v[28:31]
	v_mfma_f32_16x16x32_bf16 v[80:83], v[148:151], v[172:175], v[80:83]
	v_mfma_f32_16x16x32_bf16 v[16:19], v[156:159], v[172:175], v[16:19]
	v_mfma_f32_16x16x32_bf16 v[68:71], v[148:151], v[194:197], v[68:71]
	v_mfma_f32_16x16x32_bf16 v[8:11], v[156:159], v[194:197], v[8:11]
	v_mfma_f32_16x16x32_bf16 v[64:67], v[148:151], v[210:213], v[64:67]
	v_mfma_f32_16x16x32_bf16 v[4:7], v[156:159], v[210:213], v[4:7]
	s_setprio 0
	s_barrier
	ds_read_b128 v[160:163], v205 offset:32768
	ds_read_b128 v[164:167], v205 offset:33792
	ds_read_b128 v[168:171], v205 offset:34816
	ds_read_b128 v[172:175], v205 offset:35840
	ds_read_b128 v[190:193], v205 offset:36864
	ds_read_b128 v[194:197], v205 offset:37888
	ds_read_b128 v[206:209], v205 offset:38912
	ds_read_b128 v[210:213], v205 offset:39936
	s_add_i32 s2, 0, 0x18000
	s_add_i32 s38, 0, 0x1c000
	v_add_u32_e32 v140, s2, v202
	v_add_u32_e32 v156, s38, v202
	ds_read_b128 v[128:131], v140
	ds_read_b128 v[132:135], v140 offset:1024
	ds_read_b128 v[136:139], v140 offset:2048
	ds_read_b128 v[140:143], v140 offset:3072
	ds_read_b128 v[144:147], v156
	ds_read_b128 v[148:151], v156 offset:1024
	ds_read_b128 v[152:155], v156 offset:2048
	ds_read_b128 v[156:159], v156 offset:3072
	s_add_u32 s0, s8, 0x80000
	s_addc_u32 s1, s9, 0
	s_mov_b32 m0, s79
	v_lshl_add_u64 v[220:221], s[0:1], 0, v[178:179]
	global_load_lds_dwordx4 v[220:221], off
	s_mov_b32 m0, s80
	v_lshl_add_u64 v[220:221], s[0:1], 0, v[182:183]
	global_load_lds_dwordx4 v[220:221], off
	s_waitcnt vmcnt(8) lgkmcnt(0)
	s_setprio 1
	s_barrier
	v_mfma_f32_16x16x32_bf16 v[124:127], v[128:131], v[160:163], v[124:127]
	v_mfma_f32_16x16x32_bf16 v[56:59], v[136:139], v[160:163], v[56:59]
	v_mfma_f32_16x16x32_bf16 v[116:119], v[128:131], v[168:171], v[116:119]
	v_mfma_f32_16x16x32_bf16 v[52:55], v[136:139], v[168:171], v[52:55]
	v_mfma_f32_16x16x32_bf16 v[108:111], v[128:131], v[190:193], v[108:111]
	v_mfma_f32_16x16x32_bf16 v[44:47], v[136:139], v[190:193], v[44:47]
	v_mfma_f32_16x16x32_bf16 v[104:107], v[128:131], v[206:209], v[104:107]
	v_mfma_f32_16x16x32_bf16 v[32:35], v[136:139], v[206:209], v[32:35]
	v_mfma_f32_16x16x32_bf16 v[124:127], v[132:135], v[164:167], v[124:127]
	v_mfma_f32_16x16x32_bf16 v[56:59], v[140:143], v[164:167], v[56:59]
	v_mfma_f32_16x16x32_bf16 v[116:119], v[132:135], v[172:175], v[116:119]
	v_mfma_f32_16x16x32_bf16 v[52:55], v[140:143], v[172:175], v[52:55]
	v_mfma_f32_16x16x32_bf16 v[108:111], v[132:135], v[194:197], v[108:111]
	v_mfma_f32_16x16x32_bf16 v[44:47], v[140:143], v[194:197], v[44:47]
	v_mfma_f32_16x16x32_bf16 v[104:107], v[132:135], v[210:213], v[104:107]
	v_mfma_f32_16x16x32_bf16 v[32:35], v[140:143], v[210:213], v[32:35]
	v_mfma_f32_16x16x32_bf16 v[120:123], v[144:147], v[160:163], v[120:123]
	v_mfma_f32_16x16x32_bf16 v[60:63], v[152:155], v[160:163], v[60:63]
	v_mfma_f32_16x16x32_bf16 v[112:115], v[144:147], v[168:171], v[112:115]
	v_mfma_f32_16x16x32_bf16 v[48:51], v[152:155], v[168:171], v[48:51]
	v_mfma_f32_16x16x32_bf16 v[100:103], v[144:147], v[190:193], v[100:103]
	v_mfma_f32_16x16x32_bf16 v[40:43], v[152:155], v[190:193], v[40:43]
	v_mfma_f32_16x16x32_bf16 v[96:99], v[144:147], v[206:209], v[96:99]
	v_mfma_f32_16x16x32_bf16 v[36:39], v[152:155], v[206:209], v[36:39]
	v_mfma_f32_16x16x32_bf16 v[120:123], v[148:151], v[164:167], v[120:123]
	v_mfma_f32_16x16x32_bf16 v[60:63], v[156:159], v[164:167], v[60:63]
	v_mfma_f32_16x16x32_bf16 v[112:115], v[148:151], v[172:175], v[112:115]
	v_mfma_f32_16x16x32_bf16 v[48:51], v[156:159], v[172:175], v[48:51]
	v_mfma_f32_16x16x32_bf16 v[100:103], v[148:151], v[194:197], v[100:103]
	v_mfma_f32_16x16x32_bf16 v[40:43], v[156:159], v[194:197], v[40:43]
	v_mfma_f32_16x16x32_bf16 v[96:99], v[148:151], v[210:213], v[96:99]
	v_mfma_f32_16x16x32_bf16 v[36:39], v[156:159], v[210:213], v[36:39]
	s_setprio 0
	s_barrier
	ds_read_b128 v[160:163], v205 offset:49152
	ds_read_b128 v[164:167], v205 offset:50176
	ds_read_b128 v[168:171], v205 offset:51200
	ds_read_b128 v[172:175], v205 offset:52224
	ds_read_b128 v[190:193], v205 offset:53248
	ds_read_b128 v[194:197], v205 offset:54272
	ds_read_b128 v[206:209], v205 offset:55296
	ds_read_b128 v[210:213], v205 offset:56320
	s_add_i32 s0, s2, s76
	s_mov_b32 m0, s0
	v_lshl_add_u64 v[198:199], v[198:199], 0, s[24:25]
	global_load_lds_dwordx4 v[198:199], off
	s_add_i32 m0, s0, 0x2000
	s_add_u32 s0, s6, 0x80080
	v_lshl_add_u64 v[198:199], v[214:215], 0, s[24:25]
	s_addc_u32 s1, s7, 0
	s_add_i32 s2, s38, s76
	global_load_lds_dwordx4 v[198:199], off
	s_mov_b32 m0, s2
	v_lshl_add_u64 v[198:199], s[0:1], 0, v[180:181]
	global_load_lds_dwordx4 v[198:199], off
	s_add_i32 m0, s2, 0x2000
	v_lshl_add_u64 v[198:199], s[0:1], 0, v[184:185]
	global_load_lds_dwordx4 v[198:199], off
	s_mov_b32 m0, s86
	v_lshl_add_u64 v[198:199], v[216:217], 0, s[24:25]
	global_load_lds_dwordx4 v[198:199], off
	s_mov_b32 m0, s87
	v_lshl_add_u64 v[198:199], v[218:219], 0, s[24:25]
	global_load_lds_dwordx4 v[198:199], off
	s_waitcnt vmcnt(8) lgkmcnt(0)
	s_setprio 1
	s_barrier
	v_mfma_f32_16x16x32_bf16 v[92:95], v[128:131], v[160:163], v[92:95]
	v_mfma_f32_16x16x32_bf16 v[24:27], v[136:139], v[160:163], v[24:27]
	v_mfma_f32_16x16x32_bf16 v[84:87], v[128:131], v[168:171], v[84:87]
	v_mfma_f32_16x16x32_bf16 v[20:23], v[136:139], v[168:171], v[20:23]
	v_mfma_f32_16x16x32_bf16 v[76:79], v[128:131], v[190:193], v[76:79]
	v_mfma_f32_16x16x32_bf16 v[12:15], v[136:139], v[190:193], v[12:15]
	v_mfma_f32_16x16x32_bf16 v[72:75], v[128:131], v[206:209], v[72:75]
	v_mfma_f32_16x16x32_bf16 v[0:3], v[136:139], v[206:209], v[0:3]
	v_mfma_f32_16x16x32_bf16 v[92:95], v[132:135], v[164:167], v[92:95]
	v_mfma_f32_16x16x32_bf16 v[24:27], v[140:143], v[164:167], v[24:27]
	v_mfma_f32_16x16x32_bf16 v[84:87], v[132:135], v[172:175], v[84:87]
	v_mfma_f32_16x16x32_bf16 v[20:23], v[140:143], v[172:175], v[20:23]
	v_mfma_f32_16x16x32_bf16 v[76:79], v[132:135], v[194:197], v[76:79]
	v_mfma_f32_16x16x32_bf16 v[12:15], v[140:143], v[194:197], v[12:15]
	v_mfma_f32_16x16x32_bf16 v[72:75], v[132:135], v[210:213], v[72:75]
	v_mfma_f32_16x16x32_bf16 v[0:3], v[140:143], v[210:213], v[0:3]
	v_mfma_f32_16x16x32_bf16 v[88:91], v[144:147], v[160:163], v[88:91]
	v_mfma_f32_16x16x32_bf16 v[28:31], v[152:155], v[160:163], v[28:31]
	v_mfma_f32_16x16x32_bf16 v[80:83], v[144:147], v[168:171], v[80:83]
	v_mfma_f32_16x16x32_bf16 v[16:19], v[152:155], v[168:171], v[16:19]
	v_mfma_f32_16x16x32_bf16 v[68:71], v[144:147], v[190:193], v[68:71]
	v_mfma_f32_16x16x32_bf16 v[8:11], v[152:155], v[190:193], v[8:11]
	v_mfma_f32_16x16x32_bf16 v[64:67], v[144:147], v[206:209], v[64:67]
	v_mfma_f32_16x16x32_bf16 v[4:7], v[152:155], v[206:209], v[4:7]
	v_mfma_f32_16x16x32_bf16 v[88:91], v[148:151], v[164:167], v[88:91]
	v_mfma_f32_16x16x32_bf16 v[28:31], v[156:159], v[164:167], v[28:31]
	v_mfma_f32_16x16x32_bf16 v[80:83], v[148:151], v[172:175], v[80:83]
	v_mfma_f32_16x16x32_bf16 v[16:19], v[156:159], v[172:175], v[16:19]
	v_mfma_f32_16x16x32_bf16 v[68:71], v[148:151], v[194:197], v[68:71]
	v_mfma_f32_16x16x32_bf16 v[8:11], v[156:159], v[194:197], v[8:11]
	v_mfma_f32_16x16x32_bf16 v[64:67], v[148:151], v[210:213], v[64:67]
	v_mfma_f32_16x16x32_bf16 v[4:7], v[156:159], v[210:213], v[4:7]
	s_setprio 0
	s_barrier
	s_add_i32 s96, s96, 2
	s_add_u32 s4, s4, 0x100
	s_addc_u32 s5, s5, 0
	s_add_u32 s10, s10, 0x100
	s_addc_u32 s11, s11, 0
	s_cmp_gt_u32 s96, 29
	s_cbranch_scc0 .LBB0_1107
	s_and_b64 vcc, exec, s[26:27]
	s_cbranch_vccz .LBB0_1110
	s_barrier

.LBB0_1249:
	ds_read_b128 v[128:131], v157
	ds_read_b128 v[132:135], v157 offset:1024
	ds_read_b128 v[136:139], v157 offset:2048
	ds_read_b128 v[140:143], v157 offset:3072
	ds_read_b128 v[160:163], v158
	ds_read_b128 v[164:167], v158 offset:1024
	ds_read_b128 v[168:171], v158 offset:2048
	ds_read_b128 v[172:175], v158 offset:3072
	ds_read_b128 v[176:179], v159
	ds_read_b128 v[180:183], v159 offset:1024
	ds_read_b128 v[184:187], v159 offset:2048
	ds_read_b128 v[188:191], v159 offset:3072
	ds_read_b128 v[192:195], v159 offset:4096
	ds_read_b128 v[196:199], v159 offset:5120
	ds_read_b128 v[200:203], v159 offset:6144
	ds_read_b128 v[204:207], v159 offset:7168
	s_add_u32 s38, s36, 0x100
	s_addc_u32 s39, s37, 0
	s_cmpk_eq_i32 s74, 0x54
	s_cselect_b32 s45, s6, s39
	s_cselect_b32 s44, s35, s38
	s_cselect_b32 s43, s70, s73
	s_cselect_b32 s42, s71, s72
	s_add_i32 m0, s52, 0xc000
	v_lshl_add_u64 v[152:153], s[36:37], 0, v[148:149]
	global_load_lds_dwordx4 v[152:153], off
	s_add_i32 m0, s52, 0xe000
	v_lshl_add_u64 v[152:153], s[36:37], 0, v[150:151]
	global_load_lds_dwordx4 v[152:153], off
	s_waitcnt vmcnt(8) lgkmcnt(0)
	s_setprio 1
	s_barrier
	v_mfma_f32_16x16x32_bf16 v[124:127], v[128:131], v[176:179], v[124:127]
	v_mfma_f32_16x16x32_bf16 v[120:123], v[136:139], v[176:179], v[120:123]
	v_mfma_f32_16x16x32_bf16 v[112:115], v[128:131], v[184:187], v[112:115]
	v_mfma_f32_16x16x32_bf16 v[108:111], v[136:139], v[184:187], v[108:111]
	v_mfma_f32_16x16x32_bf16 v[96:99], v[128:131], v[192:195], v[96:99]
	v_mfma_f32_16x16x32_bf16 v[92:95], v[136:139], v[192:195], v[92:95]
	v_mfma_f32_16x16x32_bf16 v[80:83], v[128:131], v[200:203], v[80:83]
	v_mfma_f32_16x16x32_bf16 v[76:79], v[136:139], v[200:203], v[76:79]
	v_mfma_f32_16x16x32_bf16 v[124:127], v[132:135], v[180:183], v[124:127]
	v_mfma_f32_16x16x32_bf16 v[120:123], v[140:143], v[180:183], v[120:123]
	v_mfma_f32_16x16x32_bf16 v[112:115], v[132:135], v[188:191], v[112:115]
	v_mfma_f32_16x16x32_bf16 v[108:111], v[140:143], v[188:191], v[108:111]
	v_mfma_f32_16x16x32_bf16 v[96:99], v[132:135], v[196:199], v[96:99]
	v_mfma_f32_16x16x32_bf16 v[92:95], v[140:143], v[196:199], v[92:95]
	v_mfma_f32_16x16x32_bf16 v[80:83], v[132:135], v[204:207], v[80:83]
	v_mfma_f32_16x16x32_bf16 v[76:79], v[140:143], v[204:207], v[76:79]
	v_mfma_f32_16x16x32_bf16 v[116:119], v[160:163], v[176:179], v[116:119]
	v_mfma_f32_16x16x32_bf16 v[104:107], v[168:171], v[176:179], v[104:107]
	v_mfma_f32_16x16x32_bf16 v[100:103], v[160:163], v[184:187], v[100:103]
	v_mfma_f32_16x16x32_bf16 v[88:91], v[168:171], v[184:187], v[88:91]
	v_mfma_f32_16x16x32_bf16 v[84:87], v[160:163], v[192:195], v[84:87]
	v_mfma_f32_16x16x32_bf16 v[72:75], v[168:171], v[192:195], v[72:75]
	v_mfma_f32_16x16x32_bf16 v[68:71], v[160:163], v[200:203], v[68:71]
	v_mfma_f32_16x16x32_bf16 v[64:67], v[168:171], v[200:203], v[64:67]
	v_mfma_f32_16x16x32_bf16 v[116:119], v[164:167], v[180:183], v[116:119]
	v_mfma_f32_16x16x32_bf16 v[104:107], v[172:175], v[180:183], v[104:107]
	v_mfma_f32_16x16x32_bf16 v[100:103], v[164:167], v[188:191], v[100:103]
	v_mfma_f32_16x16x32_bf16 v[88:91], v[172:175], v[188:191], v[88:91]
	v_mfma_f32_16x16x32_bf16 v[84:87], v[164:167], v[196:199], v[84:87]
	v_mfma_f32_16x16x32_bf16 v[72:75], v[172:175], v[196:199], v[72:75]
	v_mfma_f32_16x16x32_bf16 v[68:71], v[164:167], v[204:207], v[68:71]
	v_mfma_f32_16x16x32_bf16 v[64:67], v[172:175], v[204:207], v[64:67]
	s_setprio 0
	s_barrier
	ds_read_b128 v[176:179], v159 offset:16384
	ds_read_b128 v[180:183], v159 offset:17408
	ds_read_b128 v[184:187], v159 offset:18432
	ds_read_b128 v[188:191], v159 offset:19456
	ds_read_b128 v[192:195], v159 offset:20480
	ds_read_b128 v[196:199], v159 offset:21504
	ds_read_b128 v[200:203], v159 offset:22528
	ds_read_b128 v[204:207], v159 offset:23552
	s_add_i32 s36, s64, s51
	s_mov_b32 m0, s36
	v_lshl_add_u64 v[152:153], s[42:43], 0, v[146:147]
	global_load_lds_dwordx4 v[152:153], off
	s_add_i32 m0, s36, 0x2000
	s_add_u32 s36, s42, 0x160000
	v_lshl_add_u64 v[208:209], s[42:43], 0, v[144:145]
	s_addc_u32 s37, s43, 0
	s_add_i32 s75, s65, s51
	global_load_lds_dwordx4 v[208:209], off
	v_lshl_add_u64 v[210:211], s[36:37], 0, v[146:147]
	s_mov_b32 m0, s75
	v_lshl_add_u64 v[212:213], s[44:45], 0, v[144:145]
	global_load_lds_dwordx4 v[210:211], off
	s_add_i32 m0, s75, 0x2000
	v_lshl_add_u64 v[210:211], s[36:37], 0, v[144:145]
	global_load_lds_dwordx4 v[210:211], off
	s_mov_b32 m0, s52
	v_lshl_add_u64 v[210:211], s[44:45], 0, v[146:147]
	global_load_lds_dwordx4 v[210:211], off
	s_mov_b32 m0, s53
	s_nop 0
	global_load_lds_dwordx4 v[212:213], off
	s_waitcnt vmcnt(8) lgkmcnt(0)
	s_setprio 1
	s_barrier
	v_mfma_f32_16x16x32_bf16 v[60:63], v[128:131], v[176:179], v[60:63]
	v_mfma_f32_16x16x32_bf16 v[56:59], v[136:139], v[176:179], v[56:59]
	v_mfma_f32_16x16x32_bf16 v[48:51], v[128:131], v[184:187], v[48:51]
	v_mfma_f32_16x16x32_bf16 v[44:47], v[136:139], v[184:187], v[44:47]
	v_mfma_f32_16x16x32_bf16 v[32:35], v[128:131], v[192:195], v[32:35]
	v_mfma_f32_16x16x32_bf16 v[28:31], v[136:139], v[192:195], v[28:31]
	v_mfma_f32_16x16x32_bf16 v[16:19], v[128:131], v[200:203], v[16:19]
	v_mfma_f32_16x16x32_bf16 v[12:15], v[136:139], v[200:203], v[12:15]
	v_mfma_f32_16x16x32_bf16 v[60:63], v[132:135], v[180:183], v[60:63]
	v_mfma_f32_16x16x32_bf16 v[56:59], v[140:143], v[180:183], v[56:59]
	v_mfma_f32_16x16x32_bf16 v[48:51], v[132:135], v[188:191], v[48:51]
	v_mfma_f32_16x16x32_bf16 v[44:47], v[140:143], v[188:191], v[44:47]
	v_mfma_f32_16x16x32_bf16 v[32:35], v[132:135], v[196:199], v[32:35]
	v_mfma_f32_16x16x32_bf16 v[28:31], v[140:143], v[196:199], v[28:31]
	v_mfma_f32_16x16x32_bf16 v[16:19], v[132:135], v[204:207], v[16:19]
	v_mfma_f32_16x16x32_bf16 v[12:15], v[140:143], v[204:207], v[12:15]
	v_mfma_f32_16x16x32_bf16 v[52:55], v[160:163], v[176:179], v[52:55]
	v_mfma_f32_16x16x32_bf16 v[40:43], v[168:171], v[176:179], v[40:43]
	v_mfma_f32_16x16x32_bf16 v[36:39], v[160:163], v[184:187], v[36:39]
	v_mfma_f32_16x16x32_bf16 v[24:27], v[168:171], v[184:187], v[24:27]
	v_mfma_f32_16x16x32_bf16 v[20:23], v[160:163], v[192:195], v[20:23]
	v_mfma_f32_16x16x32_bf16 v[8:11], v[168:171], v[192:195], v[8:11]
	v_mfma_f32_16x16x32_bf16 v[4:7], v[160:163], v[200:203], v[4:7]
	v_mfma_f32_16x16x32_bf16 v[0:3], v[168:171], v[200:203], v[0:3]
	v_mfma_f32_16x16x32_bf16 v[52:55], v[164:167], v[180:183], v[52:55]
	v_mfma_f32_16x16x32_bf16 v[40:43], v[172:175], v[180:183], v[40:43]
	v_mfma_f32_16x16x32_bf16 v[36:39], v[164:167], v[188:191], v[36:39]
	v_mfma_f32_16x16x32_bf16 v[24:27], v[172:175], v[188:191], v[24:27]
	v_mfma_f32_16x16x32_bf16 v[20:23], v[164:167], v[196:199], v[20:23]
	v_mfma_f32_16x16x32_bf16 v[8:11], v[172:175], v[196:199], v[8:11]
	v_mfma_f32_16x16x32_bf16 v[4:7], v[164:167], v[204:207], v[4:7]
	v_mfma_f32_16x16x32_bf16 v[0:3], v[172:175], v[204:207], v[0:3]
	s_setprio 0
	s_barrier
	ds_read_b128 v[176:179], v159 offset:32768
	ds_read_b128 v[180:183], v159 offset:33792
	ds_read_b128 v[184:187], v159 offset:34816
	ds_read_b128 v[188:191], v159 offset:35840
	ds_read_b128 v[192:195], v159 offset:36864
	ds_read_b128 v[196:199], v159 offset:37888
	ds_read_b128 v[200:203], v159 offset:38912
	ds_read_b128 v[204:207], v159 offset:39936
	s_add_i32 s75, 0, 0x18000
	s_add_i32 s76, 0, 0x1c000
	v_add_u32_e32 v140, s75, v156
	v_add_u32_e32 v172, s76, v156
	ds_read_b128 v[128:131], v140
	ds_read_b128 v[132:135], v140 offset:1024
	ds_read_b128 v[136:139], v140 offset:2048
	ds_read_b128 v[140:143], v140 offset:3072
	ds_read_b128 v[160:163], v172
	ds_read_b128 v[164:167], v172 offset:1024
	ds_read_b128 v[168:171], v172 offset:2048
	ds_read_b128 v[172:175], v172 offset:3072
	s_add_u32 s36, s44, 0x160000
	s_addc_u32 s37, s45, 0
	s_mov_b32 m0, s54
	v_lshl_add_u64 v[214:215], s[36:37], 0, v[146:147]
	global_load_lds_dwordx4 v[214:215], off
	s_mov_b32 m0, s55
	v_lshl_add_u64 v[214:215], s[36:37], 0, v[144:145]
	global_load_lds_dwordx4 v[214:215], off
	s_waitcnt vmcnt(8) lgkmcnt(0)
	s_setprio 1
	s_barrier
	v_mfma_f32_16x16x32_bf16 v[124:127], v[128:131], v[176:179], v[124:127]
	v_mfma_f32_16x16x32_bf16 v[120:123], v[136:139], v[176:179], v[120:123]
	v_mfma_f32_16x16x32_bf16 v[112:115], v[128:131], v[184:187], v[112:115]
	v_mfma_f32_16x16x32_bf16 v[108:111], v[136:139], v[184:187], v[108:111]
	v_mfma_f32_16x16x32_bf16 v[96:99], v[128:131], v[192:195], v[96:99]
	v_mfma_f32_16x16x32_bf16 v[92:95], v[136:139], v[192:195], v[92:95]
	v_mfma_f32_16x16x32_bf16 v[80:83], v[128:131], v[200:203], v[80:83]
	v_mfma_f32_16x16x32_bf16 v[76:79], v[136:139], v[200:203], v[76:79]
	v_mfma_f32_16x16x32_bf16 v[124:127], v[132:135], v[180:183], v[124:127]
	v_mfma_f32_16x16x32_bf16 v[120:123], v[140:143], v[180:183], v[120:123]
	v_mfma_f32_16x16x32_bf16 v[112:115], v[132:135], v[188:191], v[112:115]
	v_mfma_f32_16x16x32_bf16 v[108:111], v[140:143], v[188:191], v[108:111]
	v_mfma_f32_16x16x32_bf16 v[96:99], v[132:135], v[196:199], v[96:99]
	v_mfma_f32_16x16x32_bf16 v[92:95], v[140:143], v[196:199], v[92:95]
	v_mfma_f32_16x16x32_bf16 v[80:83], v[132:135], v[204:207], v[80:83]
	v_mfma_f32_16x16x32_bf16 v[76:79], v[140:143], v[204:207], v[76:79]
	v_mfma_f32_16x16x32_bf16 v[116:119], v[160:163], v[176:179], v[116:119]
	v_mfma_f32_16x16x32_bf16 v[104:107], v[168:171], v[176:179], v[104:107]
	v_mfma_f32_16x16x32_bf16 v[100:103], v[160:163], v[184:187], v[100:103]
	v_mfma_f32_16x16x32_bf16 v[88:91], v[168:171], v[184:187], v[88:91]
	v_mfma_f32_16x16x32_bf16 v[84:87], v[160:163], v[192:195], v[84:87]
	v_mfma_f32_16x16x32_bf16 v[72:75], v[168:171], v[192:195], v[72:75]
	v_mfma_f32_16x16x32_bf16 v[68:71], v[160:163], v[200:203], v[68:71]
	v_mfma_f32_16x16x32_bf16 v[64:67], v[168:171], v[200:203], v[64:67]
	v_mfma_f32_16x16x32_bf16 v[116:119], v[164:167], v[180:183], v[116:119]
	v_mfma_f32_16x16x32_bf16 v[104:107], v[172:175], v[180:183], v[104:107]
	v_mfma_f32_16x16x32_bf16 v[100:103], v[164:167], v[188:191], v[100:103]
	v_mfma_f32_16x16x32_bf16 v[88:91], v[172:175], v[188:191], v[88:91]
	v_mfma_f32_16x16x32_bf16 v[84:87], v[164:167], v[196:199], v[84:87]
	v_mfma_f32_16x16x32_bf16 v[72:75], v[172:175], v[196:199], v[72:75]
	v_mfma_f32_16x16x32_bf16 v[68:71], v[164:167], v[204:207], v[68:71]
	v_mfma_f32_16x16x32_bf16 v[64:67], v[172:175], v[204:207], v[64:67]
	s_setprio 0
	s_barrier
	ds_read_b128 v[176:179], v159 offset:49152
	ds_read_b128 v[180:183], v159 offset:50176
	ds_read_b128 v[184:187], v159 offset:51200
	ds_read_b128 v[188:191], v159 offset:52224
	ds_read_b128 v[192:195], v159 offset:53248
	ds_read_b128 v[196:199], v159 offset:54272
	ds_read_b128 v[200:203], v159 offset:55296
	ds_read_b128 v[204:207], v159 offset:56320
	s_add_i32 s36, s75, s51
	s_mov_b32 m0, s36
	v_lshl_add_u64 v[152:153], v[152:153], 0, s[4:5]
	global_load_lds_dwordx4 v[152:153], off
	s_add_i32 m0, s36, 0x2000
	s_add_u32 s36, s42, 0x160080
	v_lshl_add_u64 v[152:153], v[208:209], 0, s[4:5]
	s_addc_u32 s37, s43, 0
	s_add_i32 s42, s76, s51
	global_load_lds_dwordx4 v[152:153], off
	s_mov_b32 m0, s42
	v_lshl_add_u64 v[152:153], s[36:37], 0, v[146:147]
	global_load_lds_dwordx4 v[152:153], off
	s_add_i32 m0, s42, 0x2000
	v_lshl_add_u64 v[152:153], s[36:37], 0, v[144:145]
	global_load_lds_dwordx4 v[152:153], off
	s_mov_b32 m0, s62
	v_lshl_add_u64 v[152:153], v[210:211], 0, s[4:5]
	global_load_lds_dwordx4 v[152:153], off
	s_mov_b32 m0, s63
	v_lshl_add_u64 v[152:153], v[212:213], 0, s[4:5]
	global_load_lds_dwordx4 v[152:153], off
	s_waitcnt vmcnt(8) lgkmcnt(0)
	s_setprio 1
	s_barrier
	v_mfma_f32_16x16x32_bf16 v[60:63], v[128:131], v[176:179], v[60:63]
	v_mfma_f32_16x16x32_bf16 v[56:59], v[136:139], v[176:179], v[56:59]
	v_mfma_f32_16x16x32_bf16 v[48:51], v[128:131], v[184:187], v[48:51]
	v_mfma_f32_16x16x32_bf16 v[44:47], v[136:139], v[184:187], v[44:47]
	v_mfma_f32_16x16x32_bf16 v[32:35], v[128:131], v[192:195], v[32:35]
	v_mfma_f32_16x16x32_bf16 v[28:31], v[136:139], v[192:195], v[28:31]
	v_mfma_f32_16x16x32_bf16 v[16:19], v[128:131], v[200:203], v[16:19]
	v_mfma_f32_16x16x32_bf16 v[12:15], v[136:139], v[200:203], v[12:15]
	v_mfma_f32_16x16x32_bf16 v[60:63], v[132:135], v[180:183], v[60:63]
	v_mfma_f32_16x16x32_bf16 v[56:59], v[140:143], v[180:183], v[56:59]
	v_mfma_f32_16x16x32_bf16 v[48:51], v[132:135], v[188:191], v[48:51]
	v_mfma_f32_16x16x32_bf16 v[44:47], v[140:143], v[188:191], v[44:47]
	v_mfma_f32_16x16x32_bf16 v[32:35], v[132:135], v[196:199], v[32:35]
	v_mfma_f32_16x16x32_bf16 v[28:31], v[140:143], v[196:199], v[28:31]
	v_mfma_f32_16x16x32_bf16 v[16:19], v[132:135], v[204:207], v[16:19]
	v_mfma_f32_16x16x32_bf16 v[12:15], v[140:143], v[204:207], v[12:15]
	v_mfma_f32_16x16x32_bf16 v[52:55], v[160:163], v[176:179], v[52:55]
	v_mfma_f32_16x16x32_bf16 v[40:43], v[168:171], v[176:179], v[40:43]
	v_mfma_f32_16x16x32_bf16 v[36:39], v[160:163], v[184:187], v[36:39]
	v_mfma_f32_16x16x32_bf16 v[24:27], v[168:171], v[184:187], v[24:27]
	v_mfma_f32_16x16x32_bf16 v[20:23], v[160:163], v[192:195], v[20:23]
	v_mfma_f32_16x16x32_bf16 v[8:11], v[168:171], v[192:195], v[8:11]
	v_mfma_f32_16x16x32_bf16 v[4:7], v[160:163], v[200:203], v[4:7]
	v_mfma_f32_16x16x32_bf16 v[0:3], v[168:171], v[200:203], v[0:3]
	v_mfma_f32_16x16x32_bf16 v[52:55], v[164:167], v[180:183], v[52:55]
	v_mfma_f32_16x16x32_bf16 v[40:43], v[172:175], v[180:183], v[40:43]
	v_mfma_f32_16x16x32_bf16 v[36:39], v[164:167], v[188:191], v[36:39]
	v_mfma_f32_16x16x32_bf16 v[24:27], v[172:175], v[188:191], v[24:27]
	v_mfma_f32_16x16x32_bf16 v[20:23], v[164:167], v[196:199], v[20:23]
	v_mfma_f32_16x16x32_bf16 v[8:11], v[172:175], v[196:199], v[8:11]
	v_mfma_f32_16x16x32_bf16 v[4:7], v[164:167], v[204:207], v[4:7]
	v_mfma_f32_16x16x32_bf16 v[0:3], v[172:175], v[204:207], v[0:3]
	s_setprio 0
	s_barrier
	s_add_i32 s74, s74, 2
	s_add_u32 s72, s72, 0x100
	s_addc_u32 s73, s73, 0
	s_cmpk_gt_u32 s74, 0x55
	s_mov_b64 s[36:37], s[38:39]
	s_cbranch_scc0 .LBB0_1249
	s_and_b64 vcc, exec, s[8:9]
	s_cbranch_vccz .LBB0_1252
	s_barrier
